# lever 4: static s_setprio 1 for waves 4-7 at each GEMM unit loop entry, all per-segment setprio flips in the K loops deleted
# speedup vs baseline: 1.0272x; 1.0056x over previous
; template <class Epi, class Sched, bool ALIGN_EPI = false, bool SP2 = false>
; __device__ __forceinline__ void gemm_phase(PG8_LAS unsigned char* lds, const Gemm g, const Sched& S, const Epi& E) {
;     ...
;         PG8_WAIT_V(2); PG8_BAR;
;         PG8_STAGE(PG8_SB(1, 0), cB + kstep, voffB); PG8_STAGE(PG8_SA(1, 0), cA + kstep, voffA); PG8_STAGE(PG8_SB(1, 1), cB + hB + kstep, voffB);
;         PG8_WAIT_V(6); PG8_BAR;
;     __device__ __forceinline__ void operator()(AccRef acc, const pg8::Unit& u, int wr, int wc, int fr, int fq) const {
;         const int pn = u.pn, row0 = u.pm * 256 + wr * 64 + fr, cl = wc * 32 + 8 * fq;
;         if (pn < 16) {
;             const bool isk = pn >= 8; const int h = pn & 7; bf16* dst = isk ? k : q;
;             const float lg2 = head_lg2(h);
; #pragma unroll
;             for (int ai = 0; ai < 2; ++ai) {
;                 f32x4 tcv[4][2], tsv[4][2];
; #pragma unroll
;                 for (int m = 0; m < 4; ++m) { const int pos_ = (row0 + ai * 128 + m * 16) & 4095; const float* tc = tcos + pos_ * 128 + cl; const float* ts = tsin + pos_ * 128 + cl;
;                     tcv[m][0] = *(const f32x4*)tc; tcv[m][1] = *(const f32x4*)(tc + 4); tsv[m][0] = *(const f32x4*)ts; tsv[m][1] = *(const f32x4*)(ts + 4); }
; #pragma unroll
;                 for (int m = 0; m < 4; ++m) {
;                     int r = row0 + ai * 128 + m * 16; asm volatile("" : "+v"(r)); const int pos = r & 4095;
;                     const f32x4 c0 = tcv[m][0], c1 = tcv[m][1], s0 = tsv[m][0], s1 = tsv[m][1];
;                     const f32x4 a0 = acc[ai][0][m][0], a1 = acc[ai][0][m][1], b0 = acc[ai][1][m][0], b1 = acc[ai][1][m][1];
;                     const f32x4 o10 = (a0 * c0 - b0 * s0) * 0.0625f, o11 = (a1 * c1 - b1 * s1) * 0.0625f;
;                     const f32x4 o20 = (a0 * s0 + b0 * c0) * 0.0625f, o21 = (a1 * s1 + b1 * c1) * 0.0625f;
;                     const size_t blk = ((size_t)(((r >> 12) * 8 + h) * 64 + (pos >> 6))) * 16384;
;                     const int nn = r & 63;
;                     bf16* rp = dst + blk + (size_t)(((((cl >> 5) * 2 + (nn >> 5)) * 2 + ((cl >> 4) & 1)) * 64 + ((cl >> 3) & 1) * 32 + (nn & 31)) * 8);
;                     *(u32x4*)rp = pack8(o10, o11); *(u32x4*)(rp + 4 * 2048) = pack8(o20, o21);
;                     if (isk) {
;                         const float kd = exp2f((float)(63 - (r & 63)) * lg2);
.LBB0_184:
	s_add_u32 s14, s0, 0x15800000
	s_waitcnt vmcnt(0)
	v_bfe_u32 v19, v10, 4, 2
	s_addc_u32 s15, s1, 0
	v_and_b32_e32 v18, 15, v10
	v_lshlrev_b32_e32 v20, 3, v19
	v_lshlrev_b32_e32 v19, 4, v19
	s_add_u32 s16, s0, 0x1d800000
	v_lshl_or_b32 v1, s5, 6, v18
	v_lshl_or_b32 v19, v18, 6, v19
	v_lshlrev_b32_e32 v18, 2, v18
	s_mov_b64 s[38:39], 0x80
	s_addc_u32 s17, s1, 0
	s_and_b32 s8, s4, 3
	s_lshl_b32 s4, s5, 13
	v_and_b32_e32 v21, 32, v18
	s_add_i32 m0, s74, 0x18000
	v_lshl_add_u64 v[8:9], v[8:9], 0, s[38:39]
	v_bitop3_b32 v22, v19, s4, v21 bitop3:0xde
	s_lshl_b32 s4, s8, 12
	s_waitcnt vmcnt(2)
	s_barrier
	global_load_lds_dwordx4 v[8:9], off
	v_lshl_add_u64 v[6:7], v[6:7], 0, s[38:39]
	s_add_i32 m0, s74, 0x1a000
	s_add_i32 s81, s74, 0x8000
	s_add_i32 s82, s74, 0xa000
	v_bitop3_b32 v223, v19, s4, v21 bitop3:0xde
	global_load_lds_dwordx4 v[6:7], off
	v_lshl_add_u64 v[4:5], v[4:5], 0, s[38:39]
	s_mov_b32 m0, s81
	s_add_u32 s4, s64, 0x80080
	global_load_lds_dwordx4 v[4:5], off
	v_lshl_add_u64 v[2:3], v[2:3], 0, s[38:39]
	s_mov_b32 m0, s82
	s_addc_u32 s5, s65, 0
	global_load_lds_dwordx4 v[2:3], off
	s_add_i32 m0, s74, 0x1c000
	v_lshl_add_u64 v[2:3], s[4:5], 0, v[196:197]
	global_load_lds_dwordx4 v[2:3], off
	v_lshl_add_u64 v[2:3], s[4:5], 0, v[200:201]
	s_add_i32 m0, s74, 0x1e000
	v_lshrrev_b32_e32 v17, 4, v10
	global_load_lds_dwordx4 v[2:3], off
	v_and_b32_e32 v2, 3, v10
	s_cmpk_lt_u32 s6, 0x100
	v_lshlrev_b32_e32 v3, 1, v2
	v_cmp_gt_u32_e64 s[6:7], 2, v2
	v_bfe_u32 v2, v17, 1, 1
	v_lshl_or_b32 v227, s8, 2, v2
	v_lshlrev_b32_e32 v2, 1, v10
	v_or_b32_e32 v5, v20, v3
	v_and_b32_e32 v228, 32, v2
	v_bitop3_b32 v2, v20, 18, v3 bitop3:0xc8
	v_lshrrev_b32_e32 v3, 2, v10
	s_cselect_b64 s[40:41], -1, 0
	s_lshl_b32 s9, s8, 8
	v_and_b32_e32 v6, 4, v10
	v_and_b32_e32 v3, 4, v3
	v_or3_b32 v5, v21, s9, v5
	v_and_b32_e32 v7, 1, v10
	v_and_or_b32 v3, v18, 40, v3
	v_lshlrev_b32_e32 v6, 1, v6
	v_cmp_eq_u32_e64 s[4:5], 0, v7
	v_or3_b32 v7, v3, v2, s9
	v_lshl_or_b32 v202, v5, 4, v6
	v_lshl_or_b32 v4, s8, 5, v20
	v_lshl_add_u64 v[2:3], s[0:1], 0, v[202:203]
	s_mov_b64 s[8:9], 0xd800000
	v_lshl_or_b32 v202, v7, 4, v6
	v_lshl_add_u64 v[204:205], v[2:3], 0, s[8:9]
	v_lshl_add_u64 v[2:3], s[0:1], 0, v[202:203]
	s_mov_b64 s[8:9], 0x11800000
	v_lshlrev_b32_e32 v202, 2, v4
	v_lshl_add_u64 v[206:207], v[2:3], 0, s[8:9]
	v_lshl_add_u64 v[2:3], s[0:1], 0, v[202:203]
	s_mov_b64 s[42:43], 0x100000
	s_mov_b64 s[8:9], 0x300000
	v_lshl_add_u64 v[208:209], v[2:3], 0, s[42:43]
	v_lshl_add_u64 v[210:211], v[2:3], 0, s[8:9]
	v_lshlrev_b32_e32 v2, 15, v11
	v_and_b32_e32 v2, 0xffff0000, v2
	v_lshl_add_u32 v2, v12, 12, v2
	v_and_b32_e32 v3, 1, v11
	v_lshl_or_b32 v2, v3, 6, v2
	v_lshl_add_u32 v212, v13, 1, v2
	v_lshlrev_b32_e32 v2, 15, v14
	v_and_b32_e32 v2, 0xffff0000, v2
	s_waitcnt vmcnt(6)
	v_lshl_add_u32 v2, v15, 12, v2
	v_and_b32_e32 v3, 1, v14
	v_lshl_or_b32 v2, v3, 6, v2
	s_add_i32 s84, 0, 0x10000
	s_add_i32 s85, 0, 0x14000
	v_or_b32_e32 v224, 0xffffdc00, v4
	v_or_b32_e32 v225, 0xffffe000, v4
	v_or_b32_e32 v226, 0xffffe800, v4
	s_waitcnt lgkmcnt(0)
	s_ashr_i32 s83, s78, 31
	v_mov_b32_e32 v213, v203
	v_lshl_add_u32 v214, v16, 1, v2
	v_mov_b32_e32 v215, v203
	v_mov_b64_e32 v[216:217], 0xd00
	v_mov_b64_e32 v[218:219], 0xcff
	v_add_u32_e32 v229, s84, v223
	v_add_u32_e32 v230, s85, v223
	v_add_u32_e32 v231, 0, v22
	s_mov_b32 s18, 0x58000
	s_mov_b32 s87, 0x80000
	s_mov_b64 s[44:45], 0x90000
	s_mov_b32 s88, 0x90000
	s_mov_b64 s[46:47], 0xa0000
	s_mov_b32 s89, 0xa0000
	s_mov_b64 s[48:49], 0xb0000
	s_mov_b32 s90, 0xb0000
	s_mov_b32 s91, 0x5040100
	s_mov_b32 s92, 0x7060302
	s_mov_b32 s93, 0x9800000
	s_mov_b32 s94, 0xc2fc0000
	s_mov_b32 s95, 0x800000
	s_mov_b32 s50, 0x3d800000
	v_mov_b32_e32 v232, 0x42800000
	v_mov_b32_e32 v233, 0x42000000
	v_not_b32_e32 v234, 63
	s_barrier
	v_readfirstlane_b32 s99, v0
	s_nop 3
	s_lshr_b32 s99, s99, 8
	s_cmp_eq_u32 s99, 0
	s_cbranch_scc1 .Lprio_skip_1
	s_setprio 1
.Lprio_skip_1:
	s_branch .LBB0_187

; #define PG8_STAGE(bufoff, gbase, voff) do { _Pragma("unroll") for (int _i = 0; _i < 2; ++_i) \
;         __builtin_amdgcn_global_load_lds((const unsigned*)((const char*)(gbase) + (voff)[_i]), (PG8_LAS unsigned*)(lds + (bufoff) + ldsw + _i * 8192), 16, 0, 0); } while (0)
; #define PG8_LDA(dst, b, h) do { _Pragma("unroll") for (int m = 0; m < 4; ++m) _Pragma("unroll") for (int k = 0; k < 2; ++k) dst[m][k] = *(const PG8_LAS bf16x8*)(lds + PG8_SA(b, h) + aoff + m * 2048 + k * 1024); } while (0)
; #define PG8_LDB(dst, b, h) do { _Pragma("unroll") for (int n = 0; n < 2; ++n) _Pragma("unroll") for (int k = 0; k < 2; ++k) dst[n][k] = *(const PG8_LAS bf16x8*)(lds + PG8_SB(b, h) + boff + n * 2048 + k * 1024); } while (0)
; #define PG8_MMA(ai, bj, At, Bt) do { __builtin_amdgcn_s_setprio(1); _Pragma("unroll") for (int m = 0; m < 4; ++m) _Pragma("unroll") for (int n = 0; n < 2; ++n) _Pragma("unroll") for (int k = 0; k < 2; ++k) \
;         acc[ai][bj][m][n] = __builtin_amdgcn_mfma_f32_16x16x32_bf16(Bt[n][k], At[m][k], acc[ai][bj][m][n], 0, 0, 0); __builtin_amdgcn_s_setprio(0); } while (0)
; #define PG8_WAIT_V(n) asm volatile("s_waitcnt vmcnt(" #n ")" ::: "memory")
; #define PG8_WAIT_L(n) asm volatile("s_waitcnt lgkmcnt(" #n ")" ::: "memory")
; #define PG8_BAR __builtin_amdgcn_s_barrier()
; #define PG8_SCHED __builtin_amdgcn_sched_barrier(0)
; template <class Epi, class Sched, bool ALIGN_EPI = false, bool SP2 = false>
; __device__ __forceinline__ void gemm_phase(PG8_LAS unsigned char* lds, const Gemm g, const Sched& S, const Epi& E) {
;     ...
;             PG8_LDB(B0, 0, 0); PG8_LDB(B1, 0, 1); PG8_SCHED; PG8_LDA(At, 0, 0); PG8_STAGE(PG8_SA(1, 1), a1 + hA, voffA);
;             PG8_WAIT_V(8); PG8_WAIT_L(0); PG8_BAR; PG8_MMA(0, 0, At, B0); PG8_MMA(0, 1, At, B1); PG8_BAR; PG8_SCHED;
;             PG8_LDA(At, 0, 1); PG8_STAGE(PG8_SB(0, 0), b2, voffB); PG8_STAGE(PG8_SB(0, 1), b2 + hB, voffB); PG8_STAGE(PG8_SA(0, 0), a2, voffA);
;             PG8_WAIT_V(8); PG8_WAIT_L(0); PG8_BAR; PG8_MMA(1, 0, At, B0); PG8_MMA(1, 1, At, B1); PG8_BAR; PG8_SCHED;
.LBB0_190:
	ds_read_b128 v[130:133], v229
	ds_read_b128 v[134:137], v229 offset:1024
	ds_read_b128 v[138:141], v229 offset:2048
	ds_read_b128 v[142:145], v229 offset:3072
	ds_read_b128 v[146:149], v230
	ds_read_b128 v[150:153], v230 offset:1024
	ds_read_b128 v[154:157], v230 offset:2048
	ds_read_b128 v[158:161], v230 offset:3072
	s_add_u32 s64, s62, 0xfff80080
	s_addc_u32 s65, s63, -1
	s_cmp_eq_u32 s97, 28
	s_cselect_b32 s67, s11, s65
	s_cselect_b32 s66, s33, s64
	s_cselect_b32 s65, s53, s96
	s_cselect_b32 s64, s55, s61
	v_lshl_add_u64 v[220:221], s[62:63], 0, v[212:213]
	s_add_i32 m0, s74, 0xc000
	ds_read_b128 v[162:165], v231
	ds_read_b128 v[166:169], v231 offset:1024
	ds_read_b128 v[170:173], v231 offset:2048
	ds_read_b128 v[174:177], v231 offset:3072
	ds_read_b128 v[178:181], v231 offset:4096
	ds_read_b128 v[182:185], v231 offset:5120
	ds_read_b128 v[186:189], v231 offset:6144
	ds_read_b128 v[190:193], v231 offset:7168
	global_load_lds_dwordx4 v[220:221], off
	v_lshl_add_u64 v[220:221], s[62:63], 0, v[214:215]
	s_add_i32 m0, s74, 0xe000
	s_nop 0
	global_load_lds_dwordx4 v[220:221], off
	s_waitcnt vmcnt(8)
	s_waitcnt lgkmcnt(0)
	s_barrier
	s_waitcnt lgkmcnt(0)
	v_mfma_f32_16x16x32_bf16 v[126:129], v[130:133], v[162:165], v[126:129]
	v_mfma_f32_16x16x32_bf16 v[122:125], v[138:141], v[162:165], v[122:125]
	v_mfma_f32_16x16x32_bf16 v[110:113], v[130:133], v[170:173], v[110:113]
	v_mfma_f32_16x16x32_bf16 v[106:109], v[138:141], v[170:173], v[106:109]
	v_mfma_f32_16x16x32_bf16 v[94:97], v[130:133], v[178:181], v[94:97]
	v_mfma_f32_16x16x32_bf16 v[90:93], v[138:141], v[178:181], v[90:93]
	v_mfma_f32_16x16x32_bf16 v[78:81], v[130:133], v[186:189], v[78:81]
	v_mfma_f32_16x16x32_bf16 v[74:77], v[138:141], v[186:189], v[74:77]
	v_mfma_f32_16x16x32_bf16 v[126:129], v[134:137], v[166:169], v[126:129]
	v_mfma_f32_16x16x32_bf16 v[122:125], v[142:145], v[166:169], v[122:125]
	v_mfma_f32_16x16x32_bf16 v[110:113], v[134:137], v[174:177], v[110:113]
	v_mfma_f32_16x16x32_bf16 v[106:109], v[142:145], v[174:177], v[106:109]
	v_mfma_f32_16x16x32_bf16 v[94:97], v[134:137], v[182:185], v[94:97]
	v_mfma_f32_16x16x32_bf16 v[90:93], v[142:145], v[182:185], v[90:93]
	v_mfma_f32_16x16x32_bf16 v[78:81], v[134:137], v[190:193], v[78:81]
	v_mfma_f32_16x16x32_bf16 v[74:77], v[142:145], v[190:193], v[74:77]
	v_mfma_f32_16x16x32_bf16 v[118:121], v[146:149], v[162:165], v[118:121]
	v_mfma_f32_16x16x32_bf16 v[114:117], v[154:157], v[162:165], v[114:117]
	v_mfma_f32_16x16x32_bf16 v[102:105], v[146:149], v[170:173], v[102:105]
	v_mfma_f32_16x16x32_bf16 v[98:101], v[154:157], v[170:173], v[98:101]
	v_mfma_f32_16x16x32_bf16 v[86:89], v[146:149], v[178:181], v[86:89]
	v_mfma_f32_16x16x32_bf16 v[82:85], v[154:157], v[178:181], v[82:85]
	v_mfma_f32_16x16x32_bf16 v[70:73], v[146:149], v[186:189], v[70:73]
	v_mfma_f32_16x16x32_bf16 v[66:69], v[154:157], v[186:189], v[66:69]
	v_mfma_f32_16x16x32_bf16 v[118:121], v[150:153], v[166:169], v[118:121]
	v_mfma_f32_16x16x32_bf16 v[114:117], v[158:161], v[166:169], v[114:117]
	v_mfma_f32_16x16x32_bf16 v[102:105], v[150:153], v[174:177], v[102:105]
	v_mfma_f32_16x16x32_bf16 v[98:101], v[158:161], v[174:177], v[98:101]
	v_mfma_f32_16x16x32_bf16 v[86:89], v[150:153], v[182:185], v[86:89]
	v_mfma_f32_16x16x32_bf16 v[82:85], v[158:161], v[182:185], v[82:85]
	v_mfma_f32_16x16x32_bf16 v[70:73], v[150:153], v[190:193], v[70:73]
	v_mfma_f32_16x16x32_bf16 v[66:69], v[158:161], v[190:193], v[66:69]
	s_barrier
	s_add_i32 vcc_lo, s84, s73
	v_lshl_add_u64 v[220:221], s[64:65], 0, v[196:197]
	s_mov_b32 m0, vcc_lo
	ds_read_b128 v[162:165], v231 offset:16384
	ds_read_b128 v[166:169], v231 offset:17408
	ds_read_b128 v[170:173], v231 offset:18432
	ds_read_b128 v[174:177], v231 offset:19456
	ds_read_b128 v[178:181], v231 offset:20480
	ds_read_b128 v[182:185], v231 offset:21504
	ds_read_b128 v[186:189], v231 offset:22528
	ds_read_b128 v[190:193], v231 offset:23552
	global_load_lds_dwordx4 v[220:221], off
	s_add_i32 m0, vcc_lo, 0x2000
	s_add_u32 vcc_lo, s64, 0x80000
	v_lshl_add_u64 v[236:237], s[64:65], 0, v[200:201]
	s_addc_u32 vcc_hi, s65, 0
	s_add_i32 s86, s85, s73
	global_load_lds_dwordx4 v[236:237], off
	v_lshl_add_u64 v[238:239], vcc, 0, v[196:197]
	s_mov_b32 m0, s86
	v_lshl_add_u64 v[240:241], s[66:67], 0, v[198:199]
	global_load_lds_dwordx4 v[238:239], off
	v_lshl_add_u64 v[238:239], vcc, 0, v[200:201]
	s_add_i32 m0, s86, 0x2000
	s_nop 0
	global_load_lds_dwordx4 v[238:239], off
	v_lshl_add_u64 v[238:239], s[66:67], 0, v[194:195]
	s_mov_b32 m0, s74
	s_nop 0
	global_load_lds_dwordx4 v[238:239], off
	s_mov_b32 m0, s75
	s_nop 0
	global_load_lds_dwordx4 v[240:241], off
	s_waitcnt vmcnt(8)
	s_waitcnt lgkmcnt(0)
	s_barrier
; #define PG8_STAGE(bufoff, gbase, voff) do { _Pragma("unroll") for (int _i = 0; _i < 2; ++_i) \
;         __builtin_amdgcn_global_load_lds((const unsigned*)((const char*)(gbase) + (voff)[_i]), (PG8_LAS unsigned*)(lds + (bufoff) + ldsw + _i * 8192), 16, 0, 0); } while (0)
; #define PG8_LDA(dst, b, h) do { _Pragma("unroll") for (int m = 0; m < 4; ++m) _Pragma("unroll") for (int k = 0; k < 2; ++k) dst[m][k] = *(const PG8_LAS bf16x8*)(lds + PG8_SA(b, h) + aoff + m * 2048 + k * 1024); } while (0)
; #define PG8_LDB(dst, b, h) do { _Pragma("unroll") for (int n = 0; n < 2; ++n) _Pragma("unroll") for (int k = 0; k < 2; ++k) dst[n][k] = *(const PG8_LAS bf16x8*)(lds + PG8_SB(b, h) + boff + n * 2048 + k * 1024); } while (0)
; #define PG8_MMA(ai, bj, At, Bt) do { __builtin_amdgcn_s_setprio(1); _Pragma("unroll") for (int m = 0; m < 4; ++m) _Pragma("unroll") for (int n = 0; n < 2; ++n) _Pragma("unroll") for (int k = 0; k < 2; ++k) \
;         acc[ai][bj][m][n] = __builtin_amdgcn_mfma_f32_16x16x32_bf16(Bt[n][k], At[m][k], acc[ai][bj][m][n], 0, 0, 0); __builtin_amdgcn_s_setprio(0); } while (0)
; #define PG8_WAIT_V(n) asm volatile("s_waitcnt vmcnt(" #n ")" ::: "memory")
; #define PG8_WAIT_L(n) asm volatile("s_waitcnt lgkmcnt(" #n ")" ::: "memory")
; #define PG8_BAR __builtin_amdgcn_s_barrier()
; #define PG8_SCHED __builtin_amdgcn_sched_barrier(0)
; template <class Epi, class Sched, bool ALIGN_EPI = false, bool SP2 = false>
; __device__ __forceinline__ void gemm_phase(PG8_LAS unsigned char* lds, const Gemm g, const Sched& S, const Epi& E) {
;     ...
;             PG8_WAIT_V(8); PG8_WAIT_L(0); PG8_BAR; PG8_MMA(1, 0, At, B0); PG8_MMA(1, 1, At, B1); PG8_BAR; PG8_SCHED;
;             PG8_LDB(B0, 1, 0); PG8_LDB(B1, 1, 1); PG8_SCHED; PG8_LDA(At, 1, 0); PG8_STAGE(PG8_SA(0, 1), a2 + hA, voffA);
;             PG8_WAIT_V(8); PG8_WAIT_L(0); PG8_BAR; PG8_MMA(0, 0, At, B0); PG8_MMA(0, 1, At, B1); PG8_BAR; PG8_SCHED;
	s_waitcnt lgkmcnt(0)
	v_mfma_f32_16x16x32_bf16 v[62:65], v[130:133], v[162:165], v[62:65]
	v_mfma_f32_16x16x32_bf16 v[58:61], v[138:141], v[162:165], v[58:61]
	v_mfma_f32_16x16x32_bf16 v[46:49], v[130:133], v[170:173], v[46:49]
	v_mfma_f32_16x16x32_bf16 v[42:45], v[138:141], v[170:173], v[42:45]
	v_mfma_f32_16x16x32_bf16 v[30:33], v[130:133], v[178:181], v[30:33]
	v_mfma_f32_16x16x32_bf16 v[26:29], v[138:141], v[178:181], v[26:29]
	v_mfma_f32_16x16x32_bf16 v[14:17], v[130:133], v[186:189], v[14:17]
	v_mfma_f32_16x16x32_bf16 v[10:13], v[138:141], v[186:189], v[10:13]
	v_mfma_f32_16x16x32_bf16 v[62:65], v[134:137], v[166:169], v[62:65]
	v_mfma_f32_16x16x32_bf16 v[58:61], v[142:145], v[166:169], v[58:61]
	v_mfma_f32_16x16x32_bf16 v[46:49], v[134:137], v[174:177], v[46:49]
	v_mfma_f32_16x16x32_bf16 v[42:45], v[142:145], v[174:177], v[42:45]
	v_mfma_f32_16x16x32_bf16 v[30:33], v[134:137], v[182:185], v[30:33]
	v_mfma_f32_16x16x32_bf16 v[26:29], v[142:145], v[182:185], v[26:29]
	v_mfma_f32_16x16x32_bf16 v[14:17], v[134:137], v[190:193], v[14:17]
	v_mfma_f32_16x16x32_bf16 v[10:13], v[142:145], v[190:193], v[10:13]
	v_mfma_f32_16x16x32_bf16 v[54:57], v[146:149], v[162:165], v[54:57]
	v_mfma_f32_16x16x32_bf16 v[50:53], v[154:157], v[162:165], v[50:53]
	v_mfma_f32_16x16x32_bf16 v[38:41], v[146:149], v[170:173], v[38:41]
	v_mfma_f32_16x16x32_bf16 v[34:37], v[154:157], v[170:173], v[34:37]
	v_mfma_f32_16x16x32_bf16 v[22:25], v[146:149], v[178:181], v[22:25]
	v_mfma_f32_16x16x32_bf16 v[18:21], v[154:157], v[178:181], v[18:21]
	v_mfma_f32_16x16x32_bf16 v[6:9], v[146:149], v[186:189], v[6:9]
	v_mfma_f32_16x16x32_bf16 v[2:5], v[154:157], v[186:189], v[2:5]
	v_mfma_f32_16x16x32_bf16 v[54:57], v[150:153], v[166:169], v[54:57]
	v_mfma_f32_16x16x32_bf16 v[50:53], v[158:161], v[166:169], v[50:53]
	v_mfma_f32_16x16x32_bf16 v[38:41], v[150:153], v[174:177], v[38:41]
	v_mfma_f32_16x16x32_bf16 v[34:37], v[158:161], v[174:177], v[34:37]
	v_mfma_f32_16x16x32_bf16 v[22:25], v[150:153], v[182:185], v[22:25]
	v_mfma_f32_16x16x32_bf16 v[18:21], v[158:161], v[182:185], v[18:21]
	v_mfma_f32_16x16x32_bf16 v[6:9], v[150:153], v[190:193], v[6:9]
	v_mfma_f32_16x16x32_bf16 v[2:5], v[158:161], v[190:193], v[2:5]
	s_barrier
	s_add_i32 s86, 0, 0x18000
	s_add_i32 vcc_lo, 0, 0x1c000
	v_add_u32_e32 v142, s86, v223
	v_add_u32_e32 v158, vcc_lo, v223
	ds_read_b128 v[130:133], v142
	ds_read_b128 v[134:137], v142 offset:1024
	ds_read_b128 v[138:141], v142 offset:2048
	ds_read_b128 v[142:145], v142 offset:3072
	ds_read_b128 v[146:149], v158
	ds_read_b128 v[150:153], v158 offset:1024
	ds_read_b128 v[154:157], v158 offset:2048
	ds_read_b128 v[158:161], v158 offset:3072
	s_add_u32 s66, s66, 0x80000
	s_addc_u32 s67, s67, 0
	s_mov_b32 m0, s76
	v_lshl_add_u64 v[242:243], s[66:67], 0, v[194:195]
	ds_read_b128 v[162:165], v231 offset:32768
	ds_read_b128 v[166:169], v231 offset:33792
	ds_read_b128 v[170:173], v231 offset:34816
	ds_read_b128 v[174:177], v231 offset:35840
	ds_read_b128 v[178:181], v231 offset:36864
	ds_read_b128 v[182:185], v231 offset:37888
	ds_read_b128 v[186:189], v231 offset:38912
	ds_read_b128 v[190:193], v231 offset:39936
	global_load_lds_dwordx4 v[242:243], off
	v_lshl_add_u64 v[242:243], s[66:67], 0, v[198:199]
	s_mov_b32 m0, s77
	s_nop 0
	global_load_lds_dwordx4 v[242:243], off
	s_waitcnt vmcnt(8)
	s_waitcnt lgkmcnt(0)
	s_barrier
	s_waitcnt lgkmcnt(0)
	v_mfma_f32_16x16x32_bf16 v[126:129], v[130:133], v[162:165], v[126:129]
	v_mfma_f32_16x16x32_bf16 v[122:125], v[138:141], v[162:165], v[122:125]
	v_mfma_f32_16x16x32_bf16 v[110:113], v[130:133], v[170:173], v[110:113]
	v_mfma_f32_16x16x32_bf16 v[106:109], v[138:141], v[170:173], v[106:109]
	v_mfma_f32_16x16x32_bf16 v[94:97], v[130:133], v[178:181], v[94:97]
	v_mfma_f32_16x16x32_bf16 v[90:93], v[138:141], v[178:181], v[90:93]
	v_mfma_f32_16x16x32_bf16 v[78:81], v[130:133], v[186:189], v[78:81]
	v_mfma_f32_16x16x32_bf16 v[74:77], v[138:141], v[186:189], v[74:77]
	v_mfma_f32_16x16x32_bf16 v[126:129], v[134:137], v[166:169], v[126:129]
	v_mfma_f32_16x16x32_bf16 v[122:125], v[142:145], v[166:169], v[122:125]
	v_mfma_f32_16x16x32_bf16 v[110:113], v[134:137], v[174:177], v[110:113]
	v_mfma_f32_16x16x32_bf16 v[106:109], v[142:145], v[174:177], v[106:109]
	v_mfma_f32_16x16x32_bf16 v[94:97], v[134:137], v[182:185], v[94:97]
	v_mfma_f32_16x16x32_bf16 v[90:93], v[142:145], v[182:185], v[90:93]
	v_mfma_f32_16x16x32_bf16 v[78:81], v[134:137], v[190:193], v[78:81]
	v_mfma_f32_16x16x32_bf16 v[74:77], v[142:145], v[190:193], v[74:77]
	v_mfma_f32_16x16x32_bf16 v[118:121], v[146:149], v[162:165], v[118:121]
	v_mfma_f32_16x16x32_bf16 v[114:117], v[154:157], v[162:165], v[114:117]
	v_mfma_f32_16x16x32_bf16 v[102:105], v[146:149], v[170:173], v[102:105]
	v_mfma_f32_16x16x32_bf16 v[98:101], v[154:157], v[170:173], v[98:101]
	v_mfma_f32_16x16x32_bf16 v[86:89], v[146:149], v[178:181], v[86:89]
	v_mfma_f32_16x16x32_bf16 v[82:85], v[154:157], v[178:181], v[82:85]
	v_mfma_f32_16x16x32_bf16 v[70:73], v[146:149], v[186:189], v[70:73]
	v_mfma_f32_16x16x32_bf16 v[66:69], v[154:157], v[186:189], v[66:69]
	v_mfma_f32_16x16x32_bf16 v[118:121], v[150:153], v[166:169], v[118:121]
	v_mfma_f32_16x16x32_bf16 v[114:117], v[158:161], v[166:169], v[114:117]
	v_mfma_f32_16x16x32_bf16 v[102:105], v[150:153], v[174:177], v[102:105]
	v_mfma_f32_16x16x32_bf16 v[98:101], v[158:161], v[174:177], v[98:101]
	v_mfma_f32_16x16x32_bf16 v[86:89], v[150:153], v[182:185], v[86:89]
	v_mfma_f32_16x16x32_bf16 v[82:85], v[158:161], v[182:185], v[82:85]
	v_mfma_f32_16x16x32_bf16 v[70:73], v[150:153], v[190:193], v[70:73]
	v_mfma_f32_16x16x32_bf16 v[66:69], v[158:161], v[190:193], v[66:69]
	s_barrier
; #define PG8_STAGE(bufoff, gbase, voff) do { _Pragma("unroll") for (int _i = 0; _i < 2; ++_i) \
;         __builtin_amdgcn_global_load_lds((const unsigned*)((const char*)(gbase) + (voff)[_i]), (PG8_LAS unsigned*)(lds + (bufoff) + ldsw + _i * 8192), 16, 0, 0); } while (0)
; #define PG8_LDA(dst, b, h) do { _Pragma("unroll") for (int m = 0; m < 4; ++m) _Pragma("unroll") for (int k = 0; k < 2; ++k) dst[m][k] = *(const PG8_LAS bf16x8*)(lds + PG8_SA(b, h) + aoff + m * 2048 + k * 1024); } while (0)
; #define PG8_MMA(ai, bj, At, Bt) do { __builtin_amdgcn_s_setprio(1); _Pragma("unroll") for (int m = 0; m < 4; ++m) _Pragma("unroll") for (int n = 0; n < 2; ++n) _Pragma("unroll") for (int k = 0; k < 2; ++k) \
;         acc[ai][bj][m][n] = __builtin_amdgcn_mfma_f32_16x16x32_bf16(Bt[n][k], At[m][k], acc[ai][bj][m][n], 0, 0, 0); __builtin_amdgcn_s_setprio(0); } while (0)
; #define PG8_WAIT_V(n) asm volatile("s_waitcnt vmcnt(" #n ")" ::: "memory")
; #define PG8_WAIT_L(n) asm volatile("s_waitcnt lgkmcnt(" #n ")" ::: "memory")
; #define PG8_BAR __builtin_amdgcn_s_barrier()
; #define PG8_SCHED __builtin_amdgcn_sched_barrier(0)
; template <class Epi, class Sched, bool ALIGN_EPI = false, bool SP2 = false>
; __device__ __forceinline__ void gemm_phase(PG8_LAS unsigned char* lds, const Gemm g, const Sched& S, const Epi& E) {
;     ...
;             PG8_WAIT_V(8); PG8_WAIT_L(0); PG8_BAR; PG8_MMA(0, 0, At, B0); PG8_MMA(0, 1, At, B1); PG8_BAR; PG8_SCHED;
;             PG8_LDA(At, 1, 1); PG8_STAGE(PG8_SB(1, 0), b3, voffB); PG8_STAGE(PG8_SB(1, 1), b3 + hB, voffB); PG8_STAGE(PG8_SA(1, 0), a3, voffA);
;             PG8_WAIT_V(8); PG8_WAIT_L(0); PG8_BAR; PG8_MMA(1, 0, At, B0); PG8_MMA(1, 1, At, B1); PG8_BAR; PG8_SCHED;
;     ...
;         if constexpr (ALIGN_EPI) { if (wr == 0) PG8_BAR; }
	s_add_i32 s66, s86, s73
	v_lshl_add_u64 v[220:221], v[220:221], 0, s[38:39]
	s_mov_b32 m0, s66
	ds_read_b128 v[162:165], v231 offset:49152
	ds_read_b128 v[166:169], v231 offset:50176
	ds_read_b128 v[170:173], v231 offset:51200
	ds_read_b128 v[174:177], v231 offset:52224
	ds_read_b128 v[178:181], v231 offset:53248
	ds_read_b128 v[182:185], v231 offset:54272
	ds_read_b128 v[186:189], v231 offset:55296
	ds_read_b128 v[190:193], v231 offset:56320
	global_load_lds_dwordx4 v[220:221], off
	s_add_i32 m0, s66, 0x2000
	s_add_u32 s64, s64, 0x80080
	v_lshl_add_u64 v[220:221], v[236:237], 0, s[38:39]
	s_addc_u32 s65, s65, 0
	s_add_i32 s66, vcc_lo, s73
	global_load_lds_dwordx4 v[220:221], off
	v_lshl_add_u64 v[220:221], s[64:65], 0, v[196:197]
	s_mov_b32 m0, s66
	s_nop 0
	global_load_lds_dwordx4 v[220:221], off
	v_lshl_add_u64 v[220:221], s[64:65], 0, v[200:201]
	s_add_i32 m0, s66, 0x2000
	s_nop 0
	global_load_lds_dwordx4 v[220:221], off
	v_lshl_add_u64 v[220:221], v[238:239], 0, s[38:39]
	s_mov_b32 m0, s81
	s_nop 0
	global_load_lds_dwordx4 v[220:221], off
	v_lshl_add_u64 v[220:221], v[240:241], 0, s[38:39]
	s_mov_b32 m0, s82
	s_nop 0
	global_load_lds_dwordx4 v[220:221], off
	s_waitcnt vmcnt(8)
	s_waitcnt lgkmcnt(0)
	s_barrier
	s_waitcnt lgkmcnt(0)
	v_mfma_f32_16x16x32_bf16 v[62:65], v[130:133], v[162:165], v[62:65]
	v_mfma_f32_16x16x32_bf16 v[58:61], v[138:141], v[162:165], v[58:61]
	v_mfma_f32_16x16x32_bf16 v[46:49], v[130:133], v[170:173], v[46:49]
	v_mfma_f32_16x16x32_bf16 v[42:45], v[138:141], v[170:173], v[42:45]
	v_mfma_f32_16x16x32_bf16 v[30:33], v[130:133], v[178:181], v[30:33]
	v_mfma_f32_16x16x32_bf16 v[26:29], v[138:141], v[178:181], v[26:29]
	v_mfma_f32_16x16x32_bf16 v[14:17], v[130:133], v[186:189], v[14:17]
	v_mfma_f32_16x16x32_bf16 v[10:13], v[138:141], v[186:189], v[10:13]
	v_mfma_f32_16x16x32_bf16 v[62:65], v[134:137], v[166:169], v[62:65]
	v_mfma_f32_16x16x32_bf16 v[58:61], v[142:145], v[166:169], v[58:61]
	v_mfma_f32_16x16x32_bf16 v[46:49], v[134:137], v[174:177], v[46:49]
	v_mfma_f32_16x16x32_bf16 v[42:45], v[142:145], v[174:177], v[42:45]
	v_mfma_f32_16x16x32_bf16 v[30:33], v[134:137], v[182:185], v[30:33]
	v_mfma_f32_16x16x32_bf16 v[26:29], v[142:145], v[182:185], v[26:29]
	v_mfma_f32_16x16x32_bf16 v[14:17], v[134:137], v[190:193], v[14:17]
	v_mfma_f32_16x16x32_bf16 v[10:13], v[142:145], v[190:193], v[10:13]
	v_mfma_f32_16x16x32_bf16 v[54:57], v[146:149], v[162:165], v[54:57]
	v_mfma_f32_16x16x32_bf16 v[50:53], v[154:157], v[162:165], v[50:53]
	v_mfma_f32_16x16x32_bf16 v[38:41], v[146:149], v[170:173], v[38:41]
	v_mfma_f32_16x16x32_bf16 v[34:37], v[154:157], v[170:173], v[34:37]
	v_mfma_f32_16x16x32_bf16 v[22:25], v[146:149], v[178:181], v[22:25]
	v_mfma_f32_16x16x32_bf16 v[18:21], v[154:157], v[178:181], v[18:21]
	v_mfma_f32_16x16x32_bf16 v[6:9], v[146:149], v[186:189], v[6:9]
	v_mfma_f32_16x16x32_bf16 v[2:5], v[154:157], v[186:189], v[2:5]
	v_mfma_f32_16x16x32_bf16 v[54:57], v[150:153], v[166:169], v[54:57]
	v_mfma_f32_16x16x32_bf16 v[50:53], v[158:161], v[166:169], v[50:53]
	v_mfma_f32_16x16x32_bf16 v[38:41], v[150:153], v[174:177], v[38:41]
	v_mfma_f32_16x16x32_bf16 v[34:37], v[158:161], v[174:177], v[34:37]
	v_mfma_f32_16x16x32_bf16 v[22:25], v[150:153], v[182:185], v[22:25]
	v_mfma_f32_16x16x32_bf16 v[18:21], v[158:161], v[182:185], v[18:21]
	v_mfma_f32_16x16x32_bf16 v[6:9], v[150:153], v[190:193], v[6:9]
	v_mfma_f32_16x16x32_bf16 v[2:5], v[158:161], v[190:193], v[2:5]
	s_barrier
	s_add_i32 s97, s97, 2
	s_add_u32 s62, s62, 0x100
	s_addc_u32 s63, s63, 0
	s_add_u32 s61, s61, 0x100
	s_addc_u32 s96, s96, 0
	s_cmp_gt_u32 s97, 29
	s_cbranch_scc0 .LBB0_190
	s_and_b64 vcc, exec, s[40:41]
	s_cbranch_vccz .LBB0_211
	s_barrier
	v_lshl_add_u32 v220, s60, 8, v1
	s_cmp_gt_i32 s10, 15
	s_mov_b64 s[60:61], -1
	s_cbranch_scc1 .LBB0_212

; #define PG8_WAIT_V(n) asm volatile("s_waitcnt vmcnt(" #n ")" ::: "memory")
; #define PG8_BAR __builtin_amdgcn_s_barrier()
; template <class Epi, class Sched, bool ALIGN_EPI = false, bool SP2 = false>
; __device__ __forceinline__ void gemm_phase(PG8_LAS unsigned char* lds, const Gemm g, const Sched& S, const Epi& E) {
;     ...
;     PG8_WAIT_V(0);
;     if constexpr (!ALIGN_EPI) { if (wr == 0) PG8_BAR; }
;     PG8_BAR;
; __device__ __forceinline__ void xcd_barrier(const XcdBarrier& b) {
;     asm volatile("s_waitcnt vmcnt(0)" ::: "memory");
;     __syncthreads();
;     if (threadIdx.x == 0) {
;         unsigned* bar = b.bar;
;         __builtin_amdgcn_s_waitcnt(0);
;         unsigned nloc = b.st[0], nx = b.st[1];
;         if (nloc == 0u) { xcd_barrier_complete(bar, b.x, nloc, nx); b.st[0] = nloc; b.st[1] = nx; }
.LBB0_229:
	s_setprio 0
	s_waitcnt vmcnt(0)
	s_waitcnt vmcnt(0)
	s_barrier
	s_and_saveexec_b64 s[0:1], s[86:87]
	s_xor_b64 s[0:1], exec, s[0:1]
	s_cbranch_execz .LBB0_282
	s_add_i32 s4, 0, 0x20040
	v_mov_b32_e32 v1, s4
	s_waitcnt vmcnt(0) expcnt(0) lgkmcnt(0)
	ds_read_b32 v3, v1
	s_add_i32 s4, 0, 0x20044
	v_mov_b32_e32 v1, s4
	ds_read_b32 v1, v1
	s_waitcnt lgkmcnt(1)
	v_cmp_ne_u32_e32 vcc, 0, v3
	s_cbranch_vccnz .LBB0_245
	s_load_dwordx2 s[8:9], s[84:85], 0x0
	s_load_dword s7, s[84:85], 0x8
	s_add_u32 s4, s30, 0x1000
	s_addc_u32 s5, s31, 0
	s_add_u32 s6, s30, 0x1100
	s_waitcnt lgkmcnt(0)
	s_mul_i32 s33, s9, s8
	s_mul_i32 s33, s33, s7
	s_addc_u32 s7, s31, 0
	s_add_u32 s8, s30, 0x1200
	s_addc_u32 s9, s31, 0
	s_add_u32 s10, s30, 0x1300
	s_addc_u32 s11, s31, 0
	s_mov_b32 s38, 1
	v_mov_b32_e32 v17, 0
	s_branch .LBB0_233

; #define PG8_STAGE(bufoff, gbase, voff) do { _Pragma("unroll") for (int _i = 0; _i < 2; ++_i) \
;         __builtin_amdgcn_global_load_lds((const unsigned*)((const char*)(gbase) + (voff)[_i]), (PG8_LAS unsigned*)(lds + (bufoff) + ldsw + _i * 8192), 16, 0, 0); } while (0)
; #define PG8_WAIT_V(n) asm volatile("s_waitcnt vmcnt(" #n ")" ::: "memory")
; #define PG8_BAR __builtin_amdgcn_s_barrier()
; template <class Epi, class Sched, bool ALIGN_EPI = false, bool SP2 = false>
; __device__ __forceinline__ void gemm_phase(PG8_LAS unsigned char* lds, const Gemm g, const Sched& S, const Epi& E) {
;     ...
;     const unsigned ldsw = (unsigned)wid * 1024u;
;     const int aoff = lds_byte(wr * 64 + fr, fq * 8), boff = lds_byte(wc * 32 + fr, fq * 8);
;     ...
;         PG8_WAIT_V(2); PG8_BAR;
;         PG8_STAGE(PG8_SB(1, 0), cB + kstep, voffB); PG8_STAGE(PG8_SA(1, 0), cA + kstep, voffA); PG8_STAGE(PG8_SB(1, 1), cB + hB + kstep, voffB);
;         PG8_WAIT_V(6); PG8_BAR;
.LBB0_775:
	s_add_u32 s10, s6, 0x1d800000
	s_addc_u32 s11, s7, 0
	s_lshl_b32 s12, s12, 5
	s_and_b32 s18, s12, 0x60
	s_mov_b64 s[12:13], 0x80
	s_add_i32 m0, s39, 0x18000
	v_lshl_add_u64 v[8:9], v[8:9], 0, s[12:13]
	s_lshl_b32 s15, s14, 13
	s_lshl_b32 s19, s18, 7
	s_waitcnt vmcnt(2)
	s_barrier
	global_load_lds_dwordx4 v[8:9], off
	v_lshl_add_u64 v[6:7], v[6:7], 0, s[12:13]
	s_add_i32 m0, s39, 0x1a000
	s_add_i32 s77, s39, 0x8000
	s_add_i32 s78, s39, 0xa000
	global_load_lds_dwordx4 v[6:7], off
	v_lshl_add_u64 v[4:5], v[4:5], 0, s[12:13]
	s_mov_b32 m0, s77
	s_add_u32 s16, s42, 0x10080
	global_load_lds_dwordx4 v[4:5], off
	v_lshl_add_u64 v[2:3], v[2:3], 0, s[12:13]
	s_mov_b32 m0, s78
	s_addc_u32 s17, s43, 0
	global_load_lds_dwordx4 v[2:3], off
	s_add_i32 m0, s39, 0x1c000
	v_lshl_add_u64 v[2:3], s[16:17], 0, v[134:135]
	global_load_lds_dwordx4 v[2:3], off
	v_lshl_add_u64 v[2:3], s[16:17], 0, v[130:131]
	s_add_i32 m0, s39, 0x1e000
	s_cmpk_lt_u32 s5, 0x100
	global_load_lds_dwordx4 v[2:3], off
	v_lshrrev_b32_e32 v3, 1, v10
	v_and_b32_e32 v3, 24, v3
	v_and_b32_e32 v2, 15, v10
	v_lshlrev_b32_e32 v4, 1, v3
	v_lshl_or_b32 v142, s14, 6, v2
	v_lshl_or_b32 v2, v2, 6, v4
	v_lshlrev_b32_e32 v4, 2, v10
	v_and_b32_e32 v4, 32, v4
	s_waitcnt vmcnt(6)
	v_bitop3_b32 v5, v2, s15, v4 bitop3:0xde
	v_bitop3_b32 v143, v2, s19, v4 bitop3:0xde
	s_cselect_b64 s[14:15], -1, 0
	s_add_i32 s80, 0, 0x10000
	s_add_i32 s81, 0, 0x14000
	s_sext_i32_i8 s86, s4
	s_waitcnt lgkmcnt(0)
	s_ashr_i32 s79, s33, 31
	v_or_b32_e32 v144, s18, v3
	v_mov_b64_e32 v[138:139], 0x100
	v_mov_b64_e32 v[140:141], 0xff
	v_add_u32_e32 v145, s80, v143
	v_add_u32_e32 v146, s81, v143
	v_add_u32_e32 v147, 0, v5
	s_mov_b32 s82, 0x40000
	s_mov_b64 s[16:17], 0x48000
	s_mov_b32 s83, 0x48000
	s_mov_b64 s[20:21], 0x50000
	s_mov_b32 s84, 0x50000
	s_mov_b64 s[22:23], 0x58000
	s_mov_b32 s85, 0x58000
	s_barrier
	s_waitcnt vmcnt(0)
	v_readfirstlane_b32 s99, v0
	s_nop 3
	s_lshr_b32 s99, s99, 8
	s_cmp_eq_u32 s99, 0
	s_cbranch_scc1 .Lprio_skip_2
	s_setprio 1

; #define PG8_WAIT_V(n) asm volatile("s_waitcnt vmcnt(" #n ")" ::: "memory")
; #define PG8_BAR __builtin_amdgcn_s_barrier()
; template <class Epi, class Sched, bool ALIGN_EPI = false, bool SP2 = false>
; __device__ __forceinline__ void gemm_phase(PG8_LAS unsigned char* lds, const Gemm g, const Sched& S, const Epi& E) {
;     ...
;     PG8_WAIT_V(0);
;     if constexpr (!ALIGN_EPI) { if (wr == 0) PG8_BAR; }
;     PG8_BAR;
; __device__ __forceinline__ void xcd_barrier(const XcdBarrier& b) {
;     asm volatile("s_waitcnt vmcnt(0)" ::: "memory");
;     __syncthreads();
;     if (threadIdx.x == 0) {
;         unsigned* bar = b.bar;
;         __builtin_amdgcn_s_waitcnt(0);
;         unsigned nloc = b.st[0], nx = b.st[1];
;         if (nloc == 0u) { xcd_barrier_complete(bar, b.x, nloc, nx); b.st[0] = nloc; b.st[1] = nx; }
.LBB0_802:
	s_setprio 0
	s_waitcnt vmcnt(0)
	s_waitcnt vmcnt(0)
	s_barrier
	s_and_saveexec_b64 s[0:1], s[86:87]
	s_xor_b64 s[0:1], exec, s[0:1]
	s_cbranch_execz .LBB0_855
	s_add_i32 s4, 0, 0x20040
	v_mov_b32_e32 v1, s4
	s_waitcnt vmcnt(0) expcnt(0) lgkmcnt(0)
	ds_read_b32 v3, v1
	s_add_i32 s4, 0, 0x20044
	v_mov_b32_e32 v1, s4
	ds_read_b32 v1, v1
	s_waitcnt lgkmcnt(1)
	v_cmp_ne_u32_e32 vcc, 0, v3
	s_cbranch_vccnz .LBB0_818
	s_load_dwordx2 s[8:9], s[84:85], 0x0
	s_load_dword s7, s[84:85], 0x8
	s_add_u32 s4, s30, 0x1000
	s_addc_u32 s5, s31, 0
	s_add_u32 s6, s30, 0x1100
	s_waitcnt lgkmcnt(0)
	s_mul_i32 s20, s9, s8
	s_mul_i32 s20, s20, s7
	s_addc_u32 s7, s31, 0
	s_add_u32 s8, s30, 0x1200
	s_addc_u32 s9, s31, 0
	s_add_u32 s10, s30, 0x1300
	s_addc_u32 s11, s31, 0
	s_mov_b32 s21, 1
	v_mov_b32_e32 v17, 0
	s_branch .LBB0_806

; #define PG8_STAGE(bufoff, gbase, voff) do { _Pragma("unroll") for (int _i = 0; _i < 2; ++_i) \
;         __builtin_amdgcn_global_load_lds((const unsigned*)((const char*)(gbase) + (voff)[_i]), (PG8_LAS unsigned*)(lds + (bufoff) + ldsw + _i * 8192), 16, 0, 0); } while (0)
; #define PG8_WAIT_V(n) asm volatile("s_waitcnt vmcnt(" #n ")" ::: "memory")
; #define PG8_BAR __builtin_amdgcn_s_barrier()
; template <class Epi, class Sched, bool ALIGN_EPI = false, bool SP2 = false>
; __device__ __forceinline__ void gemm_phase(PG8_LAS unsigned char* lds, const Gemm g, const Sched& S, const Epi& E) {
;     ...
;         PG8_WAIT_V(2); PG8_BAR;
;         PG8_STAGE(PG8_SB(1, 0), cB + kstep, voffB); PG8_STAGE(PG8_SA(1, 0), cA + kstep, voffA); PG8_STAGE(PG8_SB(1, 1), cB + hB + kstep, voffB);
;         PG8_WAIT_V(6); PG8_BAR;
;     __device__ __forceinline__ void operator()(AccRef acc, const pg8::Unit& u, int wr, int wc, int fr, int fq) const {
;         const int row0 = u.pm * 256 + wr * 64 + fr, c0 = u.pn * 256 + wc * 32 + 8 * fq;
; #pragma unroll
;         for (int ai = 0; ai < 2; ++ai) {
;             u32x4 gv[4][2], tv[4][2];
; #pragma unroll
;             for (int m = 0; m < 4; ++m) { const int r = row0 + ai * 128 + m * 16;
; #pragma unroll
;                 for (int bj = 0; bj < 2; ++bj) { const int c = c0 + bj * 128;
;                     gv[m][bj] = *(const u32x4*)(sg + (size_t)r * 4096 + (SECOND ? 0 : 2048) + c);
;                     if (SECOND) tv[m][bj] = *(const u32x4*)(tmp + (size_t)r * 2048 + c); } }
.LBB0_858:
	s_add_u32 s6, s4, 0xd800000
	s_addc_u32 s7, s5, 0
	s_lshl_b32 s4, s8, 5
	s_mov_b64 s[8:9], 0x80
	s_and_b32 s18, s4, 0x60
	s_add_i32 m0, s41, 0x18000
	v_lshl_add_u64 v[8:9], v[8:9], 0, s[8:9]
	s_lshl_b32 s17, s16, 13
	s_lshl_b32 s19, s18, 7
	s_waitcnt vmcnt(2)
	s_barrier
	global_load_lds_dwordx4 v[8:9], off
	v_lshl_add_u64 v[6:7], v[6:7], 0, s[8:9]
	s_add_i32 m0, s41, 0x1a000
	s_add_i32 s60, s41, 0x8000
	s_add_i32 s61, s41, 0xa000
	global_load_lds_dwordx4 v[6:7], off
	v_lshl_add_u64 v[2:3], v[2:3], 0, s[8:9]
	s_mov_b32 m0, s60
	s_add_u32 s4, s44, 0x40080
	global_load_lds_dwordx4 v[2:3], off
	v_lshl_add_u64 v[2:3], v[4:5], 0, s[8:9]
	s_mov_b32 m0, s61
	s_addc_u32 s5, s45, 0
	global_load_lds_dwordx4 v[2:3], off
	s_add_i32 m0, s41, 0x1c000
	v_lshl_add_u64 v[2:3], s[4:5], 0, v[134:135]
	global_load_lds_dwordx4 v[2:3], off
	v_lshl_add_u64 v[2:3], s[4:5], 0, v[130:131]
	s_add_i32 m0, s41, 0x1e000
	s_cmpk_lt_u32 s15, 0x100
	global_load_lds_dwordx4 v[2:3], off
	v_lshrrev_b32_e32 v3, 1, v11
	v_and_b32_e32 v3, 24, v3
	v_and_b32_e32 v2, 15, v11
	v_lshlrev_b32_e32 v4, 1, v3
	v_lshl_or_b32 v1, s16, 6, v2
	v_lshl_or_b32 v2, v2, 6, v4
	v_lshlrev_b32_e32 v4, 2, v11
	v_and_b32_e32 v4, 32, v4
	v_bitop3_b32 v5, v2, s17, v4 bitop3:0xde
	v_bitop3_b32 v154, v2, s19, v4 bitop3:0xde
	v_lshlrev_b32_e32 v2, 14, v15
	v_and_b32_e32 v2, 0xffff8000, v2
	v_or_b32_e32 v155, s18, v3
	v_lshl_add_u32 v2, v14, 11, v2
	v_and_b32_e32 v3, 1, v15
	v_lshl_or_b32 v2, v3, 6, v2
	v_lshl_add_u32 v138, v16, 1, v2
	v_lshlrev_b32_e32 v2, 14, v10
	v_and_b32_e32 v2, 0xffff8000, v2
	s_waitcnt vmcnt(6)
	v_lshl_add_u32 v2, v12, 11, v2
	v_and_b32_e32 v3, 1, v10
	s_sext_i32_i8 s66, s14
	s_cselect_b64 s[14:15], -1, 0
	v_lshl_or_b32 v2, v3, 6, v2
	s_add_i32 s64, 0, 0x10000
	s_add_i32 s65, 0, 0x14000
	s_mov_b32 s62, 0
	s_waitcnt lgkmcnt(0)
	s_ashr_i32 s63, s50, 31
	v_mov_b32_e32 v139, v135
	v_lshl_add_u32 v140, v13, 1, v2
	v_mov_b32_e32 v141, v135
	v_mov_b64_e32 v[142:143], 0x200
	v_mov_b64_e32 v[144:145], 0x1ff
	v_add_u32_e32 v156, s64, v154
	v_add_u32_e32 v157, s65, v154
	v_add_u32_e32 v158, 0, v5
	s_mov_b64 s[16:17], 0x1000
	s_barrier
	v_readfirstlane_b32 s99, v0
	s_nop 3
	s_lshr_b32 s99, s99, 8
	s_cmp_eq_u32 s99, 0
	s_cbranch_scc1 .Lprio_skip_3
	s_setprio 1

; #define PG8_STAGE(bufoff, gbase, voff) do { _Pragma("unroll") for (int _i = 0; _i < 2; ++_i) \
;         __builtin_amdgcn_global_load_lds((const unsigned*)((const char*)(gbase) + (voff)[_i]), (PG8_LAS unsigned*)(lds + (bufoff) + ldsw + _i * 8192), 16, 0, 0); } while (0)
; #define PG8_LDA(dst, b, h) do { _Pragma("unroll") for (int m = 0; m < 4; ++m) _Pragma("unroll") for (int k = 0; k < 2; ++k) dst[m][k] = *(const PG8_LAS bf16x8*)(lds + PG8_SA(b, h) + aoff + m * 2048 + k * 1024); } while (0)
; #define PG8_LDB(dst, b, h) do { _Pragma("unroll") for (int n = 0; n < 2; ++n) _Pragma("unroll") for (int k = 0; k < 2; ++k) dst[n][k] = *(const PG8_LAS bf16x8*)(lds + PG8_SB(b, h) + boff + n * 2048 + k * 1024); } while (0)
; #define PG8_MMA(ai, bj, At, Bt) do { __builtin_amdgcn_s_setprio(1); _Pragma("unroll") for (int m = 0; m < 4; ++m) _Pragma("unroll") for (int n = 0; n < 2; ++n) _Pragma("unroll") for (int k = 0; k < 2; ++k) \
;         acc[ai][bj][m][n] = __builtin_amdgcn_mfma_f32_16x16x32_bf16(Bt[n][k], At[m][k], acc[ai][bj][m][n], 0, 0, 0); __builtin_amdgcn_s_setprio(0); } while (0)
; #define PG8_WAIT_V(n) asm volatile("s_waitcnt vmcnt(" #n ")" ::: "memory")
; #define PG8_WAIT_L(n) asm volatile("s_waitcnt lgkmcnt(" #n ")" ::: "memory")
; #define PG8_BAR __builtin_amdgcn_s_barrier()
; #define PG8_SCHED __builtin_amdgcn_sched_barrier(0)
; template <class Epi, class Sched, bool ALIGN_EPI = false, bool SP2 = false>
; __device__ __forceinline__ void gemm_phase(PG8_LAS unsigned char* lds, const Gemm g, const Sched& S, const Epi& E) {
;     ...
;             PG8_LDB(B0, 0, 0); PG8_LDB(B1, 0, 1); PG8_SCHED; PG8_LDA(At, 0, 0); PG8_STAGE(PG8_SA(1, 1), a1 + hA, voffA);
;             PG8_WAIT_V(8); PG8_WAIT_L(0); PG8_BAR; PG8_MMA(0, 0, At, B0); PG8_MMA(0, 1, At, B1); PG8_BAR; PG8_SCHED;
;             PG8_LDA(At, 0, 1); PG8_STAGE(PG8_SB(0, 0), b2, voffB); PG8_STAGE(PG8_SB(0, 1), b2 + hB, voffB); PG8_STAGE(PG8_SA(0, 0), a2, voffA);
;             PG8_WAIT_V(8); PG8_WAIT_L(0); PG8_BAR; PG8_MMA(1, 0, At, B0); PG8_MMA(1, 1, At, B1); PG8_BAR; PG8_SCHED;
.LBB0_868:
	ds_read_b128 v[146:149], v156
	ds_read_b128 v[150:153], v156 offset:1024
	ds_read_b128 v[160:163], v156 offset:2048
	ds_read_b128 v[164:167], v156 offset:3072
	ds_read_b128 v[168:171], v157
	ds_read_b128 v[172:175], v157 offset:1024
	ds_read_b128 v[176:179], v157 offset:2048
	ds_read_b128 v[180:183], v157 offset:3072
	s_add_u32 s18, s42, 0xfffc0080
	s_addc_u32 s19, s43, -1
	s_cmp_eq_u32 s72, 12
	s_cselect_b32 s47, s23, s19
	s_cselect_b32 s46, s67, s18
	s_cselect_b32 s45, s21, s71
	s_cselect_b32 s44, s69, s70
	v_lshl_add_u64 v[216:217], s[42:43], 0, v[138:139]
	s_add_i32 m0, s41, 0xc000
	ds_read_b128 v[184:187], v158
	ds_read_b128 v[188:191], v158 offset:1024
	ds_read_b128 v[192:195], v158 offset:2048
	ds_read_b128 v[196:199], v158 offset:3072
	ds_read_b128 v[200:203], v158 offset:4096
	ds_read_b128 v[204:207], v158 offset:5120
	ds_read_b128 v[208:211], v158 offset:6144
	ds_read_b128 v[212:215], v158 offset:7168
	global_load_lds_dwordx4 v[216:217], off
	v_lshl_add_u64 v[216:217], s[42:43], 0, v[140:141]
	s_add_i32 m0, s41, 0xe000
	s_nop 0
	global_load_lds_dwordx4 v[216:217], off
	s_waitcnt vmcnt(8)
	s_waitcnt lgkmcnt(0)
	s_barrier
	s_waitcnt lgkmcnt(0)
	v_mfma_f32_16x16x32_bf16 v[126:129], v[146:149], v[184:187], v[126:129]
	v_mfma_f32_16x16x32_bf16 v[122:125], v[160:163], v[184:187], v[122:125]
	v_mfma_f32_16x16x32_bf16 v[114:117], v[146:149], v[192:195], v[114:117]
	v_mfma_f32_16x16x32_bf16 v[106:109], v[160:163], v[192:195], v[106:109]
	v_mfma_f32_16x16x32_bf16 v[98:101], v[146:149], v[200:203], v[98:101]
	v_mfma_f32_16x16x32_bf16 v[90:93], v[160:163], v[200:203], v[90:93]
	v_mfma_f32_16x16x32_bf16 v[82:85], v[146:149], v[208:211], v[82:85]
	v_mfma_f32_16x16x32_bf16 v[74:77], v[160:163], v[208:211], v[74:77]
	v_mfma_f32_16x16x32_bf16 v[126:129], v[150:153], v[188:191], v[126:129]
	v_mfma_f32_16x16x32_bf16 v[122:125], v[164:167], v[188:191], v[122:125]
	v_mfma_f32_16x16x32_bf16 v[114:117], v[150:153], v[196:199], v[114:117]
	v_mfma_f32_16x16x32_bf16 v[106:109], v[164:167], v[196:199], v[106:109]
	v_mfma_f32_16x16x32_bf16 v[98:101], v[150:153], v[204:207], v[98:101]
	v_mfma_f32_16x16x32_bf16 v[90:93], v[164:167], v[204:207], v[90:93]
	v_mfma_f32_16x16x32_bf16 v[82:85], v[150:153], v[212:215], v[82:85]
	v_mfma_f32_16x16x32_bf16 v[74:77], v[164:167], v[212:215], v[74:77]
	v_mfma_f32_16x16x32_bf16 v[118:121], v[168:171], v[184:187], v[118:121]
	v_mfma_f32_16x16x32_bf16 v[110:113], v[176:179], v[184:187], v[110:113]
	v_mfma_f32_16x16x32_bf16 v[102:105], v[168:171], v[192:195], v[102:105]
	v_mfma_f32_16x16x32_bf16 v[94:97], v[176:179], v[192:195], v[94:97]
	v_mfma_f32_16x16x32_bf16 v[86:89], v[168:171], v[200:203], v[86:89]
	v_mfma_f32_16x16x32_bf16 v[78:81], v[176:179], v[200:203], v[78:81]
	v_mfma_f32_16x16x32_bf16 v[70:73], v[168:171], v[208:211], v[70:73]
	v_mfma_f32_16x16x32_bf16 v[66:69], v[176:179], v[208:211], v[66:69]
	v_mfma_f32_16x16x32_bf16 v[118:121], v[172:175], v[188:191], v[118:121]
	v_mfma_f32_16x16x32_bf16 v[110:113], v[180:183], v[188:191], v[110:113]
	v_mfma_f32_16x16x32_bf16 v[102:105], v[172:175], v[196:199], v[102:105]
	v_mfma_f32_16x16x32_bf16 v[94:97], v[180:183], v[196:199], v[94:97]
	v_mfma_f32_16x16x32_bf16 v[86:89], v[172:175], v[204:207], v[86:89]
	v_mfma_f32_16x16x32_bf16 v[78:81], v[180:183], v[204:207], v[78:81]
	v_mfma_f32_16x16x32_bf16 v[70:73], v[172:175], v[212:215], v[70:73]
	v_mfma_f32_16x16x32_bf16 v[66:69], v[180:183], v[212:215], v[66:69]
	s_barrier
	s_add_i32 s18, s64, s52
	v_lshl_add_u64 v[216:217], s[44:45], 0, v[134:135]
	s_mov_b32 m0, s18
	ds_read_b128 v[184:187], v158 offset:16384
	ds_read_b128 v[188:191], v158 offset:17408
	ds_read_b128 v[192:195], v158 offset:18432
	ds_read_b128 v[196:199], v158 offset:19456
	ds_read_b128 v[200:203], v158 offset:20480
	ds_read_b128 v[204:207], v158 offset:21504
	ds_read_b128 v[208:211], v158 offset:22528
	ds_read_b128 v[212:215], v158 offset:23552
	global_load_lds_dwordx4 v[216:217], off
	s_add_i32 m0, s18, 0x2000
	s_add_u32 s74, s44, 0x40000
	v_lshl_add_u64 v[218:219], s[44:45], 0, v[130:131]
	s_addc_u32 s75, s45, 0
	s_add_i32 s18, s65, s52
	global_load_lds_dwordx4 v[218:219], off
	v_lshl_add_u64 v[220:221], s[74:75], 0, v[134:135]
	s_mov_b32 m0, s18
	v_lshl_add_u64 v[224:225], s[46:47], 0, v[132:133]
	global_load_lds_dwordx4 v[220:221], off
	v_lshl_add_u64 v[220:221], s[74:75], 0, v[130:131]
	s_add_i32 m0, s18, 0x2000
	s_nop 0
	global_load_lds_dwordx4 v[220:221], off
	v_lshl_add_u64 v[220:221], s[46:47], 0, v[136:137]
	s_mov_b32 m0, s41
	s_nop 0
	global_load_lds_dwordx4 v[220:221], off
	s_mov_b32 m0, s53
	s_nop 0
	global_load_lds_dwordx4 v[224:225], off
	s_waitcnt vmcnt(8)
	s_waitcnt lgkmcnt(0)
	s_barrier
; #define PG8_STAGE(bufoff, gbase, voff) do { _Pragma("unroll") for (int _i = 0; _i < 2; ++_i) \
;         __builtin_amdgcn_global_load_lds((const unsigned*)((const char*)(gbase) + (voff)[_i]), (PG8_LAS unsigned*)(lds + (bufoff) + ldsw + _i * 8192), 16, 0, 0); } while (0)
; #define PG8_LDA(dst, b, h) do { _Pragma("unroll") for (int m = 0; m < 4; ++m) _Pragma("unroll") for (int k = 0; k < 2; ++k) dst[m][k] = *(const PG8_LAS bf16x8*)(lds + PG8_SA(b, h) + aoff + m * 2048 + k * 1024); } while (0)
; #define PG8_LDB(dst, b, h) do { _Pragma("unroll") for (int n = 0; n < 2; ++n) _Pragma("unroll") for (int k = 0; k < 2; ++k) dst[n][k] = *(const PG8_LAS bf16x8*)(lds + PG8_SB(b, h) + boff + n * 2048 + k * 1024); } while (0)
; #define PG8_MMA(ai, bj, At, Bt) do { __builtin_amdgcn_s_setprio(1); _Pragma("unroll") for (int m = 0; m < 4; ++m) _Pragma("unroll") for (int n = 0; n < 2; ++n) _Pragma("unroll") for (int k = 0; k < 2; ++k) \
;         acc[ai][bj][m][n] = __builtin_amdgcn_mfma_f32_16x16x32_bf16(Bt[n][k], At[m][k], acc[ai][bj][m][n], 0, 0, 0); __builtin_amdgcn_s_setprio(0); } while (0)
; #define PG8_WAIT_V(n) asm volatile("s_waitcnt vmcnt(" #n ")" ::: "memory")
; #define PG8_WAIT_L(n) asm volatile("s_waitcnt lgkmcnt(" #n ")" ::: "memory")
; #define PG8_BAR __builtin_amdgcn_s_barrier()
; #define PG8_SCHED __builtin_amdgcn_sched_barrier(0)
; template <class Epi, class Sched, bool ALIGN_EPI = false, bool SP2 = false>
; __device__ __forceinline__ void gemm_phase(PG8_LAS unsigned char* lds, const Gemm g, const Sched& S, const Epi& E) {
;     ...
;             PG8_WAIT_V(8); PG8_WAIT_L(0); PG8_BAR; PG8_MMA(1, 0, At, B0); PG8_MMA(1, 1, At, B1); PG8_BAR; PG8_SCHED;
;             PG8_LDB(B0, 1, 0); PG8_LDB(B1, 1, 1); PG8_SCHED; PG8_LDA(At, 1, 0); PG8_STAGE(PG8_SA(0, 1), a2 + hA, voffA);
;             PG8_WAIT_V(8); PG8_WAIT_L(0); PG8_BAR; PG8_MMA(0, 0, At, B0); PG8_MMA(0, 1, At, B1); PG8_BAR; PG8_SCHED;
	s_waitcnt lgkmcnt(0)
	v_mfma_f32_16x16x32_bf16 v[62:65], v[146:149], v[184:187], v[62:65]
	v_mfma_f32_16x16x32_bf16 v[58:61], v[160:163], v[184:187], v[58:61]
	v_mfma_f32_16x16x32_bf16 v[50:53], v[146:149], v[192:195], v[50:53]
	v_mfma_f32_16x16x32_bf16 v[42:45], v[160:163], v[192:195], v[42:45]
	v_mfma_f32_16x16x32_bf16 v[34:37], v[146:149], v[200:203], v[34:37]
	v_mfma_f32_16x16x32_bf16 v[26:29], v[160:163], v[200:203], v[26:29]
	v_mfma_f32_16x16x32_bf16 v[18:21], v[146:149], v[208:211], v[18:21]
	v_mfma_f32_16x16x32_bf16 v[10:13], v[160:163], v[208:211], v[10:13]
	v_mfma_f32_16x16x32_bf16 v[62:65], v[150:153], v[188:191], v[62:65]
	v_mfma_f32_16x16x32_bf16 v[58:61], v[164:167], v[188:191], v[58:61]
	v_mfma_f32_16x16x32_bf16 v[50:53], v[150:153], v[196:199], v[50:53]
	v_mfma_f32_16x16x32_bf16 v[42:45], v[164:167], v[196:199], v[42:45]
	v_mfma_f32_16x16x32_bf16 v[34:37], v[150:153], v[204:207], v[34:37]
	v_mfma_f32_16x16x32_bf16 v[26:29], v[164:167], v[204:207], v[26:29]
	v_mfma_f32_16x16x32_bf16 v[18:21], v[150:153], v[212:215], v[18:21]
	v_mfma_f32_16x16x32_bf16 v[10:13], v[164:167], v[212:215], v[10:13]
	v_mfma_f32_16x16x32_bf16 v[54:57], v[168:171], v[184:187], v[54:57]
	v_mfma_f32_16x16x32_bf16 v[46:49], v[176:179], v[184:187], v[46:49]
	v_mfma_f32_16x16x32_bf16 v[38:41], v[168:171], v[192:195], v[38:41]
	v_mfma_f32_16x16x32_bf16 v[30:33], v[176:179], v[192:195], v[30:33]
	v_mfma_f32_16x16x32_bf16 v[22:25], v[168:171], v[200:203], v[22:25]
	v_mfma_f32_16x16x32_bf16 v[14:17], v[176:179], v[200:203], v[14:17]
	v_mfma_f32_16x16x32_bf16 v[6:9], v[168:171], v[208:211], v[6:9]
	v_mfma_f32_16x16x32_bf16 v[2:5], v[176:179], v[208:211], v[2:5]
	v_mfma_f32_16x16x32_bf16 v[54:57], v[172:175], v[188:191], v[54:57]
	v_mfma_f32_16x16x32_bf16 v[46:49], v[180:183], v[188:191], v[46:49]
	v_mfma_f32_16x16x32_bf16 v[38:41], v[172:175], v[196:199], v[38:41]
	v_mfma_f32_16x16x32_bf16 v[30:33], v[180:183], v[196:199], v[30:33]
	v_mfma_f32_16x16x32_bf16 v[22:25], v[172:175], v[204:207], v[22:25]
	v_mfma_f32_16x16x32_bf16 v[14:17], v[180:183], v[204:207], v[14:17]
	v_mfma_f32_16x16x32_bf16 v[6:9], v[172:175], v[212:215], v[6:9]
	v_mfma_f32_16x16x32_bf16 v[2:5], v[180:183], v[212:215], v[2:5]
	s_barrier
	s_add_i32 s18, 0, 0x18000
	v_add_u32_e32 v159, s18, v154
	s_add_i32 s19, 0, 0x1c000
	ds_read_b128 v[146:149], v159
	ds_read_b128 v[150:153], v159 offset:1024
	ds_read_b128 v[160:163], v159 offset:2048
	ds_read_b128 v[164:167], v159 offset:3072
	v_add_u32_e32 v159, s19, v154
	ds_read_b128 v[168:171], v159
	ds_read_b128 v[172:175], v159 offset:1024
	ds_read_b128 v[176:179], v159 offset:2048
	ds_read_b128 v[180:183], v159 offset:3072
	s_add_u32 s46, s46, 0x40000
	s_addc_u32 s47, s47, 0
	s_mov_b32 m0, s58
	v_lshl_add_u64 v[226:227], s[46:47], 0, v[136:137]
	ds_read_b128 v[184:187], v158 offset:32768
	ds_read_b128 v[188:191], v158 offset:33792
	ds_read_b128 v[192:195], v158 offset:34816
	ds_read_b128 v[196:199], v158 offset:35840
	ds_read_b128 v[200:203], v158 offset:36864
	ds_read_b128 v[204:207], v158 offset:37888
	ds_read_b128 v[208:211], v158 offset:38912
	ds_read_b128 v[212:215], v158 offset:39936
	global_load_lds_dwordx4 v[226:227], off
	v_lshl_add_u64 v[226:227], s[46:47], 0, v[132:133]
	s_mov_b32 m0, s59
	s_nop 0
	global_load_lds_dwordx4 v[226:227], off
	s_waitcnt vmcnt(8)
	s_waitcnt lgkmcnt(0)
	s_barrier
	s_waitcnt lgkmcnt(0)
	v_mfma_f32_16x16x32_bf16 v[126:129], v[146:149], v[184:187], v[126:129]
	v_mfma_f32_16x16x32_bf16 v[122:125], v[160:163], v[184:187], v[122:125]
	v_mfma_f32_16x16x32_bf16 v[114:117], v[146:149], v[192:195], v[114:117]
	v_mfma_f32_16x16x32_bf16 v[106:109], v[160:163], v[192:195], v[106:109]
	v_mfma_f32_16x16x32_bf16 v[98:101], v[146:149], v[200:203], v[98:101]
	v_mfma_f32_16x16x32_bf16 v[90:93], v[160:163], v[200:203], v[90:93]
	v_mfma_f32_16x16x32_bf16 v[82:85], v[146:149], v[208:211], v[82:85]
	v_mfma_f32_16x16x32_bf16 v[74:77], v[160:163], v[208:211], v[74:77]
	v_mfma_f32_16x16x32_bf16 v[126:129], v[150:153], v[188:191], v[126:129]
	v_mfma_f32_16x16x32_bf16 v[122:125], v[164:167], v[188:191], v[122:125]
	v_mfma_f32_16x16x32_bf16 v[114:117], v[150:153], v[196:199], v[114:117]
	v_mfma_f32_16x16x32_bf16 v[106:109], v[164:167], v[196:199], v[106:109]
	v_mfma_f32_16x16x32_bf16 v[98:101], v[150:153], v[204:207], v[98:101]
	v_mfma_f32_16x16x32_bf16 v[90:93], v[164:167], v[204:207], v[90:93]
	v_mfma_f32_16x16x32_bf16 v[82:85], v[150:153], v[212:215], v[82:85]
	v_mfma_f32_16x16x32_bf16 v[74:77], v[164:167], v[212:215], v[74:77]
	v_mfma_f32_16x16x32_bf16 v[118:121], v[168:171], v[184:187], v[118:121]
	v_mfma_f32_16x16x32_bf16 v[110:113], v[176:179], v[184:187], v[110:113]
	v_mfma_f32_16x16x32_bf16 v[102:105], v[168:171], v[192:195], v[102:105]
	v_mfma_f32_16x16x32_bf16 v[94:97], v[176:179], v[192:195], v[94:97]
	v_mfma_f32_16x16x32_bf16 v[86:89], v[168:171], v[200:203], v[86:89]
	v_mfma_f32_16x16x32_bf16 v[78:81], v[176:179], v[200:203], v[78:81]
	v_mfma_f32_16x16x32_bf16 v[70:73], v[168:171], v[208:211], v[70:73]
	v_mfma_f32_16x16x32_bf16 v[66:69], v[176:179], v[208:211], v[66:69]
	v_mfma_f32_16x16x32_bf16 v[118:121], v[172:175], v[188:191], v[118:121]
	v_mfma_f32_16x16x32_bf16 v[110:113], v[180:183], v[188:191], v[110:113]
	v_mfma_f32_16x16x32_bf16 v[102:105], v[172:175], v[196:199], v[102:105]
	v_mfma_f32_16x16x32_bf16 v[94:97], v[180:183], v[196:199], v[94:97]
	v_mfma_f32_16x16x32_bf16 v[86:89], v[172:175], v[204:207], v[86:89]
	v_mfma_f32_16x16x32_bf16 v[78:81], v[180:183], v[204:207], v[78:81]
	v_mfma_f32_16x16x32_bf16 v[70:73], v[172:175], v[212:215], v[70:73]
	v_mfma_f32_16x16x32_bf16 v[66:69], v[180:183], v[212:215], v[66:69]
	s_barrier
; #define PG8_STAGE(bufoff, gbase, voff) do { _Pragma("unroll") for (int _i = 0; _i < 2; ++_i) \
;         __builtin_amdgcn_global_load_lds((const unsigned*)((const char*)(gbase) + (voff)[_i]), (PG8_LAS unsigned*)(lds + (bufoff) + ldsw + _i * 8192), 16, 0, 0); } while (0)
; #define PG8_LDA(dst, b, h) do { _Pragma("unroll") for (int m = 0; m < 4; ++m) _Pragma("unroll") for (int k = 0; k < 2; ++k) dst[m][k] = *(const PG8_LAS bf16x8*)(lds + PG8_SA(b, h) + aoff + m * 2048 + k * 1024); } while (0)
; #define PG8_MMA(ai, bj, At, Bt) do { __builtin_amdgcn_s_setprio(1); _Pragma("unroll") for (int m = 0; m < 4; ++m) _Pragma("unroll") for (int n = 0; n < 2; ++n) _Pragma("unroll") for (int k = 0; k < 2; ++k) \
;         acc[ai][bj][m][n] = __builtin_amdgcn_mfma_f32_16x16x32_bf16(Bt[n][k], At[m][k], acc[ai][bj][m][n], 0, 0, 0); __builtin_amdgcn_s_setprio(0); } while (0)
; #define PG8_WAIT_V(n) asm volatile("s_waitcnt vmcnt(" #n ")" ::: "memory")
; #define PG8_WAIT_L(n) asm volatile("s_waitcnt lgkmcnt(" #n ")" ::: "memory")
; #define PG8_BAR __builtin_amdgcn_s_barrier()
; #define PG8_SCHED __builtin_amdgcn_sched_barrier(0)
; template <class Epi, class Sched, bool ALIGN_EPI = false, bool SP2 = false>
; __device__ __forceinline__ void gemm_phase(PG8_LAS unsigned char* lds, const Gemm g, const Sched& S, const Epi& E) {
;     ...
;             PG8_WAIT_V(8); PG8_WAIT_L(0); PG8_BAR; PG8_MMA(0, 0, At, B0); PG8_MMA(0, 1, At, B1); PG8_BAR; PG8_SCHED;
;             PG8_LDA(At, 1, 1); PG8_STAGE(PG8_SB(1, 0), b3, voffB); PG8_STAGE(PG8_SB(1, 1), b3 + hB, voffB); PG8_STAGE(PG8_SA(1, 0), a3, voffA);
;             PG8_WAIT_V(8); PG8_WAIT_L(0); PG8_BAR; PG8_MMA(1, 0, At, B0); PG8_MMA(1, 1, At, B1); PG8_BAR; PG8_SCHED;
;     ...
;         if constexpr (ALIGN_EPI) { if (wr == 0) PG8_BAR; }
	s_add_i32 s18, s18, s52
	v_lshl_add_u64 v[216:217], v[216:217], 0, s[8:9]
	s_mov_b32 m0, s18
	ds_read_b128 v[184:187], v158 offset:49152
	ds_read_b128 v[188:191], v158 offset:50176
	ds_read_b128 v[192:195], v158 offset:51200
	ds_read_b128 v[196:199], v158 offset:52224
	ds_read_b128 v[200:203], v158 offset:53248
	ds_read_b128 v[204:207], v158 offset:54272
	ds_read_b128 v[208:211], v158 offset:55296
	ds_read_b128 v[212:215], v158 offset:56320
	global_load_lds_dwordx4 v[216:217], off
	s_add_i32 m0, s18, 0x2000
	s_add_u32 s44, s44, 0x40080
	v_lshl_add_u64 v[216:217], v[218:219], 0, s[8:9]
	s_addc_u32 s45, s45, 0
	s_add_i32 s18, s19, s52
	global_load_lds_dwordx4 v[216:217], off
	v_lshl_add_u64 v[216:217], s[44:45], 0, v[134:135]
	s_mov_b32 m0, s18
	s_nop 0
	global_load_lds_dwordx4 v[216:217], off
	v_lshl_add_u64 v[216:217], s[44:45], 0, v[130:131]
	s_add_i32 m0, s18, 0x2000
	s_nop 0
	global_load_lds_dwordx4 v[216:217], off
	v_lshl_add_u64 v[216:217], v[220:221], 0, s[8:9]
	s_mov_b32 m0, s60
	s_nop 0
	global_load_lds_dwordx4 v[216:217], off
	v_lshl_add_u64 v[216:217], v[224:225], 0, s[8:9]
	s_mov_b32 m0, s61
	s_nop 0
	global_load_lds_dwordx4 v[216:217], off
	s_waitcnt vmcnt(8)
	s_waitcnt lgkmcnt(0)
	s_barrier
	s_waitcnt lgkmcnt(0)
	v_mfma_f32_16x16x32_bf16 v[62:65], v[146:149], v[184:187], v[62:65]
	v_mfma_f32_16x16x32_bf16 v[58:61], v[160:163], v[184:187], v[58:61]
	v_mfma_f32_16x16x32_bf16 v[50:53], v[146:149], v[192:195], v[50:53]
	v_mfma_f32_16x16x32_bf16 v[42:45], v[160:163], v[192:195], v[42:45]
	v_mfma_f32_16x16x32_bf16 v[34:37], v[146:149], v[200:203], v[34:37]
	v_mfma_f32_16x16x32_bf16 v[26:29], v[160:163], v[200:203], v[26:29]
	v_mfma_f32_16x16x32_bf16 v[18:21], v[146:149], v[208:211], v[18:21]
	v_mfma_f32_16x16x32_bf16 v[10:13], v[160:163], v[208:211], v[10:13]
	v_mfma_f32_16x16x32_bf16 v[62:65], v[150:153], v[188:191], v[62:65]
	v_mfma_f32_16x16x32_bf16 v[58:61], v[164:167], v[188:191], v[58:61]
	v_mfma_f32_16x16x32_bf16 v[50:53], v[150:153], v[196:199], v[50:53]
	v_mfma_f32_16x16x32_bf16 v[42:45], v[164:167], v[196:199], v[42:45]
	v_mfma_f32_16x16x32_bf16 v[34:37], v[150:153], v[204:207], v[34:37]
	v_mfma_f32_16x16x32_bf16 v[26:29], v[164:167], v[204:207], v[26:29]
	v_mfma_f32_16x16x32_bf16 v[18:21], v[150:153], v[212:215], v[18:21]
	v_mfma_f32_16x16x32_bf16 v[10:13], v[164:167], v[212:215], v[10:13]
	v_mfma_f32_16x16x32_bf16 v[54:57], v[168:171], v[184:187], v[54:57]
	v_mfma_f32_16x16x32_bf16 v[46:49], v[176:179], v[184:187], v[46:49]
	v_mfma_f32_16x16x32_bf16 v[38:41], v[168:171], v[192:195], v[38:41]
	v_mfma_f32_16x16x32_bf16 v[30:33], v[176:179], v[192:195], v[30:33]
	v_mfma_f32_16x16x32_bf16 v[22:25], v[168:171], v[200:203], v[22:25]
	v_mfma_f32_16x16x32_bf16 v[14:17], v[176:179], v[200:203], v[14:17]
	v_mfma_f32_16x16x32_bf16 v[6:9], v[168:171], v[208:211], v[6:9]
	v_mfma_f32_16x16x32_bf16 v[2:5], v[176:179], v[208:211], v[2:5]
	v_mfma_f32_16x16x32_bf16 v[54:57], v[172:175], v[188:191], v[54:57]
	v_mfma_f32_16x16x32_bf16 v[46:49], v[180:183], v[188:191], v[46:49]
	v_mfma_f32_16x16x32_bf16 v[38:41], v[172:175], v[196:199], v[38:41]
	v_mfma_f32_16x16x32_bf16 v[30:33], v[180:183], v[196:199], v[30:33]
	v_mfma_f32_16x16x32_bf16 v[22:25], v[172:175], v[204:207], v[22:25]
	v_mfma_f32_16x16x32_bf16 v[14:17], v[180:183], v[204:207], v[14:17]
	v_mfma_f32_16x16x32_bf16 v[6:9], v[172:175], v[212:215], v[6:9]
	v_mfma_f32_16x16x32_bf16 v[2:5], v[180:183], v[212:215], v[2:5]
	s_barrier
	s_add_i32 s72, s72, 2
	s_add_u32 s42, s42, 0x100
	s_addc_u32 s43, s43, 0
	s_add_u32 s70, s70, 0x100
	s_addc_u32 s71, s71, 0
	s_cmp_gt_u32 s72, 13
	s_cbranch_scc0 .LBB0_868
	s_and_b64 vcc, exec, s[14:15]
	s_cbranch_vccz .LBB0_871
	s_barrier

; #define PG8_STAGE(bufoff, gbase, voff) do { _Pragma("unroll") for (int _i = 0; _i < 2; ++_i) \
;         __builtin_amdgcn_global_load_lds((const unsigned*)((const char*)(gbase) + (voff)[_i]), (PG8_LAS unsigned*)(lds + (bufoff) + ldsw + _i * 8192), 16, 0, 0); } while (0)
; #define PG8_WAIT_V(n) asm volatile("s_waitcnt vmcnt(" #n ")" ::: "memory")
; #define PG8_BAR __builtin_amdgcn_s_barrier()
; template <class Epi, class Sched, bool ALIGN_EPI = false, bool SP2 = false>
; __device__ __forceinline__ void gemm_phase(PG8_LAS unsigned char* lds, const Gemm g, const Sched& S, const Epi& E) {
;     ...
;         PG8_WAIT_V(2); PG8_BAR;
;         PG8_STAGE(PG8_SB(1, 0), cB + kstep, voffB); PG8_STAGE(PG8_SA(1, 0), cA + kstep, voffA); PG8_STAGE(PG8_SB(1, 1), cB + hB + kstep, voffB);
;         PG8_WAIT_V(6); PG8_BAR;
;     __device__ __forceinline__ void operator()(AccRef acc, const pg8::Unit& u, int wr, int wc, int fr, int fq) const {
;         const int row0 = u.pm * 256 + wr * 64 + fr, c0 = u.pn * 256 + wc * 32 + 8 * fq;
; #pragma unroll
;         for (int ai = 0; ai < 2; ++ai) {
;             u32x4 gv[4][2], tv[4][2];
; #pragma unroll
;             for (int m = 0; m < 4; ++m) { const int r = row0 + ai * 128 + m * 16;
; #pragma unroll
;                 for (int bj = 0; bj < 2; ++bj) { const int c = c0 + bj * 128;
;                     gv[m][bj] = *(const u32x4*)(sg + (size_t)r * 4096 + (SECOND ? 0 : 2048) + c);
;                     if (SECOND) tv[m][bj] = *(const u32x4*)(tmp + (size_t)r * 2048 + c); } }
.LBB0_878:
	s_add_u32 s8, s6, 0xd800000
	s_addc_u32 s9, s7, 0
	s_add_u32 s14, s6, 0x9800000
	s_addc_u32 s15, s7, 0
	s_lshl_b32 s6, s16, 5
	s_mov_b64 s[16:17], 0x80
	s_and_b32 s19, s6, 0x60
	s_add_i32 m0, s43, 0x18000
	v_lshl_add_u64 v[8:9], v[8:9], 0, s[16:17]
	s_lshl_b32 s18, s22, 13
	s_lshl_b32 s23, s19, 7
	s_waitcnt vmcnt(2)
	s_barrier
	global_load_lds_dwordx4 v[8:9], off
	v_lshl_add_u64 v[6:7], v[6:7], 0, s[16:17]
	s_add_i32 m0, s43, 0x1a000
	s_add_i32 s63, s43, 0x8000
	s_add_i32 s64, s43, 0xa000
	global_load_lds_dwordx4 v[6:7], off
	v_lshl_add_u64 v[2:3], v[2:3], 0, s[16:17]
	s_mov_b32 m0, s63
	s_add_u32 s6, s46, 0x80080
	global_load_lds_dwordx4 v[2:3], off
	v_lshl_add_u64 v[2:3], v[4:5], 0, s[16:17]
	s_mov_b32 m0, s64
	s_addc_u32 s7, s47, 0
	global_load_lds_dwordx4 v[2:3], off
	s_add_i32 m0, s43, 0x1c000
	v_lshl_add_u64 v[2:3], s[6:7], 0, v[150:151]
	global_load_lds_dwordx4 v[2:3], off
	v_lshl_add_u64 v[2:3], s[6:7], 0, v[146:147]
	s_add_i32 m0, s43, 0x1e000
	s_cmpk_lt_u32 s21, 0x100
	global_load_lds_dwordx4 v[2:3], off
	v_lshrrev_b32_e32 v3, 1, v11
	v_and_b32_e32 v3, 24, v3
	v_and_b32_e32 v2, 15, v11
	v_lshlrev_b32_e32 v4, 1, v3
	v_lshl_or_b32 v1, s22, 6, v2
	v_lshl_or_b32 v2, v2, 6, v4
	v_lshlrev_b32_e32 v4, 2, v11
	v_and_b32_e32 v4, 32, v4
	v_bitop3_b32 v5, v2, s18, v4 bitop3:0xde
	v_bitop3_b32 v170, v2, s23, v4 bitop3:0xde
	v_lshlrev_b32_e32 v2, 15, v15
	v_and_b32_e32 v2, 0xffff0000, v2
	v_or_b32_e32 v171, s19, v3
	v_lshl_add_u32 v2, v14, 12, v2
	v_and_b32_e32 v3, 1, v15
	v_lshl_or_b32 v2, v3, 6, v2
	v_lshl_add_u32 v154, v16, 1, v2
	v_lshlrev_b32_e32 v2, 15, v10
	v_and_b32_e32 v2, 0xffff0000, v2
	s_waitcnt vmcnt(6)
	v_lshl_add_u32 v2, v12, 12, v2
	v_and_b32_e32 v3, 1, v10
	s_sext_i32_i8 s69, s20
	s_cselect_b64 s[20:21], -1, 0
	v_lshl_or_b32 v2, v3, 6, v2
	s_add_i32 s66, 0, 0x10000
	s_add_i32 s67, 0, 0x14000
	s_waitcnt lgkmcnt(0)
	s_ashr_i32 s65, s50, 31
	v_mov_b32_e32 v155, v151
	v_lshl_add_u32 v156, v13, 1, v2
	v_mov_b32_e32 v157, v151
	v_mov_b64_e32 v[158:159], 0x200
	v_mov_b64_e32 v[160:161], 0x1ff
	v_add_u32_e32 v172, s66, v170
	v_add_u32_e32 v173, s67, v170
	v_add_u32_e32 v174, 0, v5
	s_barrier
	v_readfirstlane_b32 s99, v0
	s_nop 3
	s_lshr_b32 s99, s99, 8
	s_cmp_eq_u32 s99, 0
	s_cbranch_scc1 .Lprio_skip_4
	s_setprio 1

; #define PG8_STAGE(bufoff, gbase, voff) do { _Pragma("unroll") for (int _i = 0; _i < 2; ++_i) \
;         __builtin_amdgcn_global_load_lds((const unsigned*)((const char*)(gbase) + (voff)[_i]), (PG8_LAS unsigned*)(lds + (bufoff) + ldsw + _i * 8192), 16, 0, 0); } while (0)
; #define PG8_LDA(dst, b, h) do { _Pragma("unroll") for (int m = 0; m < 4; ++m) _Pragma("unroll") for (int k = 0; k < 2; ++k) dst[m][k] = *(const PG8_LAS bf16x8*)(lds + PG8_SA(b, h) + aoff + m * 2048 + k * 1024); } while (0)
; #define PG8_LDB(dst, b, h) do { _Pragma("unroll") for (int n = 0; n < 2; ++n) _Pragma("unroll") for (int k = 0; k < 2; ++k) dst[n][k] = *(const PG8_LAS bf16x8*)(lds + PG8_SB(b, h) + boff + n * 2048 + k * 1024); } while (0)
; #define PG8_MMA(ai, bj, At, Bt) do { __builtin_amdgcn_s_setprio(1); _Pragma("unroll") for (int m = 0; m < 4; ++m) _Pragma("unroll") for (int n = 0; n < 2; ++n) _Pragma("unroll") for (int k = 0; k < 2; ++k) \
;         acc[ai][bj][m][n] = __builtin_amdgcn_mfma_f32_16x16x32_bf16(Bt[n][k], At[m][k], acc[ai][bj][m][n], 0, 0, 0); __builtin_amdgcn_s_setprio(0); } while (0)
; #define PG8_WAIT_V(n) asm volatile("s_waitcnt vmcnt(" #n ")" ::: "memory")
; #define PG8_WAIT_L(n) asm volatile("s_waitcnt lgkmcnt(" #n ")" ::: "memory")
; #define PG8_BAR __builtin_amdgcn_s_barrier()
; #define PG8_SCHED __builtin_amdgcn_sched_barrier(0)
; template <class Epi, class Sched, bool ALIGN_EPI = false, bool SP2 = false>
; __device__ __forceinline__ void gemm_phase(PG8_LAS unsigned char* lds, const Gemm g, const Sched& S, const Epi& E) {
;     ...
;             PG8_LDB(B0, 0, 0); PG8_LDB(B1, 0, 1); PG8_SCHED; PG8_LDA(At, 0, 0); PG8_STAGE(PG8_SA(1, 1), a1 + hA, voffA);
;             PG8_WAIT_V(8); PG8_WAIT_L(0); PG8_BAR; PG8_MMA(0, 0, At, B0); PG8_MMA(0, 1, At, B1); PG8_BAR; PG8_SCHED;
;             PG8_LDA(At, 0, 1); PG8_STAGE(PG8_SB(0, 0), b2, voffB); PG8_STAGE(PG8_SB(0, 1), b2 + hB, voffB); PG8_STAGE(PG8_SA(0, 0), a2, voffA);
;             PG8_WAIT_V(8); PG8_WAIT_L(0); PG8_BAR; PG8_MMA(1, 0, At, B0); PG8_MMA(1, 1, At, B1); PG8_BAR; PG8_SCHED;
.LBB0_888:
	ds_read_b128 v[130:133], v172
	ds_read_b128 v[134:137], v172 offset:1024
	ds_read_b128 v[138:141], v172 offset:2048
	ds_read_b128 v[142:145], v172 offset:3072
	ds_read_b128 v[162:165], v173
	ds_read_b128 v[166:169], v173 offset:1024
	ds_read_b128 v[176:179], v173 offset:2048
	ds_read_b128 v[180:183], v173 offset:3072
	s_add_u32 s18, s44, 0xfff80080
	s_addc_u32 s19, s45, -1
	s_cmp_eq_u32 s74, 28
	s_cselect_b32 s49, s25, s19
	s_cselect_b32 s48, s70, s18
	s_cselect_b32 s47, s23, s73
	s_cselect_b32 s46, s71, s72
	v_lshl_add_u64 v[216:217], s[44:45], 0, v[154:155]
	s_add_i32 m0, s43, 0xc000
	ds_read_b128 v[184:187], v174
	ds_read_b128 v[188:191], v174 offset:1024
	ds_read_b128 v[192:195], v174 offset:2048
	ds_read_b128 v[196:199], v174 offset:3072
	ds_read_b128 v[200:203], v174 offset:4096
	ds_read_b128 v[204:207], v174 offset:5120
	ds_read_b128 v[208:211], v174 offset:6144
	ds_read_b128 v[212:215], v174 offset:7168
	global_load_lds_dwordx4 v[216:217], off
	v_lshl_add_u64 v[216:217], s[44:45], 0, v[156:157]
	s_add_i32 m0, s43, 0xe000
	s_nop 0
	global_load_lds_dwordx4 v[216:217], off
	s_waitcnt vmcnt(8)
	s_waitcnt lgkmcnt(0)
	s_barrier
	s_waitcnt lgkmcnt(0)
	v_mfma_f32_16x16x32_bf16 v[126:129], v[130:133], v[184:187], v[126:129]
	v_mfma_f32_16x16x32_bf16 v[122:125], v[138:141], v[184:187], v[122:125]
	v_mfma_f32_16x16x32_bf16 v[110:113], v[130:133], v[192:195], v[110:113]
	v_mfma_f32_16x16x32_bf16 v[106:109], v[138:141], v[192:195], v[106:109]
	v_mfma_f32_16x16x32_bf16 v[94:97], v[130:133], v[200:203], v[94:97]
	v_mfma_f32_16x16x32_bf16 v[90:93], v[138:141], v[200:203], v[90:93]
	v_mfma_f32_16x16x32_bf16 v[78:81], v[130:133], v[208:211], v[78:81]
	v_mfma_f32_16x16x32_bf16 v[74:77], v[138:141], v[208:211], v[74:77]
	v_mfma_f32_16x16x32_bf16 v[126:129], v[134:137], v[188:191], v[126:129]
	v_mfma_f32_16x16x32_bf16 v[122:125], v[142:145], v[188:191], v[122:125]
	v_mfma_f32_16x16x32_bf16 v[110:113], v[134:137], v[196:199], v[110:113]
	v_mfma_f32_16x16x32_bf16 v[106:109], v[142:145], v[196:199], v[106:109]
	v_mfma_f32_16x16x32_bf16 v[94:97], v[134:137], v[204:207], v[94:97]
	v_mfma_f32_16x16x32_bf16 v[90:93], v[142:145], v[204:207], v[90:93]
	v_mfma_f32_16x16x32_bf16 v[78:81], v[134:137], v[212:215], v[78:81]
	v_mfma_f32_16x16x32_bf16 v[74:77], v[142:145], v[212:215], v[74:77]
	v_mfma_f32_16x16x32_bf16 v[118:121], v[162:165], v[184:187], v[118:121]
	v_mfma_f32_16x16x32_bf16 v[114:117], v[176:179], v[184:187], v[114:117]
	v_mfma_f32_16x16x32_bf16 v[102:105], v[162:165], v[192:195], v[102:105]
	v_mfma_f32_16x16x32_bf16 v[98:101], v[176:179], v[192:195], v[98:101]
	v_mfma_f32_16x16x32_bf16 v[86:89], v[162:165], v[200:203], v[86:89]
	v_mfma_f32_16x16x32_bf16 v[82:85], v[176:179], v[200:203], v[82:85]
	v_mfma_f32_16x16x32_bf16 v[70:73], v[162:165], v[208:211], v[70:73]
	v_mfma_f32_16x16x32_bf16 v[66:69], v[176:179], v[208:211], v[66:69]
	v_mfma_f32_16x16x32_bf16 v[118:121], v[166:169], v[188:191], v[118:121]
	v_mfma_f32_16x16x32_bf16 v[114:117], v[180:183], v[188:191], v[114:117]
	v_mfma_f32_16x16x32_bf16 v[102:105], v[166:169], v[196:199], v[102:105]
	v_mfma_f32_16x16x32_bf16 v[98:101], v[180:183], v[196:199], v[98:101]
	v_mfma_f32_16x16x32_bf16 v[86:89], v[166:169], v[204:207], v[86:89]
	v_mfma_f32_16x16x32_bf16 v[82:85], v[180:183], v[204:207], v[82:85]
	v_mfma_f32_16x16x32_bf16 v[70:73], v[166:169], v[212:215], v[70:73]
	v_mfma_f32_16x16x32_bf16 v[66:69], v[180:183], v[212:215], v[66:69]
	s_barrier
	s_add_i32 s18, s66, s58
	v_lshl_add_u64 v[216:217], s[46:47], 0, v[150:151]
	s_mov_b32 m0, s18
	ds_read_b128 v[184:187], v174 offset:16384
	ds_read_b128 v[188:191], v174 offset:17408
	ds_read_b128 v[192:195], v174 offset:18432
	ds_read_b128 v[196:199], v174 offset:19456
	ds_read_b128 v[200:203], v174 offset:20480
	ds_read_b128 v[204:207], v174 offset:21504
	ds_read_b128 v[208:211], v174 offset:22528
	ds_read_b128 v[212:215], v174 offset:23552
	global_load_lds_dwordx4 v[216:217], off
	s_add_i32 m0, s18, 0x2000
	s_add_u32 s76, s46, 0x80000
	v_lshl_add_u64 v[218:219], s[46:47], 0, v[146:147]
	s_addc_u32 s77, s47, 0
	s_add_i32 s18, s67, s58
	global_load_lds_dwordx4 v[218:219], off
	v_lshl_add_u64 v[220:221], s[76:77], 0, v[150:151]
	s_mov_b32 m0, s18
	v_lshl_add_u64 v[224:225], s[48:49], 0, v[148:149]
	global_load_lds_dwordx4 v[220:221], off
	v_lshl_add_u64 v[220:221], s[76:77], 0, v[146:147]
	s_add_i32 m0, s18, 0x2000
	s_nop 0
	global_load_lds_dwordx4 v[220:221], off
	v_lshl_add_u64 v[220:221], s[48:49], 0, v[152:153]
	s_mov_b32 m0, s43
	s_nop 0
	global_load_lds_dwordx4 v[220:221], off
	s_mov_b32 m0, s59
	s_nop 0
	global_load_lds_dwordx4 v[224:225], off
	s_waitcnt vmcnt(8)
	s_waitcnt lgkmcnt(0)
	s_barrier
; #define PG8_STAGE(bufoff, gbase, voff) do { _Pragma("unroll") for (int _i = 0; _i < 2; ++_i) \
;         __builtin_amdgcn_global_load_lds((const unsigned*)((const char*)(gbase) + (voff)[_i]), (PG8_LAS unsigned*)(lds + (bufoff) + ldsw + _i * 8192), 16, 0, 0); } while (0)
; #define PG8_LDA(dst, b, h) do { _Pragma("unroll") for (int m = 0; m < 4; ++m) _Pragma("unroll") for (int k = 0; k < 2; ++k) dst[m][k] = *(const PG8_LAS bf16x8*)(lds + PG8_SA(b, h) + aoff + m * 2048 + k * 1024); } while (0)
; #define PG8_LDB(dst, b, h) do { _Pragma("unroll") for (int n = 0; n < 2; ++n) _Pragma("unroll") for (int k = 0; k < 2; ++k) dst[n][k] = *(const PG8_LAS bf16x8*)(lds + PG8_SB(b, h) + boff + n * 2048 + k * 1024); } while (0)
; #define PG8_MMA(ai, bj, At, Bt) do { __builtin_amdgcn_s_setprio(1); _Pragma("unroll") for (int m = 0; m < 4; ++m) _Pragma("unroll") for (int n = 0; n < 2; ++n) _Pragma("unroll") for (int k = 0; k < 2; ++k) \
;         acc[ai][bj][m][n] = __builtin_amdgcn_mfma_f32_16x16x32_bf16(Bt[n][k], At[m][k], acc[ai][bj][m][n], 0, 0, 0); __builtin_amdgcn_s_setprio(0); } while (0)
; #define PG8_WAIT_V(n) asm volatile("s_waitcnt vmcnt(" #n ")" ::: "memory")
; #define PG8_WAIT_L(n) asm volatile("s_waitcnt lgkmcnt(" #n ")" ::: "memory")
; #define PG8_BAR __builtin_amdgcn_s_barrier()
; #define PG8_SCHED __builtin_amdgcn_sched_barrier(0)
; template <class Epi, class Sched, bool ALIGN_EPI = false, bool SP2 = false>
; __device__ __forceinline__ void gemm_phase(PG8_LAS unsigned char* lds, const Gemm g, const Sched& S, const Epi& E) {
;     ...
;             PG8_WAIT_V(8); PG8_WAIT_L(0); PG8_BAR; PG8_MMA(1, 0, At, B0); PG8_MMA(1, 1, At, B1); PG8_BAR; PG8_SCHED;
;             PG8_LDB(B0, 1, 0); PG8_LDB(B1, 1, 1); PG8_SCHED; PG8_LDA(At, 1, 0); PG8_STAGE(PG8_SA(0, 1), a2 + hA, voffA);
;             PG8_WAIT_V(8); PG8_WAIT_L(0); PG8_BAR; PG8_MMA(0, 0, At, B0); PG8_MMA(0, 1, At, B1); PG8_BAR; PG8_SCHED;
	s_waitcnt lgkmcnt(0)
	v_mfma_f32_16x16x32_bf16 v[62:65], v[130:133], v[184:187], v[62:65]
	v_mfma_f32_16x16x32_bf16 v[58:61], v[138:141], v[184:187], v[58:61]
	v_mfma_f32_16x16x32_bf16 v[46:49], v[130:133], v[192:195], v[46:49]
	v_mfma_f32_16x16x32_bf16 v[42:45], v[138:141], v[192:195], v[42:45]
	v_mfma_f32_16x16x32_bf16 v[30:33], v[130:133], v[200:203], v[30:33]
	v_mfma_f32_16x16x32_bf16 v[26:29], v[138:141], v[200:203], v[26:29]
	v_mfma_f32_16x16x32_bf16 v[14:17], v[130:133], v[208:211], v[14:17]
	v_mfma_f32_16x16x32_bf16 v[10:13], v[138:141], v[208:211], v[10:13]
	v_mfma_f32_16x16x32_bf16 v[62:65], v[134:137], v[188:191], v[62:65]
	v_mfma_f32_16x16x32_bf16 v[58:61], v[142:145], v[188:191], v[58:61]
	v_mfma_f32_16x16x32_bf16 v[46:49], v[134:137], v[196:199], v[46:49]
	v_mfma_f32_16x16x32_bf16 v[42:45], v[142:145], v[196:199], v[42:45]
	v_mfma_f32_16x16x32_bf16 v[30:33], v[134:137], v[204:207], v[30:33]
	v_mfma_f32_16x16x32_bf16 v[26:29], v[142:145], v[204:207], v[26:29]
	v_mfma_f32_16x16x32_bf16 v[14:17], v[134:137], v[212:215], v[14:17]
	v_mfma_f32_16x16x32_bf16 v[10:13], v[142:145], v[212:215], v[10:13]
	v_mfma_f32_16x16x32_bf16 v[54:57], v[162:165], v[184:187], v[54:57]
	v_mfma_f32_16x16x32_bf16 v[50:53], v[176:179], v[184:187], v[50:53]
	v_mfma_f32_16x16x32_bf16 v[38:41], v[162:165], v[192:195], v[38:41]
	v_mfma_f32_16x16x32_bf16 v[34:37], v[176:179], v[192:195], v[34:37]
	v_mfma_f32_16x16x32_bf16 v[22:25], v[162:165], v[200:203], v[22:25]
	v_mfma_f32_16x16x32_bf16 v[18:21], v[176:179], v[200:203], v[18:21]
	v_mfma_f32_16x16x32_bf16 v[6:9], v[162:165], v[208:211], v[6:9]
	v_mfma_f32_16x16x32_bf16 v[2:5], v[176:179], v[208:211], v[2:5]
	v_mfma_f32_16x16x32_bf16 v[54:57], v[166:169], v[188:191], v[54:57]
	v_mfma_f32_16x16x32_bf16 v[50:53], v[180:183], v[188:191], v[50:53]
	v_mfma_f32_16x16x32_bf16 v[38:41], v[166:169], v[196:199], v[38:41]
	v_mfma_f32_16x16x32_bf16 v[34:37], v[180:183], v[196:199], v[34:37]
	v_mfma_f32_16x16x32_bf16 v[22:25], v[166:169], v[204:207], v[22:25]
	v_mfma_f32_16x16x32_bf16 v[18:21], v[180:183], v[204:207], v[18:21]
	v_mfma_f32_16x16x32_bf16 v[6:9], v[166:169], v[212:215], v[6:9]
	v_mfma_f32_16x16x32_bf16 v[2:5], v[180:183], v[212:215], v[2:5]
	s_barrier
	s_add_i32 s18, 0, 0x18000
	s_add_i32 s19, 0, 0x1c000
	v_add_u32_e32 v142, s18, v170
	v_add_u32_e32 v175, s19, v170
	ds_read_b128 v[130:133], v142
	ds_read_b128 v[134:137], v142 offset:1024
	ds_read_b128 v[138:141], v142 offset:2048
	ds_read_b128 v[142:145], v142 offset:3072
	ds_read_b128 v[162:165], v175
	ds_read_b128 v[166:169], v175 offset:1024
	ds_read_b128 v[176:179], v175 offset:2048
	ds_read_b128 v[180:183], v175 offset:3072
	s_add_u32 s48, s48, 0x80000
	s_addc_u32 s49, s49, 0
	s_mov_b32 m0, s60
	v_lshl_add_u64 v[226:227], s[48:49], 0, v[152:153]
	ds_read_b128 v[184:187], v174 offset:32768
	ds_read_b128 v[188:191], v174 offset:33792
	ds_read_b128 v[192:195], v174 offset:34816
	ds_read_b128 v[196:199], v174 offset:35840
	ds_read_b128 v[200:203], v174 offset:36864
	ds_read_b128 v[204:207], v174 offset:37888
	ds_read_b128 v[208:211], v174 offset:38912
	ds_read_b128 v[212:215], v174 offset:39936
	global_load_lds_dwordx4 v[226:227], off
	v_lshl_add_u64 v[226:227], s[48:49], 0, v[148:149]
	s_mov_b32 m0, s61
	s_nop 0
	global_load_lds_dwordx4 v[226:227], off
	s_waitcnt vmcnt(8)
	s_waitcnt lgkmcnt(0)
	s_barrier
	s_waitcnt lgkmcnt(0)
	v_mfma_f32_16x16x32_bf16 v[126:129], v[130:133], v[184:187], v[126:129]
	v_mfma_f32_16x16x32_bf16 v[122:125], v[138:141], v[184:187], v[122:125]
	v_mfma_f32_16x16x32_bf16 v[110:113], v[130:133], v[192:195], v[110:113]
	v_mfma_f32_16x16x32_bf16 v[106:109], v[138:141], v[192:195], v[106:109]
	v_mfma_f32_16x16x32_bf16 v[94:97], v[130:133], v[200:203], v[94:97]
	v_mfma_f32_16x16x32_bf16 v[90:93], v[138:141], v[200:203], v[90:93]
	v_mfma_f32_16x16x32_bf16 v[78:81], v[130:133], v[208:211], v[78:81]
	v_mfma_f32_16x16x32_bf16 v[74:77], v[138:141], v[208:211], v[74:77]
	v_mfma_f32_16x16x32_bf16 v[126:129], v[134:137], v[188:191], v[126:129]
	v_mfma_f32_16x16x32_bf16 v[122:125], v[142:145], v[188:191], v[122:125]
	v_mfma_f32_16x16x32_bf16 v[110:113], v[134:137], v[196:199], v[110:113]
	v_mfma_f32_16x16x32_bf16 v[106:109], v[142:145], v[196:199], v[106:109]
	v_mfma_f32_16x16x32_bf16 v[94:97], v[134:137], v[204:207], v[94:97]
	v_mfma_f32_16x16x32_bf16 v[90:93], v[142:145], v[204:207], v[90:93]
	v_mfma_f32_16x16x32_bf16 v[78:81], v[134:137], v[212:215], v[78:81]
	v_mfma_f32_16x16x32_bf16 v[74:77], v[142:145], v[212:215], v[74:77]
	v_mfma_f32_16x16x32_bf16 v[118:121], v[162:165], v[184:187], v[118:121]
	v_mfma_f32_16x16x32_bf16 v[114:117], v[176:179], v[184:187], v[114:117]
	v_mfma_f32_16x16x32_bf16 v[102:105], v[162:165], v[192:195], v[102:105]
	v_mfma_f32_16x16x32_bf16 v[98:101], v[176:179], v[192:195], v[98:101]
	v_mfma_f32_16x16x32_bf16 v[86:89], v[162:165], v[200:203], v[86:89]
	v_mfma_f32_16x16x32_bf16 v[82:85], v[176:179], v[200:203], v[82:85]
	v_mfma_f32_16x16x32_bf16 v[70:73], v[162:165], v[208:211], v[70:73]
	v_mfma_f32_16x16x32_bf16 v[66:69], v[176:179], v[208:211], v[66:69]
	v_mfma_f32_16x16x32_bf16 v[118:121], v[166:169], v[188:191], v[118:121]
	v_mfma_f32_16x16x32_bf16 v[114:117], v[180:183], v[188:191], v[114:117]
	v_mfma_f32_16x16x32_bf16 v[102:105], v[166:169], v[196:199], v[102:105]
	v_mfma_f32_16x16x32_bf16 v[98:101], v[180:183], v[196:199], v[98:101]
	v_mfma_f32_16x16x32_bf16 v[86:89], v[166:169], v[204:207], v[86:89]
	v_mfma_f32_16x16x32_bf16 v[82:85], v[180:183], v[204:207], v[82:85]
	v_mfma_f32_16x16x32_bf16 v[70:73], v[166:169], v[212:215], v[70:73]
	v_mfma_f32_16x16x32_bf16 v[66:69], v[180:183], v[212:215], v[66:69]
	s_barrier
; #define PG8_STAGE(bufoff, gbase, voff) do { _Pragma("unroll") for (int _i = 0; _i < 2; ++_i) \
;         __builtin_amdgcn_global_load_lds((const unsigned*)((const char*)(gbase) + (voff)[_i]), (PG8_LAS unsigned*)(lds + (bufoff) + ldsw + _i * 8192), 16, 0, 0); } while (0)
; #define PG8_LDA(dst, b, h) do { _Pragma("unroll") for (int m = 0; m < 4; ++m) _Pragma("unroll") for (int k = 0; k < 2; ++k) dst[m][k] = *(const PG8_LAS bf16x8*)(lds + PG8_SA(b, h) + aoff + m * 2048 + k * 1024); } while (0)
; #define PG8_MMA(ai, bj, At, Bt) do { __builtin_amdgcn_s_setprio(1); _Pragma("unroll") for (int m = 0; m < 4; ++m) _Pragma("unroll") for (int n = 0; n < 2; ++n) _Pragma("unroll") for (int k = 0; k < 2; ++k) \
;         acc[ai][bj][m][n] = __builtin_amdgcn_mfma_f32_16x16x32_bf16(Bt[n][k], At[m][k], acc[ai][bj][m][n], 0, 0, 0); __builtin_amdgcn_s_setprio(0); } while (0)
; #define PG8_WAIT_V(n) asm volatile("s_waitcnt vmcnt(" #n ")" ::: "memory")
; #define PG8_WAIT_L(n) asm volatile("s_waitcnt lgkmcnt(" #n ")" ::: "memory")
; #define PG8_BAR __builtin_amdgcn_s_barrier()
; #define PG8_SCHED __builtin_amdgcn_sched_barrier(0)
; template <class Epi, class Sched, bool ALIGN_EPI = false, bool SP2 = false>
; __device__ __forceinline__ void gemm_phase(PG8_LAS unsigned char* lds, const Gemm g, const Sched& S, const Epi& E) {
;     ...
;             PG8_WAIT_V(8); PG8_WAIT_L(0); PG8_BAR; PG8_MMA(0, 0, At, B0); PG8_MMA(0, 1, At, B1); PG8_BAR; PG8_SCHED;
;             PG8_LDA(At, 1, 1); PG8_STAGE(PG8_SB(1, 0), b3, voffB); PG8_STAGE(PG8_SB(1, 1), b3 + hB, voffB); PG8_STAGE(PG8_SA(1, 0), a3, voffA);
;             PG8_WAIT_V(8); PG8_WAIT_L(0); PG8_BAR; PG8_MMA(1, 0, At, B0); PG8_MMA(1, 1, At, B1); PG8_BAR; PG8_SCHED;
;     ...
;         if constexpr (ALIGN_EPI) { if (wr == 0) PG8_BAR; }
	s_add_i32 s18, s18, s58
	v_lshl_add_u64 v[216:217], v[216:217], 0, s[16:17]
	s_mov_b32 m0, s18
	ds_read_b128 v[184:187], v174 offset:49152
	ds_read_b128 v[188:191], v174 offset:50176
	ds_read_b128 v[192:195], v174 offset:51200
	ds_read_b128 v[196:199], v174 offset:52224
	ds_read_b128 v[200:203], v174 offset:53248
	ds_read_b128 v[204:207], v174 offset:54272
	ds_read_b128 v[208:211], v174 offset:55296
	ds_read_b128 v[212:215], v174 offset:56320
	global_load_lds_dwordx4 v[216:217], off
	s_add_i32 m0, s18, 0x2000
	s_add_u32 s46, s46, 0x80080
	v_lshl_add_u64 v[216:217], v[218:219], 0, s[16:17]
	s_addc_u32 s47, s47, 0
	s_add_i32 s18, s19, s58
	global_load_lds_dwordx4 v[216:217], off
	v_lshl_add_u64 v[216:217], s[46:47], 0, v[150:151]
	s_mov_b32 m0, s18
	s_nop 0
	global_load_lds_dwordx4 v[216:217], off
	v_lshl_add_u64 v[216:217], s[46:47], 0, v[146:147]
	s_add_i32 m0, s18, 0x2000
	s_nop 0
	global_load_lds_dwordx4 v[216:217], off
	v_lshl_add_u64 v[216:217], v[220:221], 0, s[16:17]
	s_mov_b32 m0, s63
	s_nop 0
	global_load_lds_dwordx4 v[216:217], off
	v_lshl_add_u64 v[216:217], v[224:225], 0, s[16:17]
	s_mov_b32 m0, s64
	s_nop 0
	global_load_lds_dwordx4 v[216:217], off
	s_waitcnt vmcnt(8)
	s_waitcnt lgkmcnt(0)
	s_barrier
	s_waitcnt lgkmcnt(0)
	v_mfma_f32_16x16x32_bf16 v[62:65], v[130:133], v[184:187], v[62:65]
	v_mfma_f32_16x16x32_bf16 v[58:61], v[138:141], v[184:187], v[58:61]
	v_mfma_f32_16x16x32_bf16 v[46:49], v[130:133], v[192:195], v[46:49]
	v_mfma_f32_16x16x32_bf16 v[42:45], v[138:141], v[192:195], v[42:45]
	v_mfma_f32_16x16x32_bf16 v[30:33], v[130:133], v[200:203], v[30:33]
	v_mfma_f32_16x16x32_bf16 v[26:29], v[138:141], v[200:203], v[26:29]
	v_mfma_f32_16x16x32_bf16 v[14:17], v[130:133], v[208:211], v[14:17]
	v_mfma_f32_16x16x32_bf16 v[10:13], v[138:141], v[208:211], v[10:13]
	v_mfma_f32_16x16x32_bf16 v[62:65], v[134:137], v[188:191], v[62:65]
	v_mfma_f32_16x16x32_bf16 v[58:61], v[142:145], v[188:191], v[58:61]
	v_mfma_f32_16x16x32_bf16 v[46:49], v[134:137], v[196:199], v[46:49]
	v_mfma_f32_16x16x32_bf16 v[42:45], v[142:145], v[196:199], v[42:45]
	v_mfma_f32_16x16x32_bf16 v[30:33], v[134:137], v[204:207], v[30:33]
	v_mfma_f32_16x16x32_bf16 v[26:29], v[142:145], v[204:207], v[26:29]
	v_mfma_f32_16x16x32_bf16 v[14:17], v[134:137], v[212:215], v[14:17]
	v_mfma_f32_16x16x32_bf16 v[10:13], v[142:145], v[212:215], v[10:13]
	v_mfma_f32_16x16x32_bf16 v[54:57], v[162:165], v[184:187], v[54:57]
	v_mfma_f32_16x16x32_bf16 v[50:53], v[176:179], v[184:187], v[50:53]
	v_mfma_f32_16x16x32_bf16 v[38:41], v[162:165], v[192:195], v[38:41]
	v_mfma_f32_16x16x32_bf16 v[34:37], v[176:179], v[192:195], v[34:37]
	v_mfma_f32_16x16x32_bf16 v[22:25], v[162:165], v[200:203], v[22:25]
	v_mfma_f32_16x16x32_bf16 v[18:21], v[176:179], v[200:203], v[18:21]
	v_mfma_f32_16x16x32_bf16 v[6:9], v[162:165], v[208:211], v[6:9]
	v_mfma_f32_16x16x32_bf16 v[2:5], v[176:179], v[208:211], v[2:5]
	v_mfma_f32_16x16x32_bf16 v[54:57], v[166:169], v[188:191], v[54:57]
	v_mfma_f32_16x16x32_bf16 v[50:53], v[180:183], v[188:191], v[50:53]
	v_mfma_f32_16x16x32_bf16 v[38:41], v[166:169], v[196:199], v[38:41]
	v_mfma_f32_16x16x32_bf16 v[34:37], v[180:183], v[196:199], v[34:37]
	v_mfma_f32_16x16x32_bf16 v[22:25], v[166:169], v[204:207], v[22:25]
	v_mfma_f32_16x16x32_bf16 v[18:21], v[180:183], v[204:207], v[18:21]
	v_mfma_f32_16x16x32_bf16 v[6:9], v[166:169], v[212:215], v[6:9]
	v_mfma_f32_16x16x32_bf16 v[2:5], v[180:183], v[212:215], v[2:5]
	s_barrier
	s_add_i32 s74, s74, 2
	s_add_u32 s44, s44, 0x100
	s_addc_u32 s45, s45, 0
	s_add_u32 s72, s72, 0x100
	s_addc_u32 s73, s73, 0
	s_cmp_gt_u32 s74, 29
	s_cbranch_scc0 .LBB0_888
	s_and_b64 vcc, exec, s[20:21]
	s_cbranch_vccz .LBB0_891
	s_barrier

; #define PG8_WAIT_V(n) asm volatile("s_waitcnt vmcnt(" #n ")" ::: "memory")
; #define PG8_BAR __builtin_amdgcn_s_barrier()
; template <class Epi, class Sched, bool ALIGN_EPI = false, bool SP2 = false>
; __device__ __forceinline__ void gemm_phase(PG8_LAS unsigned char* lds, const Gemm g, const Sched& S, const Epi& E) {
;     ...
;     PG8_WAIT_V(0);
;     if constexpr (!ALIGN_EPI) { if (wr == 0) PG8_BAR; }
;     PG8_BAR;
; __device__ __forceinline__ void xcd_barrier(const XcdBarrier& b) {
;     asm volatile("s_waitcnt vmcnt(0)" ::: "memory");
;     __syncthreads();
;     if (threadIdx.x == 0) {
;         unsigned* bar = b.bar;
;         __builtin_amdgcn_s_waitcnt(0);
;         unsigned nloc = b.st[0], nx = b.st[1];
;         if (nloc == 0u) { xcd_barrier_complete(bar, b.x, nloc, nx); b.st[0] = nloc; b.st[1] = nx; }
.LBB0_895:
	s_setprio 0
	s_waitcnt vmcnt(0)
	s_waitcnt lgkmcnt(0)
	s_barrier
	s_and_saveexec_b64 s[0:1], s[86:87]
	s_xor_b64 s[0:1], exec, s[0:1]
	s_cbranch_execz .LBB0_948
	s_add_i32 s6, 0, 0x20040
	v_mov_b32_e32 v1, s6
	s_waitcnt vmcnt(0) expcnt(0) lgkmcnt(0)
	ds_read_b32 v3, v1
	s_add_i32 s6, 0, 0x20044
	v_mov_b32_e32 v1, s6
	ds_read_b32 v1, v1
	s_waitcnt lgkmcnt(1)
	v_cmp_ne_u32_e32 vcc, 0, v3
	s_cbranch_vccnz .LBB0_911
	s_load_dwordx2 s[14:15], s[84:85], 0x0
	s_load_dword s9, s[84:85], 0x8
	s_add_u32 s6, s30, 0x1000
	s_addc_u32 s7, s31, 0
	s_add_u32 s8, s30, 0x1100
	s_waitcnt lgkmcnt(0)
	s_mul_i32 s33, s15, s14
	s_mul_i32 s33, s33, s9
	s_addc_u32 s9, s31, 0
	s_add_u32 s14, s30, 0x1200
	s_addc_u32 s15, s31, 0
	s_add_u32 s16, s30, 0x1300
	s_addc_u32 s17, s31, 0
	s_mov_b32 s38, 1
	v_mov_b32_e32 v17, 0
	s_branch .LBB0_899

; #define PG8_STAGE(bufoff, gbase, voff) do { _Pragma("unroll") for (int _i = 0; _i < 2; ++_i) \
;         __builtin_amdgcn_global_load_lds((const unsigned*)((const char*)(gbase) + (voff)[_i]), (PG8_LAS unsigned*)(lds + (bufoff) + ldsw + _i * 8192), 16, 0, 0); } while (0)
; #define PG8_WAIT_V(n) asm volatile("s_waitcnt vmcnt(" #n ")" ::: "memory")
; #define PG8_BAR __builtin_amdgcn_s_barrier()
; template <class Epi, class Sched, bool ALIGN_EPI = false, bool SP2 = false>
; __device__ __forceinline__ void gemm_phase(PG8_LAS unsigned char* lds, const Gemm g, const Sched& S, const Epi& E) {
;     ...
;         PG8_WAIT_V(2); PG8_BAR;
;         PG8_STAGE(PG8_SB(1, 0), cB + kstep, voffB); PG8_STAGE(PG8_SA(1, 0), cA + kstep, voffA); PG8_STAGE(PG8_SB(1, 1), cB + hB + kstep, voffB);
;         PG8_WAIT_V(6); PG8_BAR;
;     __device__ __forceinline__ void operator()(AccRef acc, const pg8::Unit& u, int wr, int wc, int fr, int fq) const {
;         const int row0 = u.pm * 256 + wr * 64 + fr, c0 = u.pn * 256 + wc * 32 + 8 * fq;
; #pragma unroll
;         for (int ai = 0; ai < 2; ++ai) {
;             f32x4 xv[4][2][2]; u32x4 hv[4][2];
; #pragma unroll
;             for (int m = 0; m < 4; ++m) { const int r = row0 + ai * 128 + m * 16;
; #pragma unroll
;                 for (int bj = 0; bj < 2; ++bj) { const size_t off = (size_t)r * 2048 + c0 + bj * 128;
;                     if (FIRST) { xv[m][bj][0] = *(const f32x4*)(x + off); xv[m][bj][1] = *(const f32x4*)(x + off + 4); } else hv[m][bj] = *(const u32x4*)(hb + off); } }
.LBB0_953:
	s_add_u32 s16, s6, 0x15800000
	s_addc_u32 s17, s7, 0
	s_add_u32 s20, s6, 0x1e00000
	s_mov_b64 s[22:23], 0x80
	s_addc_u32 s21, s7, 0
	s_and_b32 s67, s9, 3
	s_add_i32 m0, s62, 0x18000
	v_lshl_add_u64 v[8:9], v[8:9], 0, s[22:23]
	s_lshl_b32 s9, s24, 13
	s_lshl_b32 s18, s67, 12
	s_waitcnt vmcnt(2)
	s_barrier
	global_load_lds_dwordx4 v[8:9], off
	v_lshl_add_u64 v[6:7], v[6:7], 0, s[22:23]
	s_add_i32 m0, s62, 0x1a000
	s_add_i32 s69, s62, 0x8000
	s_add_i32 s70, s62, 0xa000
	global_load_lds_dwordx4 v[6:7], off
	v_lshl_add_u64 v[2:3], v[2:3], 0, s[22:23]
	s_mov_b32 m0, s69
	s_add_u32 s6, s50, 0x80080
	global_load_lds_dwordx4 v[2:3], off
	v_lshl_add_u64 v[2:3], v[4:5], 0, s[22:23]
	s_mov_b32 m0, s70
	s_addc_u32 s7, s51, 0
	global_load_lds_dwordx4 v[2:3], off
	s_add_i32 m0, s62, 0x1c000
	v_lshl_add_u64 v[2:3], s[6:7], 0, v[180:181]
	global_load_lds_dwordx4 v[2:3], off
	v_lshl_add_u64 v[2:3], s[6:7], 0, v[184:185]
	s_add_i32 m0, s62, 0x1e000
	s_cmpk_lt_u32 s8, 0x100
	global_load_lds_dwordx4 v[2:3], off
	v_bfe_u32 v3, v10, 4, 2
	v_and_b32_e32 v2, 15, v10
	v_lshlrev_b32_e32 v5, 4, v3
	v_lshl_or_b32 v1, s24, 6, v2
	v_lshl_or_b32 v2, v2, 6, v5
	v_lshlrev_b32_e32 v5, 2, v10
	v_and_b32_e32 v5, 32, v5
	v_bitop3_b32 v6, v2, s9, v5 bitop3:0xde
	v_bitop3_b32 v206, v2, s18, v5 bitop3:0xde
	v_lshlrev_b32_e32 v2, 15, v11
	v_and_b32_e32 v2, 0xffff0000, v2
	v_lshlrev_b32_e32 v4, 3, v3
	v_cmp_eq_u32_e64 s[6:7], 0, v3
	v_lshl_add_u32 v2, v12, 12, v2
	v_and_b32_e32 v3, 1, v11
	v_lshl_or_b32 v2, v3, 6, v2
	v_lshl_add_u32 v186, v13, 1, v2
	v_lshlrev_b32_e32 v2, 15, v14
	v_and_b32_e32 v2, 0xffff0000, v2
	s_waitcnt vmcnt(6)
	v_lshl_add_u32 v2, v15, 12, v2
	v_and_b32_e32 v3, 1, v14
	s_cselect_b64 s[24:25], -1, 0
	v_lshl_or_b32 v2, v3, 6, v2
	s_add_i32 s72, 0, 0x10000
	s_add_i32 s73, 0, 0x14000
	v_lshl_or_b32 v207, s67, 5, v4
	s_waitcnt lgkmcnt(0)
	s_ashr_i32 s71, s66, 31
	v_mov_b32_e32 v187, v181
	v_lshl_add_u32 v188, v16, 1, v2
	v_mov_b32_e32 v189, v181
	v_mov_b64_e32 v[190:191], 0x200
	v_mov_b64_e32 v[192:193], 0x1ff
	v_add_u32_e32 v208, s72, v206
	v_add_u32_e32 v209, s73, v206
	v_add_u32_e32 v210, 0, v6
	v_mbcnt_hi_u32_b32 v211, -1, v222
	s_mov_b32 s74, 0
	s_barrier
	v_readfirstlane_b32 s99, v0
	s_nop 3
	s_lshr_b32 s99, s99, 8
	s_cmp_eq_u32 s99, 0
	s_cbranch_scc1 .Lprio_skip_5
	s_setprio 1

; #define PG8_STAGE(bufoff, gbase, voff) do { _Pragma("unroll") for (int _i = 0; _i < 2; ++_i) \
;         __builtin_amdgcn_global_load_lds((const unsigned*)((const char*)(gbase) + (voff)[_i]), (PG8_LAS unsigned*)(lds + (bufoff) + ldsw + _i * 8192), 16, 0, 0); } while (0)
; #define PG8_LDA(dst, b, h) do { _Pragma("unroll") for (int m = 0; m < 4; ++m) _Pragma("unroll") for (int k = 0; k < 2; ++k) dst[m][k] = *(const PG8_LAS bf16x8*)(lds + PG8_SA(b, h) + aoff + m * 2048 + k * 1024); } while (0)
; #define PG8_LDB(dst, b, h) do { _Pragma("unroll") for (int n = 0; n < 2; ++n) _Pragma("unroll") for (int k = 0; k < 2; ++k) dst[n][k] = *(const PG8_LAS bf16x8*)(lds + PG8_SB(b, h) + boff + n * 2048 + k * 1024); } while (0)
; #define PG8_MMA(ai, bj, At, Bt) do { __builtin_amdgcn_s_setprio(1); _Pragma("unroll") for (int m = 0; m < 4; ++m) _Pragma("unroll") for (int n = 0; n < 2; ++n) _Pragma("unroll") for (int k = 0; k < 2; ++k) \
;         acc[ai][bj][m][n] = __builtin_amdgcn_mfma_f32_16x16x32_bf16(Bt[n][k], At[m][k], acc[ai][bj][m][n], 0, 0, 0); __builtin_amdgcn_s_setprio(0); } while (0)
; #define PG8_WAIT_V(n) asm volatile("s_waitcnt vmcnt(" #n ")" ::: "memory")
; #define PG8_WAIT_L(n) asm volatile("s_waitcnt lgkmcnt(" #n ")" ::: "memory")
; #define PG8_BAR __builtin_amdgcn_s_barrier()
; #define PG8_SCHED __builtin_amdgcn_sched_barrier(0)
; template <class Epi, class Sched, bool ALIGN_EPI = false, bool SP2 = false>
; __device__ __forceinline__ void gemm_phase(PG8_LAS unsigned char* lds, const Gemm g, const Sched& S, const Epi& E) {
;     ...
;             PG8_LDB(B0, 0, 0); PG8_LDB(B1, 0, 1); PG8_SCHED; PG8_LDA(At, 0, 0); PG8_STAGE(PG8_SA(1, 1), a1 + hA, voffA);
;             PG8_WAIT_V(8); PG8_WAIT_L(0); PG8_BAR; PG8_MMA(0, 0, At, B0); PG8_MMA(0, 1, At, B1); PG8_BAR; PG8_SCHED;
;             PG8_LDA(At, 0, 1); PG8_STAGE(PG8_SB(0, 0), b2, voffB); PG8_STAGE(PG8_SB(0, 1), b2 + hB, voffB); PG8_STAGE(PG8_SA(0, 0), a2, voffA);
;             PG8_WAIT_V(8); PG8_WAIT_L(0); PG8_BAR; PG8_MMA(1, 0, At, B0); PG8_MMA(1, 1, At, B1); PG8_BAR; PG8_SCHED;
.LBB0_963:
	ds_read_b128 v[130:133], v208
	ds_read_b128 v[134:137], v208 offset:1024
	ds_read_b128 v[138:141], v208 offset:2048
	ds_read_b128 v[142:145], v208 offset:3072
	ds_read_b128 v[146:149], v209
	ds_read_b128 v[150:153], v209 offset:1024
	ds_read_b128 v[154:157], v209 offset:2048
	ds_read_b128 v[158:161], v209 offset:3072
	s_add_u32 s18, s48, 0xfff80080
	s_addc_u32 s19, s49, -1
	s_cmp_eq_u32 s78, 28
	s_cselect_b32 s53, s41, s19
	s_cselect_b32 s52, s47, s18
	s_cselect_b32 s51, s39, s77
	s_cselect_b32 s50, s75, s76
	v_lshl_add_u64 v[216:217], s[48:49], 0, v[186:187]
	s_add_i32 m0, s62, 0xc000
	ds_read_b128 v[162:165], v210
	ds_read_b128 v[166:169], v210 offset:1024
	ds_read_b128 v[170:173], v210 offset:2048
	ds_read_b128 v[174:177], v210 offset:3072
	ds_read_b128 v[194:197], v210 offset:4096
	ds_read_b128 v[198:201], v210 offset:5120
	ds_read_b128 v[202:205], v210 offset:6144
	ds_read_b128 v[212:215], v210 offset:7168
	global_load_lds_dwordx4 v[216:217], off
	v_lshl_add_u64 v[216:217], s[48:49], 0, v[188:189]
	s_add_i32 m0, s62, 0xe000
	s_nop 0
	global_load_lds_dwordx4 v[216:217], off
	s_waitcnt vmcnt(8)
	s_waitcnt lgkmcnt(0)
	s_barrier
	s_waitcnt lgkmcnt(0)
	v_mfma_f32_16x16x32_bf16 v[126:129], v[130:133], v[162:165], v[126:129]
	v_mfma_f32_16x16x32_bf16 v[122:125], v[138:141], v[162:165], v[122:125]
	v_mfma_f32_16x16x32_bf16 v[110:113], v[130:133], v[170:173], v[110:113]
	v_mfma_f32_16x16x32_bf16 v[106:109], v[138:141], v[170:173], v[106:109]
	v_mfma_f32_16x16x32_bf16 v[94:97], v[130:133], v[194:197], v[94:97]
	v_mfma_f32_16x16x32_bf16 v[90:93], v[138:141], v[194:197], v[90:93]
	v_mfma_f32_16x16x32_bf16 v[78:81], v[130:133], v[202:205], v[78:81]
	v_mfma_f32_16x16x32_bf16 v[74:77], v[138:141], v[202:205], v[74:77]
	v_mfma_f32_16x16x32_bf16 v[126:129], v[134:137], v[166:169], v[126:129]
	v_mfma_f32_16x16x32_bf16 v[122:125], v[142:145], v[166:169], v[122:125]
	v_mfma_f32_16x16x32_bf16 v[110:113], v[134:137], v[174:177], v[110:113]
	v_mfma_f32_16x16x32_bf16 v[106:109], v[142:145], v[174:177], v[106:109]
	v_mfma_f32_16x16x32_bf16 v[94:97], v[134:137], v[198:201], v[94:97]
	v_mfma_f32_16x16x32_bf16 v[90:93], v[142:145], v[198:201], v[90:93]
	v_mfma_f32_16x16x32_bf16 v[78:81], v[134:137], v[212:215], v[78:81]
	v_mfma_f32_16x16x32_bf16 v[74:77], v[142:145], v[212:215], v[74:77]
	v_mfma_f32_16x16x32_bf16 v[118:121], v[146:149], v[162:165], v[118:121]
	v_mfma_f32_16x16x32_bf16 v[114:117], v[154:157], v[162:165], v[114:117]
	v_mfma_f32_16x16x32_bf16 v[102:105], v[146:149], v[170:173], v[102:105]
	v_mfma_f32_16x16x32_bf16 v[98:101], v[154:157], v[170:173], v[98:101]
	v_mfma_f32_16x16x32_bf16 v[86:89], v[146:149], v[194:197], v[86:89]
	v_mfma_f32_16x16x32_bf16 v[82:85], v[154:157], v[194:197], v[82:85]
	v_mfma_f32_16x16x32_bf16 v[70:73], v[146:149], v[202:205], v[70:73]
	v_mfma_f32_16x16x32_bf16 v[66:69], v[154:157], v[202:205], v[66:69]
	v_mfma_f32_16x16x32_bf16 v[118:121], v[150:153], v[166:169], v[118:121]
	v_mfma_f32_16x16x32_bf16 v[114:117], v[158:161], v[166:169], v[114:117]
	v_mfma_f32_16x16x32_bf16 v[102:105], v[150:153], v[174:177], v[102:105]
	v_mfma_f32_16x16x32_bf16 v[98:101], v[158:161], v[174:177], v[98:101]
	v_mfma_f32_16x16x32_bf16 v[86:89], v[150:153], v[198:201], v[86:89]
	v_mfma_f32_16x16x32_bf16 v[82:85], v[158:161], v[198:201], v[82:85]
	v_mfma_f32_16x16x32_bf16 v[70:73], v[150:153], v[212:215], v[70:73]
	v_mfma_f32_16x16x32_bf16 v[66:69], v[158:161], v[212:215], v[66:69]
	s_barrier
	s_add_i32 s18, s72, s61
	v_lshl_add_u64 v[216:217], s[50:51], 0, v[180:181]
	s_mov_b32 m0, s18
	ds_read_b128 v[162:165], v210 offset:16384
	ds_read_b128 v[166:169], v210 offset:17408
	ds_read_b128 v[170:173], v210 offset:18432
	ds_read_b128 v[174:177], v210 offset:19456
	ds_read_b128 v[194:197], v210 offset:20480
	ds_read_b128 v[198:201], v210 offset:21504
	ds_read_b128 v[202:205], v210 offset:22528
	ds_read_b128 v[212:215], v210 offset:23552
	global_load_lds_dwordx4 v[216:217], off
	s_add_i32 m0, s18, 0x2000
	s_add_u32 s80, s50, 0x80000
	v_lshl_add_u64 v[218:219], s[50:51], 0, v[184:185]
	s_addc_u32 s81, s51, 0
	s_add_i32 s18, s73, s61
	global_load_lds_dwordx4 v[218:219], off
	v_lshl_add_u64 v[220:221], s[80:81], 0, v[180:181]
	s_mov_b32 m0, s18
	v_lshl_add_u64 v[224:225], s[52:53], 0, v[182:183]
	global_load_lds_dwordx4 v[220:221], off
	v_lshl_add_u64 v[220:221], s[80:81], 0, v[184:185]
	s_add_i32 m0, s18, 0x2000
	s_nop 0
	global_load_lds_dwordx4 v[220:221], off
	v_lshl_add_u64 v[220:221], s[52:53], 0, v[178:179]
	s_mov_b32 m0, s62
	s_nop 0
	global_load_lds_dwordx4 v[220:221], off
	s_mov_b32 m0, s63
	s_nop 0
	global_load_lds_dwordx4 v[224:225], off
	s_waitcnt vmcnt(8)
	s_waitcnt lgkmcnt(0)
	s_barrier
; #define PG8_STAGE(bufoff, gbase, voff) do { _Pragma("unroll") for (int _i = 0; _i < 2; ++_i) \
;         __builtin_amdgcn_global_load_lds((const unsigned*)((const char*)(gbase) + (voff)[_i]), (PG8_LAS unsigned*)(lds + (bufoff) + ldsw + _i * 8192), 16, 0, 0); } while (0)
; #define PG8_LDA(dst, b, h) do { _Pragma("unroll") for (int m = 0; m < 4; ++m) _Pragma("unroll") for (int k = 0; k < 2; ++k) dst[m][k] = *(const PG8_LAS bf16x8*)(lds + PG8_SA(b, h) + aoff + m * 2048 + k * 1024); } while (0)
; #define PG8_LDB(dst, b, h) do { _Pragma("unroll") for (int n = 0; n < 2; ++n) _Pragma("unroll") for (int k = 0; k < 2; ++k) dst[n][k] = *(const PG8_LAS bf16x8*)(lds + PG8_SB(b, h) + boff + n * 2048 + k * 1024); } while (0)
; #define PG8_MMA(ai, bj, At, Bt) do { __builtin_amdgcn_s_setprio(1); _Pragma("unroll") for (int m = 0; m < 4; ++m) _Pragma("unroll") for (int n = 0; n < 2; ++n) _Pragma("unroll") for (int k = 0; k < 2; ++k) \
;         acc[ai][bj][m][n] = __builtin_amdgcn_mfma_f32_16x16x32_bf16(Bt[n][k], At[m][k], acc[ai][bj][m][n], 0, 0, 0); __builtin_amdgcn_s_setprio(0); } while (0)
; #define PG8_WAIT_V(n) asm volatile("s_waitcnt vmcnt(" #n ")" ::: "memory")
; #define PG8_WAIT_L(n) asm volatile("s_waitcnt lgkmcnt(" #n ")" ::: "memory")
; #define PG8_BAR __builtin_amdgcn_s_barrier()
; #define PG8_SCHED __builtin_amdgcn_sched_barrier(0)
; template <class Epi, class Sched, bool ALIGN_EPI = false, bool SP2 = false>
; __device__ __forceinline__ void gemm_phase(PG8_LAS unsigned char* lds, const Gemm g, const Sched& S, const Epi& E) {
;     ...
;             PG8_WAIT_V(8); PG8_WAIT_L(0); PG8_BAR; PG8_MMA(1, 0, At, B0); PG8_MMA(1, 1, At, B1); PG8_BAR; PG8_SCHED;
;             PG8_LDB(B0, 1, 0); PG8_LDB(B1, 1, 1); PG8_SCHED; PG8_LDA(At, 1, 0); PG8_STAGE(PG8_SA(0, 1), a2 + hA, voffA);
;             PG8_WAIT_V(8); PG8_WAIT_L(0); PG8_BAR; PG8_MMA(0, 0, At, B0); PG8_MMA(0, 1, At, B1); PG8_BAR; PG8_SCHED;
	s_waitcnt lgkmcnt(0)
	v_mfma_f32_16x16x32_bf16 v[62:65], v[130:133], v[162:165], v[62:65]
	v_mfma_f32_16x16x32_bf16 v[58:61], v[138:141], v[162:165], v[58:61]
	v_mfma_f32_16x16x32_bf16 v[46:49], v[130:133], v[170:173], v[46:49]
	v_mfma_f32_16x16x32_bf16 v[42:45], v[138:141], v[170:173], v[42:45]
	v_mfma_f32_16x16x32_bf16 v[30:33], v[130:133], v[194:197], v[30:33]
	v_mfma_f32_16x16x32_bf16 v[26:29], v[138:141], v[194:197], v[26:29]
	v_mfma_f32_16x16x32_bf16 v[14:17], v[130:133], v[202:205], v[14:17]
	v_mfma_f32_16x16x32_bf16 v[10:13], v[138:141], v[202:205], v[10:13]
	v_mfma_f32_16x16x32_bf16 v[62:65], v[134:137], v[166:169], v[62:65]
	v_mfma_f32_16x16x32_bf16 v[58:61], v[142:145], v[166:169], v[58:61]
	v_mfma_f32_16x16x32_bf16 v[46:49], v[134:137], v[174:177], v[46:49]
	v_mfma_f32_16x16x32_bf16 v[42:45], v[142:145], v[174:177], v[42:45]
	v_mfma_f32_16x16x32_bf16 v[30:33], v[134:137], v[198:201], v[30:33]
	v_mfma_f32_16x16x32_bf16 v[26:29], v[142:145], v[198:201], v[26:29]
	v_mfma_f32_16x16x32_bf16 v[14:17], v[134:137], v[212:215], v[14:17]
	v_mfma_f32_16x16x32_bf16 v[10:13], v[142:145], v[212:215], v[10:13]
	v_mfma_f32_16x16x32_bf16 v[54:57], v[146:149], v[162:165], v[54:57]
	v_mfma_f32_16x16x32_bf16 v[50:53], v[154:157], v[162:165], v[50:53]
	v_mfma_f32_16x16x32_bf16 v[38:41], v[146:149], v[170:173], v[38:41]
	v_mfma_f32_16x16x32_bf16 v[34:37], v[154:157], v[170:173], v[34:37]
	v_mfma_f32_16x16x32_bf16 v[22:25], v[146:149], v[194:197], v[22:25]
	v_mfma_f32_16x16x32_bf16 v[18:21], v[154:157], v[194:197], v[18:21]
	v_mfma_f32_16x16x32_bf16 v[6:9], v[146:149], v[202:205], v[6:9]
	v_mfma_f32_16x16x32_bf16 v[2:5], v[154:157], v[202:205], v[2:5]
	v_mfma_f32_16x16x32_bf16 v[54:57], v[150:153], v[166:169], v[54:57]
	v_mfma_f32_16x16x32_bf16 v[50:53], v[158:161], v[166:169], v[50:53]
	v_mfma_f32_16x16x32_bf16 v[38:41], v[150:153], v[174:177], v[38:41]
	v_mfma_f32_16x16x32_bf16 v[34:37], v[158:161], v[174:177], v[34:37]
	v_mfma_f32_16x16x32_bf16 v[22:25], v[150:153], v[198:201], v[22:25]
	v_mfma_f32_16x16x32_bf16 v[18:21], v[158:161], v[198:201], v[18:21]
	v_mfma_f32_16x16x32_bf16 v[6:9], v[150:153], v[212:215], v[6:9]
	v_mfma_f32_16x16x32_bf16 v[2:5], v[158:161], v[212:215], v[2:5]
	s_barrier
	s_add_i32 s18, 0, 0x18000
	s_add_i32 s19, 0, 0x1c000
	v_add_u32_e32 v142, s18, v206
	v_add_u32_e32 v158, s19, v206
	ds_read_b128 v[130:133], v142
	ds_read_b128 v[134:137], v142 offset:1024
	ds_read_b128 v[138:141], v142 offset:2048
	ds_read_b128 v[142:145], v142 offset:3072
	ds_read_b128 v[146:149], v158
	ds_read_b128 v[150:153], v158 offset:1024
	ds_read_b128 v[154:157], v158 offset:2048
	ds_read_b128 v[158:161], v158 offset:3072
	s_add_u32 s52, s52, 0x80000
	s_addc_u32 s53, s53, 0
	s_mov_b32 m0, s64
	v_lshl_add_u64 v[226:227], s[52:53], 0, v[178:179]
	ds_read_b128 v[162:165], v210 offset:32768
	ds_read_b128 v[166:169], v210 offset:33792
	ds_read_b128 v[170:173], v210 offset:34816
	ds_read_b128 v[174:177], v210 offset:35840
	ds_read_b128 v[194:197], v210 offset:36864
	ds_read_b128 v[198:201], v210 offset:37888
	ds_read_b128 v[202:205], v210 offset:38912
	ds_read_b128 v[212:215], v210 offset:39936
	global_load_lds_dwordx4 v[226:227], off
	v_lshl_add_u64 v[226:227], s[52:53], 0, v[182:183]
	s_mov_b32 m0, s65
	s_nop 0
	global_load_lds_dwordx4 v[226:227], off
	s_waitcnt vmcnt(8)
	s_waitcnt lgkmcnt(0)
	s_barrier
	s_waitcnt lgkmcnt(0)
	v_mfma_f32_16x16x32_bf16 v[126:129], v[130:133], v[162:165], v[126:129]
	v_mfma_f32_16x16x32_bf16 v[122:125], v[138:141], v[162:165], v[122:125]
	v_mfma_f32_16x16x32_bf16 v[110:113], v[130:133], v[170:173], v[110:113]
	v_mfma_f32_16x16x32_bf16 v[106:109], v[138:141], v[170:173], v[106:109]
	v_mfma_f32_16x16x32_bf16 v[94:97], v[130:133], v[194:197], v[94:97]
	v_mfma_f32_16x16x32_bf16 v[90:93], v[138:141], v[194:197], v[90:93]
	v_mfma_f32_16x16x32_bf16 v[78:81], v[130:133], v[202:205], v[78:81]
	v_mfma_f32_16x16x32_bf16 v[74:77], v[138:141], v[202:205], v[74:77]
	v_mfma_f32_16x16x32_bf16 v[126:129], v[134:137], v[166:169], v[126:129]
	v_mfma_f32_16x16x32_bf16 v[122:125], v[142:145], v[166:169], v[122:125]
	v_mfma_f32_16x16x32_bf16 v[110:113], v[134:137], v[174:177], v[110:113]
	v_mfma_f32_16x16x32_bf16 v[106:109], v[142:145], v[174:177], v[106:109]
	v_mfma_f32_16x16x32_bf16 v[94:97], v[134:137], v[198:201], v[94:97]
	v_mfma_f32_16x16x32_bf16 v[90:93], v[142:145], v[198:201], v[90:93]
	v_mfma_f32_16x16x32_bf16 v[78:81], v[134:137], v[212:215], v[78:81]
	v_mfma_f32_16x16x32_bf16 v[74:77], v[142:145], v[212:215], v[74:77]
	v_mfma_f32_16x16x32_bf16 v[118:121], v[146:149], v[162:165], v[118:121]
	v_mfma_f32_16x16x32_bf16 v[114:117], v[154:157], v[162:165], v[114:117]
	v_mfma_f32_16x16x32_bf16 v[102:105], v[146:149], v[170:173], v[102:105]
	v_mfma_f32_16x16x32_bf16 v[98:101], v[154:157], v[170:173], v[98:101]
	v_mfma_f32_16x16x32_bf16 v[86:89], v[146:149], v[194:197], v[86:89]
	v_mfma_f32_16x16x32_bf16 v[82:85], v[154:157], v[194:197], v[82:85]
	v_mfma_f32_16x16x32_bf16 v[70:73], v[146:149], v[202:205], v[70:73]
	v_mfma_f32_16x16x32_bf16 v[66:69], v[154:157], v[202:205], v[66:69]
	v_mfma_f32_16x16x32_bf16 v[118:121], v[150:153], v[166:169], v[118:121]
	v_mfma_f32_16x16x32_bf16 v[114:117], v[158:161], v[166:169], v[114:117]
	v_mfma_f32_16x16x32_bf16 v[102:105], v[150:153], v[174:177], v[102:105]
	v_mfma_f32_16x16x32_bf16 v[98:101], v[158:161], v[174:177], v[98:101]
	v_mfma_f32_16x16x32_bf16 v[86:89], v[150:153], v[198:201], v[86:89]
	v_mfma_f32_16x16x32_bf16 v[82:85], v[158:161], v[198:201], v[82:85]
	v_mfma_f32_16x16x32_bf16 v[70:73], v[150:153], v[212:215], v[70:73]
	v_mfma_f32_16x16x32_bf16 v[66:69], v[158:161], v[212:215], v[66:69]
	s_barrier
; #define PG8_STAGE(bufoff, gbase, voff) do { _Pragma("unroll") for (int _i = 0; _i < 2; ++_i) \
;         __builtin_amdgcn_global_load_lds((const unsigned*)((const char*)(gbase) + (voff)[_i]), (PG8_LAS unsigned*)(lds + (bufoff) + ldsw + _i * 8192), 16, 0, 0); } while (0)
; #define PG8_LDA(dst, b, h) do { _Pragma("unroll") for (int m = 0; m < 4; ++m) _Pragma("unroll") for (int k = 0; k < 2; ++k) dst[m][k] = *(const PG8_LAS bf16x8*)(lds + PG8_SA(b, h) + aoff + m * 2048 + k * 1024); } while (0)
; #define PG8_MMA(ai, bj, At, Bt) do { __builtin_amdgcn_s_setprio(1); _Pragma("unroll") for (int m = 0; m < 4; ++m) _Pragma("unroll") for (int n = 0; n < 2; ++n) _Pragma("unroll") for (int k = 0; k < 2; ++k) \
;         acc[ai][bj][m][n] = __builtin_amdgcn_mfma_f32_16x16x32_bf16(Bt[n][k], At[m][k], acc[ai][bj][m][n], 0, 0, 0); __builtin_amdgcn_s_setprio(0); } while (0)
; #define PG8_WAIT_V(n) asm volatile("s_waitcnt vmcnt(" #n ")" ::: "memory")
; #define PG8_WAIT_L(n) asm volatile("s_waitcnt lgkmcnt(" #n ")" ::: "memory")
; #define PG8_BAR __builtin_amdgcn_s_barrier()
; #define PG8_SCHED __builtin_amdgcn_sched_barrier(0)
; template <class Epi, class Sched, bool ALIGN_EPI = false, bool SP2 = false>
; __device__ __forceinline__ void gemm_phase(PG8_LAS unsigned char* lds, const Gemm g, const Sched& S, const Epi& E) {
;     ...
;             PG8_WAIT_V(8); PG8_WAIT_L(0); PG8_BAR; PG8_MMA(0, 0, At, B0); PG8_MMA(0, 1, At, B1); PG8_BAR; PG8_SCHED;
;             PG8_LDA(At, 1, 1); PG8_STAGE(PG8_SB(1, 0), b3, voffB); PG8_STAGE(PG8_SB(1, 1), b3 + hB, voffB); PG8_STAGE(PG8_SA(1, 0), a3, voffA);
;             PG8_WAIT_V(8); PG8_WAIT_L(0); PG8_BAR; PG8_MMA(1, 0, At, B0); PG8_MMA(1, 1, At, B1); PG8_BAR; PG8_SCHED;
;     ...
;         if constexpr (ALIGN_EPI) { if (wr == 0) PG8_BAR; }
	s_add_i32 s18, s18, s61
	v_lshl_add_u64 v[216:217], v[216:217], 0, s[22:23]
	s_mov_b32 m0, s18
	ds_read_b128 v[162:165], v210 offset:49152
	ds_read_b128 v[166:169], v210 offset:50176
	ds_read_b128 v[170:173], v210 offset:51200
	ds_read_b128 v[174:177], v210 offset:52224
	ds_read_b128 v[194:197], v210 offset:53248
	ds_read_b128 v[198:201], v210 offset:54272
	ds_read_b128 v[202:205], v210 offset:55296
	ds_read_b128 v[212:215], v210 offset:56320
	global_load_lds_dwordx4 v[216:217], off
	s_add_i32 m0, s18, 0x2000
	s_add_u32 s50, s50, 0x80080
	v_lshl_add_u64 v[216:217], v[218:219], 0, s[22:23]
	s_addc_u32 s51, s51, 0
	s_add_i32 s18, s19, s61
	global_load_lds_dwordx4 v[216:217], off
	v_lshl_add_u64 v[216:217], s[50:51], 0, v[180:181]
	s_mov_b32 m0, s18
	s_nop 0
	global_load_lds_dwordx4 v[216:217], off
	v_lshl_add_u64 v[216:217], s[50:51], 0, v[184:185]
	s_add_i32 m0, s18, 0x2000
	s_nop 0
	global_load_lds_dwordx4 v[216:217], off
	v_lshl_add_u64 v[216:217], v[220:221], 0, s[22:23]
	s_mov_b32 m0, s69
	s_nop 0
	global_load_lds_dwordx4 v[216:217], off
	v_lshl_add_u64 v[216:217], v[224:225], 0, s[22:23]
	s_mov_b32 m0, s70
	s_nop 0
	global_load_lds_dwordx4 v[216:217], off
	s_waitcnt vmcnt(8)
	s_waitcnt lgkmcnt(0)
	s_barrier
	s_waitcnt lgkmcnt(0)
	v_mfma_f32_16x16x32_bf16 v[62:65], v[130:133], v[162:165], v[62:65]
	v_mfma_f32_16x16x32_bf16 v[58:61], v[138:141], v[162:165], v[58:61]
	v_mfma_f32_16x16x32_bf16 v[46:49], v[130:133], v[170:173], v[46:49]
	v_mfma_f32_16x16x32_bf16 v[42:45], v[138:141], v[170:173], v[42:45]
	v_mfma_f32_16x16x32_bf16 v[30:33], v[130:133], v[194:197], v[30:33]
	v_mfma_f32_16x16x32_bf16 v[26:29], v[138:141], v[194:197], v[26:29]
	v_mfma_f32_16x16x32_bf16 v[14:17], v[130:133], v[202:205], v[14:17]
	v_mfma_f32_16x16x32_bf16 v[10:13], v[138:141], v[202:205], v[10:13]
	v_mfma_f32_16x16x32_bf16 v[62:65], v[134:137], v[166:169], v[62:65]
	v_mfma_f32_16x16x32_bf16 v[58:61], v[142:145], v[166:169], v[58:61]
	v_mfma_f32_16x16x32_bf16 v[46:49], v[134:137], v[174:177], v[46:49]
	v_mfma_f32_16x16x32_bf16 v[42:45], v[142:145], v[174:177], v[42:45]
	v_mfma_f32_16x16x32_bf16 v[30:33], v[134:137], v[198:201], v[30:33]
	v_mfma_f32_16x16x32_bf16 v[26:29], v[142:145], v[198:201], v[26:29]
	v_mfma_f32_16x16x32_bf16 v[14:17], v[134:137], v[212:215], v[14:17]
	v_mfma_f32_16x16x32_bf16 v[10:13], v[142:145], v[212:215], v[10:13]
	v_mfma_f32_16x16x32_bf16 v[54:57], v[146:149], v[162:165], v[54:57]
	v_mfma_f32_16x16x32_bf16 v[50:53], v[154:157], v[162:165], v[50:53]
	v_mfma_f32_16x16x32_bf16 v[38:41], v[146:149], v[170:173], v[38:41]
	v_mfma_f32_16x16x32_bf16 v[34:37], v[154:157], v[170:173], v[34:37]
	v_mfma_f32_16x16x32_bf16 v[22:25], v[146:149], v[194:197], v[22:25]
	v_mfma_f32_16x16x32_bf16 v[18:21], v[154:157], v[194:197], v[18:21]
	v_mfma_f32_16x16x32_bf16 v[6:9], v[146:149], v[202:205], v[6:9]
	v_mfma_f32_16x16x32_bf16 v[2:5], v[154:157], v[202:205], v[2:5]
	v_mfma_f32_16x16x32_bf16 v[54:57], v[150:153], v[166:169], v[54:57]
	v_mfma_f32_16x16x32_bf16 v[50:53], v[158:161], v[166:169], v[50:53]
	v_mfma_f32_16x16x32_bf16 v[38:41], v[150:153], v[174:177], v[38:41]
	v_mfma_f32_16x16x32_bf16 v[34:37], v[158:161], v[174:177], v[34:37]
	v_mfma_f32_16x16x32_bf16 v[22:25], v[150:153], v[198:201], v[22:25]
	v_mfma_f32_16x16x32_bf16 v[18:21], v[158:161], v[198:201], v[18:21]
	v_mfma_f32_16x16x32_bf16 v[6:9], v[150:153], v[212:215], v[6:9]
	v_mfma_f32_16x16x32_bf16 v[2:5], v[158:161], v[212:215], v[2:5]
	s_barrier
	s_add_i32 s78, s78, 2
	s_add_u32 s48, s48, 0x100
	s_addc_u32 s49, s49, 0
	s_add_u32 s76, s76, 0x100
	s_addc_u32 s77, s77, 0
	s_cmp_gt_u32 s78, 29
	s_cbranch_scc0 .LBB0_963
	s_and_b64 vcc, exec, s[24:25]
	s_cbranch_vccz .LBB0_966
	s_barrier

; #define PG8_WAIT_V(n) asm volatile("s_waitcnt vmcnt(" #n ")" ::: "memory")
; #define PG8_BAR __builtin_amdgcn_s_barrier()
; template <class Epi, class Sched, bool ALIGN_EPI = false, bool SP2 = false>
; __device__ __forceinline__ void gemm_phase(PG8_LAS unsigned char* lds, const Gemm g, const Sched& S, const Epi& E) {
;     ...
;     PG8_WAIT_V(0);
;     if constexpr (!ALIGN_EPI) { if (wr == 0) PG8_BAR; }
;     PG8_BAR;
; __device__ __forceinline__ void xcd_barrier(const XcdBarrier& b) {
;     asm volatile("s_waitcnt vmcnt(0)" ::: "memory");
;     __syncthreads();
;     if (threadIdx.x == 0) {
;         unsigned* bar = b.bar;
;         __builtin_amdgcn_s_waitcnt(0);
;         unsigned nloc = b.st[0], nx = b.st[1];
;         if (nloc == 0u) { xcd_barrier_complete(bar, b.x, nloc, nx); b.st[0] = nloc; b.st[1] = nx; }
.LBB0_986:
	s_setprio 0
	s_waitcnt vmcnt(0)
	s_waitcnt lgkmcnt(0)
	s_barrier
	s_and_saveexec_b64 s[0:1], s[86:87]
	s_xor_b64 s[0:1], exec, s[0:1]
	s_cbranch_execz .LBB0_1039
	s_add_i32 s6, 0, 0x20040
	v_mov_b32_e32 v1, s6
	s_waitcnt vmcnt(0) expcnt(0) lgkmcnt(0)
	ds_read_b32 v3, v1
	s_add_i32 s6, 0, 0x20044
	v_mov_b32_e32 v1, s6
	ds_read_b32 v1, v1
	s_waitcnt lgkmcnt(1)
	v_cmp_ne_u32_e32 vcc, 0, v3
	s_cbranch_vccnz .LBB0_1002
	s_load_dwordx2 s[14:15], s[84:85], 0x0
	s_load_dword s9, s[84:85], 0x8
	s_add_u32 s6, s30, 0x1000
	s_addc_u32 s7, s31, 0
	s_add_u32 s8, s30, 0x1100
	s_waitcnt lgkmcnt(0)
	s_mul_i32 s33, s15, s14
	s_mul_i32 s33, s33, s9
	s_addc_u32 s9, s31, 0
	s_add_u32 s14, s30, 0x1200
	s_addc_u32 s15, s31, 0
	s_add_u32 s16, s30, 0x1300
	s_addc_u32 s17, s31, 0
	s_mov_b32 s36, 1
	v_mov_b32_e32 v17, 0
	s_branch .LBB0_990

; #define PG8_STAGE(bufoff, gbase, voff) do { _Pragma("unroll") for (int _i = 0; _i < 2; ++_i) \
;         __builtin_amdgcn_global_load_lds((const unsigned*)((const char*)(gbase) + (voff)[_i]), (PG8_LAS unsigned*)(lds + (bufoff) + ldsw + _i * 8192), 16, 0, 0); } while (0)
; #define PG8_WAIT_V(n) asm volatile("s_waitcnt vmcnt(" #n ")" ::: "memory")
; #define PG8_BAR __builtin_amdgcn_s_barrier()
; __device__ __forceinline__ float sum4(f32x4 a) { return (a[0] + a[1]) + (a[2] + a[3]); }
; template <class Epi, class Sched, bool ALIGN_EPI = false, bool SP2 = false>
; __device__ __forceinline__ void gemm_phase(PG8_LAS unsigned char* lds, const Gemm g, const Sched& S, const Epi& E) {
;     ...
;         PG8_WAIT_V(2); PG8_BAR;
;         PG8_STAGE(PG8_SB(1, 0), cB + kstep, voffB); PG8_STAGE(PG8_SA(1, 0), cA + kstep, voffA); PG8_STAGE(PG8_SB(1, 1), cB + hB + kstep, voffB);
;         PG8_WAIT_V(6); PG8_BAR;
;     __device__ __forceinline__ void operator()(AccRef acc, const pg8::Unit& u, int wr, int wc, int fr, int fq) const {
;         const int row0 = u.pm * 256 + wr * 64 + fr, c0 = u.pn * 128 + wc * 32 + 8 * fq;
;         float r2[2][4];
; #pragma unroll
;         for (int ai = 0; ai < 2; ++ai)
; #pragma unroll
;             for (int m = 0; m < 4; ++m) { const int r = row0 + ai * 128 + m * 16;
;                 const float* pp = part + (size_t)r * 32 + 8 * fq;
;                 float s = sum4(*(const f32x4*)pp) + sum4(*(const f32x4*)(pp + 4));
;                 s += __shfl_xor(s, 16); s += __shfl_xor(s, 32);
;                 r2[ai][m] = 1.0f / sqrtf(s * (1.0f / 2048.0f) + EPS); }
.LBB0_1042:
	s_add_u32 s16, s6, 0x5800000
	s_addc_u32 s17, s7, 0
	s_lshl_b32 s18, s20, 5
	s_mov_b64 s[20:21], 0x80
	s_and_b32 s18, s18, 0x60
	s_add_i32 m0, s51, 0x18000
	v_lshl_add_u64 v[8:9], v[8:9], 0, s[20:21]
	s_lshl_b32 s1, s24, 13
	s_lshl_b32 s19, s18, 7
	s_waitcnt vmcnt(2)
	s_barrier
	global_load_lds_dwordx4 v[8:9], off
	v_lshl_add_u64 v[6:7], v[6:7], 0, s[20:21]
	s_add_i32 m0, s51, 0x1a000
	s_add_i32 s60, s51, 0x8000
	s_add_i32 s61, s51, 0xa000
	global_load_lds_dwordx4 v[6:7], off
	v_lshl_add_u64 v[2:3], v[2:3], 0, s[20:21]
	s_mov_b32 m0, s60
	s_add_u32 s36, s42, 0x80080
	global_load_lds_dwordx4 v[2:3], off
	v_lshl_add_u64 v[2:3], v[4:5], 0, s[20:21]
	s_mov_b32 m0, s61
	s_addc_u32 s37, s43, 0
	global_load_lds_dwordx4 v[2:3], off
	s_add_i32 m0, s51, 0x1c000
	v_lshl_add_u64 v[2:3], s[36:37], 0, v[134:135]
	global_load_lds_dwordx4 v[2:3], off
	v_lshl_add_u64 v[2:3], s[36:37], 0, v[130:131]
	s_add_i32 m0, s51, 0x1e000
	s_cmpk_lt_u32 s23, 0x100
	global_load_lds_dwordx4 v[2:3], off
	v_lshrrev_b32_e32 v3, 1, v12
	v_and_b32_e32 v4, 24, v3
	v_and_b32_e32 v2, 15, v12
	v_lshlrev_b32_e32 v3, 1, v4
	v_lshl_or_b32 v1, s24, 6, v2
	v_lshl_or_b32 v2, v2, 6, v3
	v_lshlrev_b32_e32 v3, 2, v12
	v_and_b32_e32 v3, 32, v3
	v_bitop3_b32 v5, v2, s1, v3 bitop3:0xde
	v_bitop3_b32 v165, v2, s19, v3 bitop3:0xde
	v_lshlrev_b32_e32 v2, 2, v4
	v_mov_b32_e32 v3, v135
	v_lshl_add_u64 v[2:3], s[6:7], 0, v[2:3]
	s_mov_b64 s[6:7], 0x1e00000
	v_lshl_add_u64 v[138:139], v[2:3], 0, s[6:7]
	v_lshlrev_b32_e32 v2, 15, v15
	v_and_b32_e32 v2, 0xffff0000, v2
	v_lshl_add_u32 v2, v14, 12, v2
	v_and_b32_e32 v3, 1, v15
	v_lshl_or_b32 v2, v3, 6, v2
	v_lshl_add_u32 v140, v16, 1, v2
	v_lshlrev_b32_e32 v2, 15, v10
	v_and_b32_e32 v2, 0xffff0000, v2
	s_waitcnt vmcnt(6)
	v_lshl_add_u32 v2, v11, 12, v2
	v_and_b32_e32 v3, 1, v10
	s_sext_i32_i16 s67, s22
	s_cselect_b64 s[22:23], -1, 0
	v_lshl_or_b32 v2, v3, 6, v2
	s_add_i32 s63, 0, 0x10000
	s_add_i32 s64, 0, 0x14000
	s_waitcnt lgkmcnt(0)
	s_ashr_i32 s62, s58, 31
	v_or_b32_e32 v167, s18, v4
	v_mov_b32_e32 v141, v135
	v_lshl_add_u32 v142, v13, 1, v2
	v_mov_b32_e32 v143, v135
	v_mov_b64_e32 v[144:145], 0xb00
	v_mov_b64_e32 v[146:147], 0xaff
	v_add_u32_e32 v169, s63, v165
	v_add_u32_e32 v171, s64, v165
	v_add_u32_e32 v173, 0, v5
	v_mbcnt_hi_u32_b32 v175, -1, v222
	v_mov_b32_e32 v177, 0x358637bd
	s_mov_b32 s65, 0xf800000
	v_mov_b32_e32 v179, 0x260
	s_movk_i32 s66, 0x2c00
	s_barrier
	s_mov_b32 s98, -1
	v_readfirstlane_b32 s99, v0
	s_nop 3
	s_lshr_b32 s99, s99, 8
	s_cmp_eq_u32 s99, 0
	s_cbranch_scc1 .Lprio_skip_6
	s_setprio 1

; #define PG8_STAGE(bufoff, gbase, voff) do { _Pragma("unroll") for (int _i = 0; _i < 2; ++_i) \
;         __builtin_amdgcn_global_load_lds((const unsigned*)((const char*)(gbase) + (voff)[_i]), (PG8_LAS unsigned*)(lds + (bufoff) + ldsw + _i * 8192), 16, 0, 0); } while (0)
; #define PG8_LDA(dst, b, h) do { _Pragma("unroll") for (int m = 0; m < 4; ++m) _Pragma("unroll") for (int k = 0; k < 2; ++k) dst[m][k] = *(const PG8_LAS bf16x8*)(lds + PG8_SA(b, h) + aoff + m * 2048 + k * 1024); } while (0)
; #define PG8_LDB(dst, b, h) do { _Pragma("unroll") for (int n = 0; n < 2; ++n) _Pragma("unroll") for (int k = 0; k < 2; ++k) dst[n][k] = *(const PG8_LAS bf16x8*)(lds + PG8_SB(b, h) + boff + n * 2048 + k * 1024); } while (0)
; #define PG8_MMA(ai, bj, At, Bt) do { __builtin_amdgcn_s_setprio(1); _Pragma("unroll") for (int m = 0; m < 4; ++m) _Pragma("unroll") for (int n = 0; n < 2; ++n) _Pragma("unroll") for (int k = 0; k < 2; ++k) \
;         acc[ai][bj][m][n] = __builtin_amdgcn_mfma_f32_16x16x32_bf16(Bt[n][k], At[m][k], acc[ai][bj][m][n], 0, 0, 0); __builtin_amdgcn_s_setprio(0); } while (0)
; #define PG8_WAIT_V(n) asm volatile("s_waitcnt vmcnt(" #n ")" ::: "memory")
; #define PG8_WAIT_L(n) asm volatile("s_waitcnt lgkmcnt(" #n ")" ::: "memory")
; #define PG8_BAR __builtin_amdgcn_s_barrier()
; #define PG8_SCHED __builtin_amdgcn_sched_barrier(0)
; template <class Epi, class Sched, bool ALIGN_EPI = false, bool SP2 = false>
; __device__ __forceinline__ void gemm_phase(PG8_LAS unsigned char* lds, const Gemm g, const Sched& S, const Epi& E) {
;     ...
;             PG8_LDB(B0, 0, 0); PG8_LDB(B1, 0, 1); PG8_SCHED; PG8_LDA(At, 0, 0); PG8_STAGE(PG8_SA(1, 1), a1 + hA, voffA);
;             PG8_WAIT_V(8); PG8_WAIT_L(0); PG8_BAR; PG8_MMA(0, 0, At, B0); PG8_MMA(0, 1, At, B1); PG8_BAR; PG8_SCHED;
;             PG8_LDA(At, 0, 1); PG8_STAGE(PG8_SB(0, 0), b2, voffB); PG8_STAGE(PG8_SB(0, 1), b2 + hB, voffB); PG8_STAGE(PG8_SA(0, 0), a2, voffA);
;             PG8_WAIT_V(8); PG8_WAIT_L(0); PG8_BAR; PG8_MMA(1, 0, At, B0); PG8_MMA(1, 1, At, B1); PG8_BAR; PG8_SCHED;
.LBB0_1048:
	ds_read_b128 v[148:151], v169
	ds_read_b128 v[152:155], v169 offset:1024
	ds_read_b128 v[156:159], v169 offset:2048
	ds_read_b128 v[160:163], v169 offset:3072
	ds_read_b128 v[180:183], v171
	ds_read_b128 v[184:187], v171 offset:1024
	ds_read_b128 v[188:191], v171 offset:2048
	ds_read_b128 v[192:195], v171 offset:3072
	s_add_u32 s18, s8, 0xfff80080
	s_addc_u32 s19, s9, -1
	s_cmp_eq_u32 s72, 28
	s_cselect_b32 s45, s1, s19
	s_cselect_b32 s44, s37, s18
	s_cselect_b32 s43, s25, s71
	s_cselect_b32 s42, s69, s70
	v_lshl_add_u64 v[220:221], s[8:9], 0, v[140:141]
	s_add_i32 m0, s51, 0xc000
	ds_read_b128 v[196:199], v173
	ds_read_b128 v[200:203], v173 offset:1024
	ds_read_b128 v[204:207], v173 offset:2048
	ds_read_b128 v[208:211], v173 offset:3072
	ds_read_b128 v[212:215], v173 offset:4096
	ds_read_b128 v[216:219], v173 offset:5120
	ds_read_b128 v[224:227], v173 offset:6144
	ds_read_b128 v[228:231], v173 offset:7168
	global_load_lds_dwordx4 v[220:221], off
	v_lshl_add_u64 v[220:221], s[8:9], 0, v[142:143]
	s_add_i32 m0, s51, 0xe000
	s_nop 0
	global_load_lds_dwordx4 v[220:221], off
	s_waitcnt vmcnt(8)
	s_waitcnt lgkmcnt(0)
	s_barrier
	s_waitcnt lgkmcnt(0)
	v_mfma_f32_16x16x32_bf16 v[126:129], v[148:151], v[196:199], v[126:129]
	v_mfma_f32_16x16x32_bf16 v[122:125], v[156:159], v[196:199], v[122:125]
	v_mfma_f32_16x16x32_bf16 v[110:113], v[148:151], v[204:207], v[110:113]
	v_mfma_f32_16x16x32_bf16 v[106:109], v[156:159], v[204:207], v[106:109]
	v_mfma_f32_16x16x32_bf16 v[94:97], v[148:151], v[212:215], v[94:97]
	v_mfma_f32_16x16x32_bf16 v[90:93], v[156:159], v[212:215], v[90:93]
	v_mfma_f32_16x16x32_bf16 v[78:81], v[148:151], v[224:227], v[78:81]
	v_mfma_f32_16x16x32_bf16 v[74:77], v[156:159], v[224:227], v[74:77]
	v_mfma_f32_16x16x32_bf16 v[126:129], v[152:155], v[200:203], v[126:129]
	v_mfma_f32_16x16x32_bf16 v[122:125], v[160:163], v[200:203], v[122:125]
	v_mfma_f32_16x16x32_bf16 v[110:113], v[152:155], v[208:211], v[110:113]
	v_mfma_f32_16x16x32_bf16 v[106:109], v[160:163], v[208:211], v[106:109]
	v_mfma_f32_16x16x32_bf16 v[94:97], v[152:155], v[216:219], v[94:97]
	v_mfma_f32_16x16x32_bf16 v[90:93], v[160:163], v[216:219], v[90:93]
	v_mfma_f32_16x16x32_bf16 v[78:81], v[152:155], v[228:231], v[78:81]
	v_mfma_f32_16x16x32_bf16 v[74:77], v[160:163], v[228:231], v[74:77]
	v_mfma_f32_16x16x32_bf16 v[118:121], v[180:183], v[196:199], v[118:121]
	v_mfma_f32_16x16x32_bf16 v[114:117], v[188:191], v[196:199], v[114:117]
	v_mfma_f32_16x16x32_bf16 v[102:105], v[180:183], v[204:207], v[102:105]
	v_mfma_f32_16x16x32_bf16 v[98:101], v[188:191], v[204:207], v[98:101]
	v_mfma_f32_16x16x32_bf16 v[86:89], v[180:183], v[212:215], v[86:89]
	v_mfma_f32_16x16x32_bf16 v[82:85], v[188:191], v[212:215], v[82:85]
	v_mfma_f32_16x16x32_bf16 v[70:73], v[180:183], v[224:227], v[70:73]
	v_mfma_f32_16x16x32_bf16 v[66:69], v[188:191], v[224:227], v[66:69]
	v_mfma_f32_16x16x32_bf16 v[118:121], v[184:187], v[200:203], v[118:121]
	v_mfma_f32_16x16x32_bf16 v[114:117], v[192:195], v[200:203], v[114:117]
	v_mfma_f32_16x16x32_bf16 v[102:105], v[184:187], v[208:211], v[102:105]
	v_mfma_f32_16x16x32_bf16 v[98:101], v[192:195], v[208:211], v[98:101]
	v_mfma_f32_16x16x32_bf16 v[86:89], v[184:187], v[216:219], v[86:89]
	v_mfma_f32_16x16x32_bf16 v[82:85], v[192:195], v[216:219], v[82:85]
	v_mfma_f32_16x16x32_bf16 v[70:73], v[184:187], v[228:231], v[70:73]
	v_mfma_f32_16x16x32_bf16 v[66:69], v[192:195], v[228:231], v[66:69]
	s_barrier
	s_add_i32 s18, s63, s49
	v_lshl_add_u64 v[220:221], s[42:43], 0, v[134:135]
	s_mov_b32 m0, s18
	ds_read_b128 v[196:199], v173 offset:16384
	ds_read_b128 v[200:203], v173 offset:17408
	ds_read_b128 v[204:207], v173 offset:18432
	ds_read_b128 v[208:211], v173 offset:19456
	ds_read_b128 v[212:215], v173 offset:20480
	ds_read_b128 v[216:219], v173 offset:21504
	ds_read_b128 v[224:227], v173 offset:22528
	ds_read_b128 v[228:231], v173 offset:23552
	global_load_lds_dwordx4 v[220:221], off
	s_add_i32 m0, s18, 0x2000
	s_add_u32 s74, s42, 0x80000
	v_lshl_add_u64 v[232:233], s[42:43], 0, v[130:131]
	s_addc_u32 s75, s43, 0
	s_add_i32 s18, s64, s49
	global_load_lds_dwordx4 v[232:233], off
	v_lshl_add_u64 v[234:235], s[74:75], 0, v[134:135]
	s_mov_b32 m0, s18
	v_lshl_add_u64 v[236:237], s[44:45], 0, v[132:133]
	global_load_lds_dwordx4 v[234:235], off
	v_lshl_add_u64 v[234:235], s[74:75], 0, v[130:131]
	s_add_i32 m0, s18, 0x2000
	s_nop 0
	global_load_lds_dwordx4 v[234:235], off
	v_lshl_add_u64 v[234:235], s[44:45], 0, v[136:137]
	s_mov_b32 m0, s51
	s_nop 0
	global_load_lds_dwordx4 v[234:235], off
	s_mov_b32 m0, s52
	s_nop 0
	global_load_lds_dwordx4 v[236:237], off
	s_waitcnt vmcnt(8)
	s_waitcnt lgkmcnt(0)
	s_barrier
; #define PG8_STAGE(bufoff, gbase, voff) do { _Pragma("unroll") for (int _i = 0; _i < 2; ++_i) \
;         __builtin_amdgcn_global_load_lds((const unsigned*)((const char*)(gbase) + (voff)[_i]), (PG8_LAS unsigned*)(lds + (bufoff) + ldsw + _i * 8192), 16, 0, 0); } while (0)
; #define PG8_LDA(dst, b, h) do { _Pragma("unroll") for (int m = 0; m < 4; ++m) _Pragma("unroll") for (int k = 0; k < 2; ++k) dst[m][k] = *(const PG8_LAS bf16x8*)(lds + PG8_SA(b, h) + aoff + m * 2048 + k * 1024); } while (0)
; #define PG8_LDB(dst, b, h) do { _Pragma("unroll") for (int n = 0; n < 2; ++n) _Pragma("unroll") for (int k = 0; k < 2; ++k) dst[n][k] = *(const PG8_LAS bf16x8*)(lds + PG8_SB(b, h) + boff + n * 2048 + k * 1024); } while (0)
; #define PG8_MMA(ai, bj, At, Bt) do { __builtin_amdgcn_s_setprio(1); _Pragma("unroll") for (int m = 0; m < 4; ++m) _Pragma("unroll") for (int n = 0; n < 2; ++n) _Pragma("unroll") for (int k = 0; k < 2; ++k) \
;         acc[ai][bj][m][n] = __builtin_amdgcn_mfma_f32_16x16x32_bf16(Bt[n][k], At[m][k], acc[ai][bj][m][n], 0, 0, 0); __builtin_amdgcn_s_setprio(0); } while (0)
; #define PG8_WAIT_V(n) asm volatile("s_waitcnt vmcnt(" #n ")" ::: "memory")
; #define PG8_WAIT_L(n) asm volatile("s_waitcnt lgkmcnt(" #n ")" ::: "memory")
; #define PG8_BAR __builtin_amdgcn_s_barrier()
; #define PG8_SCHED __builtin_amdgcn_sched_barrier(0)
; template <class Epi, class Sched, bool ALIGN_EPI = false, bool SP2 = false>
; __device__ __forceinline__ void gemm_phase(PG8_LAS unsigned char* lds, const Gemm g, const Sched& S, const Epi& E) {
;     ...
;             PG8_WAIT_V(8); PG8_WAIT_L(0); PG8_BAR; PG8_MMA(1, 0, At, B0); PG8_MMA(1, 1, At, B1); PG8_BAR; PG8_SCHED;
;             PG8_LDB(B0, 1, 0); PG8_LDB(B1, 1, 1); PG8_SCHED; PG8_LDA(At, 1, 0); PG8_STAGE(PG8_SA(0, 1), a2 + hA, voffA);
;             PG8_WAIT_V(8); PG8_WAIT_L(0); PG8_BAR; PG8_MMA(0, 0, At, B0); PG8_MMA(0, 1, At, B1); PG8_BAR; PG8_SCHED;
	s_waitcnt lgkmcnt(0)
	v_mfma_f32_16x16x32_bf16 v[62:65], v[148:151], v[196:199], v[62:65]
	v_mfma_f32_16x16x32_bf16 v[58:61], v[156:159], v[196:199], v[58:61]
	v_mfma_f32_16x16x32_bf16 v[46:49], v[148:151], v[204:207], v[46:49]
	v_mfma_f32_16x16x32_bf16 v[42:45], v[156:159], v[204:207], v[42:45]
	v_mfma_f32_16x16x32_bf16 v[30:33], v[148:151], v[212:215], v[30:33]
	v_mfma_f32_16x16x32_bf16 v[26:29], v[156:159], v[212:215], v[26:29]
	v_mfma_f32_16x16x32_bf16 v[14:17], v[148:151], v[224:227], v[14:17]
	v_mfma_f32_16x16x32_bf16 v[10:13], v[156:159], v[224:227], v[10:13]
	v_mfma_f32_16x16x32_bf16 v[62:65], v[152:155], v[200:203], v[62:65]
	v_mfma_f32_16x16x32_bf16 v[58:61], v[160:163], v[200:203], v[58:61]
	v_mfma_f32_16x16x32_bf16 v[46:49], v[152:155], v[208:211], v[46:49]
	v_mfma_f32_16x16x32_bf16 v[42:45], v[160:163], v[208:211], v[42:45]
	v_mfma_f32_16x16x32_bf16 v[30:33], v[152:155], v[216:219], v[30:33]
	v_mfma_f32_16x16x32_bf16 v[26:29], v[160:163], v[216:219], v[26:29]
	v_mfma_f32_16x16x32_bf16 v[14:17], v[152:155], v[228:231], v[14:17]
	v_mfma_f32_16x16x32_bf16 v[10:13], v[160:163], v[228:231], v[10:13]
	v_mfma_f32_16x16x32_bf16 v[54:57], v[180:183], v[196:199], v[54:57]
	v_mfma_f32_16x16x32_bf16 v[50:53], v[188:191], v[196:199], v[50:53]
	v_mfma_f32_16x16x32_bf16 v[38:41], v[180:183], v[204:207], v[38:41]
	v_mfma_f32_16x16x32_bf16 v[34:37], v[188:191], v[204:207], v[34:37]
	v_mfma_f32_16x16x32_bf16 v[22:25], v[180:183], v[212:215], v[22:25]
	v_mfma_f32_16x16x32_bf16 v[18:21], v[188:191], v[212:215], v[18:21]
	v_mfma_f32_16x16x32_bf16 v[6:9], v[180:183], v[224:227], v[6:9]
	v_mfma_f32_16x16x32_bf16 v[2:5], v[188:191], v[224:227], v[2:5]
	v_mfma_f32_16x16x32_bf16 v[54:57], v[184:187], v[200:203], v[54:57]
	v_mfma_f32_16x16x32_bf16 v[50:53], v[192:195], v[200:203], v[50:53]
	v_mfma_f32_16x16x32_bf16 v[38:41], v[184:187], v[208:211], v[38:41]
	v_mfma_f32_16x16x32_bf16 v[34:37], v[192:195], v[208:211], v[34:37]
	v_mfma_f32_16x16x32_bf16 v[22:25], v[184:187], v[216:219], v[22:25]
	v_mfma_f32_16x16x32_bf16 v[18:21], v[192:195], v[216:219], v[18:21]
	v_mfma_f32_16x16x32_bf16 v[6:9], v[184:187], v[228:231], v[6:9]
	v_mfma_f32_16x16x32_bf16 v[2:5], v[192:195], v[228:231], v[2:5]
	s_barrier
	s_add_i32 s18, 0, 0x18000
	s_add_i32 s19, 0, 0x1c000
	v_add_u32_e32 v160, s18, v165
	v_add_u32_e32 v164, s19, v165
	ds_read_b128 v[148:151], v160
	ds_read_b128 v[152:155], v160 offset:1024
	ds_read_b128 v[156:159], v160 offset:2048
	ds_read_b128 v[160:163], v160 offset:3072
	ds_read_b128 v[180:183], v164
	ds_read_b128 v[184:187], v164 offset:1024
	ds_read_b128 v[188:191], v164 offset:2048
	ds_read_b128 v[192:195], v164 offset:3072
	s_add_u32 s44, s44, 0x80000
	s_addc_u32 s45, s45, 0
	s_mov_b32 m0, s53
	v_lshl_add_u64 v[238:239], s[44:45], 0, v[136:137]
	ds_read_b128 v[196:199], v173 offset:32768
	ds_read_b128 v[200:203], v173 offset:33792
	ds_read_b128 v[204:207], v173 offset:34816
	ds_read_b128 v[208:211], v173 offset:35840
	ds_read_b128 v[212:215], v173 offset:36864
	ds_read_b128 v[216:219], v173 offset:37888
	ds_read_b128 v[224:227], v173 offset:38912
	ds_read_b128 v[228:231], v173 offset:39936
	global_load_lds_dwordx4 v[238:239], off
	v_lshl_add_u64 v[238:239], s[44:45], 0, v[132:133]
	s_mov_b32 m0, s57
	s_nop 0
	global_load_lds_dwordx4 v[238:239], off
	s_waitcnt vmcnt(8)
	s_waitcnt lgkmcnt(0)
	s_barrier
	s_waitcnt lgkmcnt(0)
	v_mfma_f32_16x16x32_bf16 v[126:129], v[148:151], v[196:199], v[126:129]
	v_mfma_f32_16x16x32_bf16 v[122:125], v[156:159], v[196:199], v[122:125]
	v_mfma_f32_16x16x32_bf16 v[110:113], v[148:151], v[204:207], v[110:113]
	v_mfma_f32_16x16x32_bf16 v[106:109], v[156:159], v[204:207], v[106:109]
	v_mfma_f32_16x16x32_bf16 v[94:97], v[148:151], v[212:215], v[94:97]
	v_mfma_f32_16x16x32_bf16 v[90:93], v[156:159], v[212:215], v[90:93]
	v_mfma_f32_16x16x32_bf16 v[78:81], v[148:151], v[224:227], v[78:81]
	v_mfma_f32_16x16x32_bf16 v[74:77], v[156:159], v[224:227], v[74:77]
	v_mfma_f32_16x16x32_bf16 v[126:129], v[152:155], v[200:203], v[126:129]
	v_mfma_f32_16x16x32_bf16 v[122:125], v[160:163], v[200:203], v[122:125]
	v_mfma_f32_16x16x32_bf16 v[110:113], v[152:155], v[208:211], v[110:113]
	v_mfma_f32_16x16x32_bf16 v[106:109], v[160:163], v[208:211], v[106:109]
	v_mfma_f32_16x16x32_bf16 v[94:97], v[152:155], v[216:219], v[94:97]
	v_mfma_f32_16x16x32_bf16 v[90:93], v[160:163], v[216:219], v[90:93]
	v_mfma_f32_16x16x32_bf16 v[78:81], v[152:155], v[228:231], v[78:81]
	v_mfma_f32_16x16x32_bf16 v[74:77], v[160:163], v[228:231], v[74:77]
	v_mfma_f32_16x16x32_bf16 v[118:121], v[180:183], v[196:199], v[118:121]
	v_mfma_f32_16x16x32_bf16 v[114:117], v[188:191], v[196:199], v[114:117]
	v_mfma_f32_16x16x32_bf16 v[102:105], v[180:183], v[204:207], v[102:105]
	v_mfma_f32_16x16x32_bf16 v[98:101], v[188:191], v[204:207], v[98:101]
	v_mfma_f32_16x16x32_bf16 v[86:89], v[180:183], v[212:215], v[86:89]
	v_mfma_f32_16x16x32_bf16 v[82:85], v[188:191], v[212:215], v[82:85]
	v_mfma_f32_16x16x32_bf16 v[70:73], v[180:183], v[224:227], v[70:73]
	v_mfma_f32_16x16x32_bf16 v[66:69], v[188:191], v[224:227], v[66:69]
	v_mfma_f32_16x16x32_bf16 v[118:121], v[184:187], v[200:203], v[118:121]
	v_mfma_f32_16x16x32_bf16 v[114:117], v[192:195], v[200:203], v[114:117]
	v_mfma_f32_16x16x32_bf16 v[102:105], v[184:187], v[208:211], v[102:105]
	v_mfma_f32_16x16x32_bf16 v[98:101], v[192:195], v[208:211], v[98:101]
	v_mfma_f32_16x16x32_bf16 v[86:89], v[184:187], v[216:219], v[86:89]
	v_mfma_f32_16x16x32_bf16 v[82:85], v[192:195], v[216:219], v[82:85]
	v_mfma_f32_16x16x32_bf16 v[70:73], v[184:187], v[228:231], v[70:73]
	v_mfma_f32_16x16x32_bf16 v[66:69], v[192:195], v[228:231], v[66:69]
	s_barrier
; #define PG8_STAGE(bufoff, gbase, voff) do { _Pragma("unroll") for (int _i = 0; _i < 2; ++_i) \
;         __builtin_amdgcn_global_load_lds((const unsigned*)((const char*)(gbase) + (voff)[_i]), (PG8_LAS unsigned*)(lds + (bufoff) + ldsw + _i * 8192), 16, 0, 0); } while (0)
; #define PG8_LDA(dst, b, h) do { _Pragma("unroll") for (int m = 0; m < 4; ++m) _Pragma("unroll") for (int k = 0; k < 2; ++k) dst[m][k] = *(const PG8_LAS bf16x8*)(lds + PG8_SA(b, h) + aoff + m * 2048 + k * 1024); } while (0)
; #define PG8_MMA(ai, bj, At, Bt) do { __builtin_amdgcn_s_setprio(1); _Pragma("unroll") for (int m = 0; m < 4; ++m) _Pragma("unroll") for (int n = 0; n < 2; ++n) _Pragma("unroll") for (int k = 0; k < 2; ++k) \
;         acc[ai][bj][m][n] = __builtin_amdgcn_mfma_f32_16x16x32_bf16(Bt[n][k], At[m][k], acc[ai][bj][m][n], 0, 0, 0); __builtin_amdgcn_s_setprio(0); } while (0)
; #define PG8_WAIT_V(n) asm volatile("s_waitcnt vmcnt(" #n ")" ::: "memory")
; #define PG8_WAIT_L(n) asm volatile("s_waitcnt lgkmcnt(" #n ")" ::: "memory")
; #define PG8_BAR __builtin_amdgcn_s_barrier()
; #define PG8_SCHED __builtin_amdgcn_sched_barrier(0)
; template <class Epi, class Sched, bool ALIGN_EPI = false, bool SP2 = false>
; __device__ __forceinline__ void gemm_phase(PG8_LAS unsigned char* lds, const Gemm g, const Sched& S, const Epi& E) {
;     ...
;             PG8_WAIT_V(8); PG8_WAIT_L(0); PG8_BAR; PG8_MMA(0, 0, At, B0); PG8_MMA(0, 1, At, B1); PG8_BAR; PG8_SCHED;
;             PG8_LDA(At, 1, 1); PG8_STAGE(PG8_SB(1, 0), b3, voffB); PG8_STAGE(PG8_SB(1, 1), b3 + hB, voffB); PG8_STAGE(PG8_SA(1, 0), a3, voffA);
;             PG8_WAIT_V(8); PG8_WAIT_L(0); PG8_BAR; PG8_MMA(1, 0, At, B0); PG8_MMA(1, 1, At, B1); PG8_BAR; PG8_SCHED;
;     ...
;         if constexpr (ALIGN_EPI) { if (wr == 0) PG8_BAR; }
	s_add_i32 s18, s18, s49
	v_lshl_add_u64 v[220:221], v[220:221], 0, s[20:21]
	s_mov_b32 m0, s18
	ds_read_b128 v[196:199], v173 offset:49152
	ds_read_b128 v[200:203], v173 offset:50176
	ds_read_b128 v[204:207], v173 offset:51200
	ds_read_b128 v[208:211], v173 offset:52224
	ds_read_b128 v[212:215], v173 offset:53248
	ds_read_b128 v[216:219], v173 offset:54272
	ds_read_b128 v[224:227], v173 offset:55296
	ds_read_b128 v[228:231], v173 offset:56320
	global_load_lds_dwordx4 v[220:221], off
	s_add_i32 m0, s18, 0x2000
	s_add_u32 s42, s42, 0x80080
	v_lshl_add_u64 v[220:221], v[232:233], 0, s[20:21]
	s_addc_u32 s43, s43, 0
	s_add_i32 s18, s19, s49
	global_load_lds_dwordx4 v[220:221], off
	v_lshl_add_u64 v[220:221], s[42:43], 0, v[134:135]
	s_mov_b32 m0, s18
	s_nop 0
	global_load_lds_dwordx4 v[220:221], off
	v_lshl_add_u64 v[220:221], s[42:43], 0, v[130:131]
	s_add_i32 m0, s18, 0x2000
	s_nop 0
	global_load_lds_dwordx4 v[220:221], off
	v_lshl_add_u64 v[220:221], v[234:235], 0, s[20:21]
	s_mov_b32 m0, s60
	s_nop 0
	global_load_lds_dwordx4 v[220:221], off
	v_lshl_add_u64 v[220:221], v[236:237], 0, s[20:21]
	s_mov_b32 m0, s61
	s_nop 0
	global_load_lds_dwordx4 v[220:221], off
	s_waitcnt vmcnt(8)
	s_waitcnt lgkmcnt(0)
	s_barrier
	s_waitcnt lgkmcnt(0)
	v_mfma_f32_16x16x32_bf16 v[62:65], v[148:151], v[196:199], v[62:65]
	v_mfma_f32_16x16x32_bf16 v[58:61], v[156:159], v[196:199], v[58:61]
	v_mfma_f32_16x16x32_bf16 v[46:49], v[148:151], v[204:207], v[46:49]
	v_mfma_f32_16x16x32_bf16 v[42:45], v[156:159], v[204:207], v[42:45]
	v_mfma_f32_16x16x32_bf16 v[30:33], v[148:151], v[212:215], v[30:33]
	v_mfma_f32_16x16x32_bf16 v[26:29], v[156:159], v[212:215], v[26:29]
	v_mfma_f32_16x16x32_bf16 v[14:17], v[148:151], v[224:227], v[14:17]
	v_mfma_f32_16x16x32_bf16 v[10:13], v[156:159], v[224:227], v[10:13]
	v_mfma_f32_16x16x32_bf16 v[62:65], v[152:155], v[200:203], v[62:65]
	v_mfma_f32_16x16x32_bf16 v[58:61], v[160:163], v[200:203], v[58:61]
	v_mfma_f32_16x16x32_bf16 v[46:49], v[152:155], v[208:211], v[46:49]
	v_mfma_f32_16x16x32_bf16 v[42:45], v[160:163], v[208:211], v[42:45]
	v_mfma_f32_16x16x32_bf16 v[30:33], v[152:155], v[216:219], v[30:33]
	v_mfma_f32_16x16x32_bf16 v[26:29], v[160:163], v[216:219], v[26:29]
	v_mfma_f32_16x16x32_bf16 v[14:17], v[152:155], v[228:231], v[14:17]
	v_mfma_f32_16x16x32_bf16 v[10:13], v[160:163], v[228:231], v[10:13]
	v_mfma_f32_16x16x32_bf16 v[54:57], v[180:183], v[196:199], v[54:57]
	v_mfma_f32_16x16x32_bf16 v[50:53], v[188:191], v[196:199], v[50:53]
	v_mfma_f32_16x16x32_bf16 v[38:41], v[180:183], v[204:207], v[38:41]
	v_mfma_f32_16x16x32_bf16 v[34:37], v[188:191], v[204:207], v[34:37]
	v_mfma_f32_16x16x32_bf16 v[22:25], v[180:183], v[212:215], v[22:25]
	v_mfma_f32_16x16x32_bf16 v[18:21], v[188:191], v[212:215], v[18:21]
	v_mfma_f32_16x16x32_bf16 v[6:9], v[180:183], v[224:227], v[6:9]
	v_mfma_f32_16x16x32_bf16 v[2:5], v[188:191], v[224:227], v[2:5]
	v_mfma_f32_16x16x32_bf16 v[54:57], v[184:187], v[200:203], v[54:57]
	v_mfma_f32_16x16x32_bf16 v[50:53], v[192:195], v[200:203], v[50:53]
	v_mfma_f32_16x16x32_bf16 v[38:41], v[184:187], v[208:211], v[38:41]
	v_mfma_f32_16x16x32_bf16 v[34:37], v[192:195], v[208:211], v[34:37]
	v_mfma_f32_16x16x32_bf16 v[22:25], v[184:187], v[216:219], v[22:25]
	v_mfma_f32_16x16x32_bf16 v[18:21], v[192:195], v[216:219], v[18:21]
	v_mfma_f32_16x16x32_bf16 v[6:9], v[184:187], v[228:231], v[6:9]
	v_mfma_f32_16x16x32_bf16 v[2:5], v[192:195], v[228:231], v[2:5]
	s_barrier
	s_add_i32 s72, s72, 2
	s_add_u32 s8, s8, 0x100
	s_addc_u32 s9, s9, 0
	s_add_u32 s70, s70, 0x100
	s_addc_u32 s71, s71, 0
	s_cmp_gt_u32 s72, 29
	s_cbranch_scc0 .LBB0_1048
	s_and_b64 vcc, exec, s[22:23]
	s_cbranch_vccz .LBB0_1051
	s_barrier

; #define PG8_WAIT_V(n) asm volatile("s_waitcnt vmcnt(" #n ")" ::: "memory")
; #define PG8_BAR __builtin_amdgcn_s_barrier()
; template <class Epi, class Sched, bool ALIGN_EPI = false, bool SP2 = false>
; __device__ __forceinline__ void gemm_phase(PG8_LAS unsigned char* lds, const Gemm g, const Sched& S, const Epi& E) {
;     ...
;     PG8_WAIT_V(0);
;     if constexpr (!ALIGN_EPI) { if (wr == 0) PG8_BAR; }
;     PG8_BAR;
; __device__ __forceinline__ void xcd_barrier(const XcdBarrier& b) {
;     asm volatile("s_waitcnt vmcnt(0)" ::: "memory");
;     __syncthreads();
;     if (threadIdx.x == 0) {
;         unsigned* bar = b.bar;
;         __builtin_amdgcn_s_waitcnt(0);
;         unsigned nloc = b.st[0], nx = b.st[1];
;         if (nloc == 0u) { xcd_barrier_complete(bar, b.x, nloc, nx); b.st[0] = nloc; b.st[1] = nx; }
.LBB0_1055:
	s_setprio 0
	s_waitcnt vmcnt(0)
	s_barrier
	s_and_saveexec_b64 s[0:1], s[86:87]
	s_xor_b64 s[0:1], exec, s[0:1]
	s_cbranch_execz .LBB0_1108
	s_add_i32 s6, 0, 0x20040
	v_mov_b32_e32 v1, s6
	s_waitcnt vmcnt(0) expcnt(0) lgkmcnt(0)
	ds_read_b32 v3, v1
	s_add_i32 s6, 0, 0x20044
	v_mov_b32_e32 v1, s6
	ds_read_b32 v1, v1
	s_waitcnt lgkmcnt(1)
	v_cmp_ne_u32_e32 vcc, 0, v3
	s_cbranch_vccnz .LBB0_1071
	s_load_dwordx2 s[14:15], s[84:85], 0x0
	s_load_dword s9, s[84:85], 0x8
	s_add_u32 s6, s30, 0x1000
	s_addc_u32 s7, s31, 0
	s_add_u32 s8, s30, 0x1100
	s_waitcnt lgkmcnt(0)
	s_mul_i32 s33, s15, s14
	s_mul_i32 s33, s33, s9
	s_addc_u32 s9, s31, 0
	s_add_u32 s14, s30, 0x1200
	s_addc_u32 s15, s31, 0
	s_add_u32 s16, s30, 0x1300
	s_addc_u32 s17, s31, 0
	s_mov_b32 s36, 1
	v_mov_b32_e32 v17, 0
	s_branch .LBB0_1059

; #define PG8_STAGE(bufoff, gbase, voff) do { _Pragma("unroll") for (int _i = 0; _i < 2; ++_i) \
;         __builtin_amdgcn_global_load_lds((const unsigned*)((const char*)(gbase) + (voff)[_i]), (PG8_LAS unsigned*)(lds + (bufoff) + ldsw + _i * 8192), 16, 0, 0); } while (0)
; #define PG8_WAIT_V(n) asm volatile("s_waitcnt vmcnt(" #n ")" ::: "memory")
; #define PG8_BAR __builtin_amdgcn_s_barrier()
; template <class Epi, class Sched, bool ALIGN_EPI = false, bool SP2 = false>
; __device__ __forceinline__ void gemm_phase(PG8_LAS unsigned char* lds, const Gemm g, const Sched& S, const Epi& E) {
;     ...
;     for (int i = 0; i < 2; ++i) { int R, C; stage_rc(tid * 16 + i * 8192, R, C); const int Rb = Epi::PERM ? ((R & ~31) + perm32(R & 31)) : R;
;         voffA[i] = (unsigned)(R * g.lda + C) * 2u; voffB[i] = (unsigned)(Rb * g.ldb + C) * 2u; }
;     ...
;         PG8_WAIT_V(2); PG8_BAR;
;         PG8_STAGE(PG8_SB(1, 0), cB + kstep, voffB); PG8_STAGE(PG8_SA(1, 0), cA + kstep, voffA); PG8_STAGE(PG8_SB(1, 1), cB + hB + kstep, voffB);
;         PG8_WAIT_V(6); PG8_BAR;
.LBB0_1113:
	s_add_u32 s12, s6, 0x15800000
	s_addc_u32 s13, s7, 0
	s_add_u32 s14, s6, 0x2000000
	s_mov_b64 s[16:17], 0x80
	s_addc_u32 s15, s7, 0
	s_and_b32 s51, s4, 3
	s_add_i32 m0, s46, 0x18000
	v_lshl_add_u64 v[8:9], v[8:9], 0, s[16:17]
	s_lshl_b32 s4, s5, 13
	s_lshl_b32 s18, s51, 12
	s_waitcnt vmcnt(2)
	s_barrier
	global_load_lds_dwordx4 v[8:9], off
	v_lshl_add_u64 v[4:5], v[4:5], 0, s[16:17]
	s_add_i32 m0, s46, 0x1a000
	s_add_i32 s52, s46, 0x8000
	s_add_i32 s53, s46, 0xa000
	global_load_lds_dwordx4 v[4:5], off
	v_lshl_add_u64 v[2:3], v[2:3], 0, s[16:17]
	s_mov_b32 m0, s52
	s_add_u32 s6, s36, 0x160080
	global_load_lds_dwordx4 v[2:3], off
	v_lshl_add_u64 v[2:3], v[6:7], 0, s[16:17]
	s_mov_b32 m0, s53
	s_addc_u32 s7, s37, 0
	global_load_lds_dwordx4 v[2:3], off
	s_add_i32 m0, s46, 0x1c000
	v_lshl_add_u64 v[2:3], s[6:7], 0, v[156:157]
	global_load_lds_dwordx4 v[2:3], off
	v_lshl_add_u64 v[2:3], s[6:7], 0, v[160:161]
	s_add_i32 m0, s46, 0x1e000
	s_mov_b64 s[6:7], 0x160080
	global_load_lds_dwordx4 v[2:3], off
	v_bfe_u32 v3, v10, 4, 2
	v_and_b32_e32 v2, 15, v10
	v_lshlrev_b32_e32 v5, 4, v3
	v_lshl_or_b32 v1, s5, 6, v2
	v_lshl_or_b32 v2, v2, 6, v5
	v_lshlrev_b32_e32 v5, 2, v10
	v_and_b32_e32 v5, 32, v5
	v_lshlrev_b32_e32 v4, 3, v3
	v_bitop3_b32 v6, v2, s4, v5 bitop3:0xde
	v_bitop3_b32 v188, v2, s18, v5 bitop3:0xde
	v_cmp_eq_u32_e64 s[4:5], 0, v3
	v_lshrrev_b32_e32 v3, 1, v11
	v_mul_lo_u32 v2, v12, s9
	v_mad_u64_u32 v[2:3], s[38:39], v3, s22, v[2:3]
	v_or_b32_e32 v2, v2, v13
	v_add_lshl_u32 v2, v2, v14, 1
	v_mov_b32_e32 v3, v157
	v_lshl_add_u64 v[162:163], v[2:3], 0, s[6:7]
	v_lshrrev_b32_e32 v3, 1, v15
	v_mul_lo_u32 v2, v16, s9
	s_cmpk_lt_u32 s8, 0x100
	v_mad_u64_u32 v[2:3], s[8:9], v3, s22, v[2:3]
	s_waitcnt vmcnt(6)
	v_or_b32_e32 v2, v2, v17
	s_cselect_b64 s[20:21], -1, 0
	v_add_lshl_u32 v2, v2, v18, 1
	v_mov_b32_e32 v3, v157
	s_add_i32 s55, 0, 0x10000
	s_add_i32 s56, 0, 0x14000
	v_lshl_or_b32 v189, s51, 5, v4
	s_waitcnt lgkmcnt(0)
	s_ashr_i32 s54, s50, 31
	v_lshl_add_u64 v[164:165], v[2:3], 0, s[6:7]
	v_mov_b64_e32 v[166:167], 0x200
	v_mov_b64_e32 v[168:169], 0x1ff
	v_add_u32_e32 v190, s55, v188
	v_add_u32_e32 v191, s56, v188
	v_add_u32_e32 v192, 0, v6
	v_mbcnt_hi_u32_b32 v193, -1, v222
	s_mov_b32 s57, 0
	s_barrier
	v_readfirstlane_b32 s99, v0
	s_nop 3
	s_lshr_b32 s99, s99, 8
	s_cmp_eq_u32 s99, 0
	s_cbranch_scc1 .Lprio_skip_7
	s_setprio 1

; #define PG8_STAGE(bufoff, gbase, voff) do { _Pragma("unroll") for (int _i = 0; _i < 2; ++_i) \
;         __builtin_amdgcn_global_load_lds((const unsigned*)((const char*)(gbase) + (voff)[_i]), (PG8_LAS unsigned*)(lds + (bufoff) + ldsw + _i * 8192), 16, 0, 0); } while (0)
; #define PG8_LDA(dst, b, h) do { _Pragma("unroll") for (int m = 0; m < 4; ++m) _Pragma("unroll") for (int k = 0; k < 2; ++k) dst[m][k] = *(const PG8_LAS bf16x8*)(lds + PG8_SA(b, h) + aoff + m * 2048 + k * 1024); } while (0)
; #define PG8_LDB(dst, b, h) do { _Pragma("unroll") for (int n = 0; n < 2; ++n) _Pragma("unroll") for (int k = 0; k < 2; ++k) dst[n][k] = *(const PG8_LAS bf16x8*)(lds + PG8_SB(b, h) + boff + n * 2048 + k * 1024); } while (0)
; #define PG8_MMA(ai, bj, At, Bt) do { __builtin_amdgcn_s_setprio(1); _Pragma("unroll") for (int m = 0; m < 4; ++m) _Pragma("unroll") for (int n = 0; n < 2; ++n) _Pragma("unroll") for (int k = 0; k < 2; ++k) \
;         acc[ai][bj][m][n] = __builtin_amdgcn_mfma_f32_16x16x32_bf16(Bt[n][k], At[m][k], acc[ai][bj][m][n], 0, 0, 0); __builtin_amdgcn_s_setprio(0); } while (0)
; #define PG8_WAIT_V(n) asm volatile("s_waitcnt vmcnt(" #n ")" ::: "memory")
; #define PG8_WAIT_L(n) asm volatile("s_waitcnt lgkmcnt(" #n ")" ::: "memory")
; #define PG8_BAR __builtin_amdgcn_s_barrier()
; #define PG8_SCHED __builtin_amdgcn_sched_barrier(0)
; template <class Epi, class Sched, bool ALIGN_EPI = false, bool SP2 = false>
; __device__ __forceinline__ void gemm_phase(PG8_LAS unsigned char* lds, const Gemm g, const Sched& S, const Epi& E) {
;     ...
;             PG8_LDB(B0, 0, 0); PG8_LDB(B1, 0, 1); PG8_SCHED; PG8_LDA(At, 0, 0); PG8_STAGE(PG8_SA(1, 1), a1 + hA, voffA);
;             PG8_WAIT_V(8); PG8_WAIT_L(0); PG8_BAR; PG8_MMA(0, 0, At, B0); PG8_MMA(0, 1, At, B1); PG8_BAR; PG8_SCHED;
;             PG8_LDA(At, 0, 1); PG8_STAGE(PG8_SB(0, 0), b2, voffB); PG8_STAGE(PG8_SB(0, 1), b2 + hB, voffB); PG8_STAGE(PG8_SA(0, 0), a2, voffA);
;             PG8_WAIT_V(8); PG8_WAIT_L(0); PG8_BAR; PG8_MMA(1, 0, At, B0); PG8_MMA(1, 1, At, B1); PG8_BAR; PG8_SCHED;
.LBB0_1127:
	ds_read_b128 v[130:133], v190
	ds_read_b128 v[134:137], v190 offset:1024
	ds_read_b128 v[138:141], v190 offset:2048
	ds_read_b128 v[142:145], v190 offset:3072
	ds_read_b128 v[146:149], v191
	ds_read_b128 v[150:153], v191 offset:1024
	ds_read_b128 v[170:173], v191 offset:2048
	ds_read_b128 v[174:177], v191 offset:3072
	s_add_u32 s36, s24, 0x100
	s_addc_u32 s37, s25, 0
	s_cmpk_eq_i32 s63, 0x54
	s_cselect_b32 s41, s9, s37
	s_cselect_b32 s40, s8, s36
	s_cselect_b32 s39, s23, s62
	s_cselect_b32 s38, s22, s61
	v_lshl_add_u64 v[186:187], s[24:25], 0, v[162:163]
	s_add_i32 m0, s46, 0xc000
	ds_read_b128 v[178:181], v192
	ds_read_b128 v[182:185], v192 offset:1024
	ds_read_b128 v[194:197], v192 offset:2048
	ds_read_b128 v[198:201], v192 offset:3072
	ds_read_b128 v[202:205], v192 offset:4096
	ds_read_b128 v[206:209], v192 offset:5120
	ds_read_b128 v[210:213], v192 offset:6144
	ds_read_b128 v[214:217], v192 offset:7168
	global_load_lds_dwordx4 v[186:187], off
	v_lshl_add_u64 v[186:187], s[24:25], 0, v[164:165]
	s_add_i32 m0, s46, 0xe000
	s_nop 0
	global_load_lds_dwordx4 v[186:187], off
	s_waitcnt vmcnt(8)
	s_waitcnt lgkmcnt(0)
	s_barrier
	s_waitcnt lgkmcnt(0)
	v_mfma_f32_16x16x32_bf16 v[126:129], v[130:133], v[178:181], v[126:129]
	v_mfma_f32_16x16x32_bf16 v[122:125], v[138:141], v[178:181], v[122:125]
	v_mfma_f32_16x16x32_bf16 v[110:113], v[130:133], v[194:197], v[110:113]
	v_mfma_f32_16x16x32_bf16 v[106:109], v[138:141], v[194:197], v[106:109]
	v_mfma_f32_16x16x32_bf16 v[94:97], v[130:133], v[202:205], v[94:97]
	v_mfma_f32_16x16x32_bf16 v[90:93], v[138:141], v[202:205], v[90:93]
	v_mfma_f32_16x16x32_bf16 v[78:81], v[130:133], v[210:213], v[78:81]
	v_mfma_f32_16x16x32_bf16 v[74:77], v[138:141], v[210:213], v[74:77]
	v_mfma_f32_16x16x32_bf16 v[126:129], v[134:137], v[182:185], v[126:129]
	v_mfma_f32_16x16x32_bf16 v[122:125], v[142:145], v[182:185], v[122:125]
	v_mfma_f32_16x16x32_bf16 v[110:113], v[134:137], v[198:201], v[110:113]
	v_mfma_f32_16x16x32_bf16 v[106:109], v[142:145], v[198:201], v[106:109]
	v_mfma_f32_16x16x32_bf16 v[94:97], v[134:137], v[206:209], v[94:97]
	v_mfma_f32_16x16x32_bf16 v[90:93], v[142:145], v[206:209], v[90:93]
	v_mfma_f32_16x16x32_bf16 v[78:81], v[134:137], v[214:217], v[78:81]
	v_mfma_f32_16x16x32_bf16 v[74:77], v[142:145], v[214:217], v[74:77]
	v_mfma_f32_16x16x32_bf16 v[118:121], v[146:149], v[178:181], v[118:121]
	v_mfma_f32_16x16x32_bf16 v[114:117], v[170:173], v[178:181], v[114:117]
	v_mfma_f32_16x16x32_bf16 v[102:105], v[146:149], v[194:197], v[102:105]
	v_mfma_f32_16x16x32_bf16 v[98:101], v[170:173], v[194:197], v[98:101]
	v_mfma_f32_16x16x32_bf16 v[86:89], v[146:149], v[202:205], v[86:89]
	v_mfma_f32_16x16x32_bf16 v[82:85], v[170:173], v[202:205], v[82:85]
	v_mfma_f32_16x16x32_bf16 v[70:73], v[146:149], v[210:213], v[70:73]
	v_mfma_f32_16x16x32_bf16 v[66:69], v[170:173], v[210:213], v[66:69]
	v_mfma_f32_16x16x32_bf16 v[118:121], v[150:153], v[182:185], v[118:121]
	v_mfma_f32_16x16x32_bf16 v[114:117], v[174:177], v[182:185], v[114:117]
	v_mfma_f32_16x16x32_bf16 v[102:105], v[150:153], v[198:201], v[102:105]
	v_mfma_f32_16x16x32_bf16 v[98:101], v[174:177], v[198:201], v[98:101]
	v_mfma_f32_16x16x32_bf16 v[86:89], v[150:153], v[206:209], v[86:89]
	v_mfma_f32_16x16x32_bf16 v[82:85], v[174:177], v[206:209], v[82:85]
	v_mfma_f32_16x16x32_bf16 v[70:73], v[150:153], v[214:217], v[70:73]
	v_mfma_f32_16x16x32_bf16 v[66:69], v[174:177], v[214:217], v[66:69]
	s_barrier
	s_add_i32 s18, s55, s45
	v_lshl_add_u64 v[186:187], s[38:39], 0, v[156:157]
	s_mov_b32 m0, s18
	ds_read_b128 v[178:181], v192 offset:16384
	ds_read_b128 v[182:185], v192 offset:17408
	ds_read_b128 v[194:197], v192 offset:18432
	ds_read_b128 v[198:201], v192 offset:19456
	ds_read_b128 v[202:205], v192 offset:20480
	ds_read_b128 v[206:209], v192 offset:21504
	ds_read_b128 v[210:213], v192 offset:22528
	ds_read_b128 v[214:217], v192 offset:23552
	global_load_lds_dwordx4 v[186:187], off
	s_add_i32 m0, s18, 0x2000
	s_add_u32 s24, s38, 0x160000
	v_lshl_add_u64 v[218:219], s[38:39], 0, v[160:161]
	s_addc_u32 s25, s39, 0
	s_add_i32 s18, s56, s45
	global_load_lds_dwordx4 v[218:219], off
	v_lshl_add_u64 v[220:221], s[24:25], 0, v[156:157]
	s_mov_b32 m0, s18
	v_lshl_add_u64 v[224:225], s[40:41], 0, v[158:159]
	global_load_lds_dwordx4 v[220:221], off
	v_lshl_add_u64 v[220:221], s[24:25], 0, v[160:161]
	s_add_i32 m0, s18, 0x2000
	s_nop 0
	global_load_lds_dwordx4 v[220:221], off
	v_lshl_add_u64 v[220:221], s[40:41], 0, v[154:155]
	s_mov_b32 m0, s46
	s_nop 0
	global_load_lds_dwordx4 v[220:221], off
	s_mov_b32 m0, s47
	s_nop 0
	global_load_lds_dwordx4 v[224:225], off
	s_waitcnt vmcnt(8)
	s_waitcnt lgkmcnt(0)
	s_barrier
; #define PG8_STAGE(bufoff, gbase, voff) do { _Pragma("unroll") for (int _i = 0; _i < 2; ++_i) \
;         __builtin_amdgcn_global_load_lds((const unsigned*)((const char*)(gbase) + (voff)[_i]), (PG8_LAS unsigned*)(lds + (bufoff) + ldsw + _i * 8192), 16, 0, 0); } while (0)
; #define PG8_LDA(dst, b, h) do { _Pragma("unroll") for (int m = 0; m < 4; ++m) _Pragma("unroll") for (int k = 0; k < 2; ++k) dst[m][k] = *(const PG8_LAS bf16x8*)(lds + PG8_SA(b, h) + aoff + m * 2048 + k * 1024); } while (0)
; #define PG8_LDB(dst, b, h) do { _Pragma("unroll") for (int n = 0; n < 2; ++n) _Pragma("unroll") for (int k = 0; k < 2; ++k) dst[n][k] = *(const PG8_LAS bf16x8*)(lds + PG8_SB(b, h) + boff + n * 2048 + k * 1024); } while (0)
; #define PG8_MMA(ai, bj, At, Bt) do { __builtin_amdgcn_s_setprio(1); _Pragma("unroll") for (int m = 0; m < 4; ++m) _Pragma("unroll") for (int n = 0; n < 2; ++n) _Pragma("unroll") for (int k = 0; k < 2; ++k) \
;         acc[ai][bj][m][n] = __builtin_amdgcn_mfma_f32_16x16x32_bf16(Bt[n][k], At[m][k], acc[ai][bj][m][n], 0, 0, 0); __builtin_amdgcn_s_setprio(0); } while (0)
; #define PG8_WAIT_V(n) asm volatile("s_waitcnt vmcnt(" #n ")" ::: "memory")
; #define PG8_WAIT_L(n) asm volatile("s_waitcnt lgkmcnt(" #n ")" ::: "memory")
; #define PG8_BAR __builtin_amdgcn_s_barrier()
; #define PG8_SCHED __builtin_amdgcn_sched_barrier(0)
; template <class Epi, class Sched, bool ALIGN_EPI = false, bool SP2 = false>
; __device__ __forceinline__ void gemm_phase(PG8_LAS unsigned char* lds, const Gemm g, const Sched& S, const Epi& E) {
;     ...
;             PG8_WAIT_V(8); PG8_WAIT_L(0); PG8_BAR; PG8_MMA(1, 0, At, B0); PG8_MMA(1, 1, At, B1); PG8_BAR; PG8_SCHED;
;             PG8_LDB(B0, 1, 0); PG8_LDB(B1, 1, 1); PG8_SCHED; PG8_LDA(At, 1, 0); PG8_STAGE(PG8_SA(0, 1), a2 + hA, voffA);
;             PG8_WAIT_V(8); PG8_WAIT_L(0); PG8_BAR; PG8_MMA(0, 0, At, B0); PG8_MMA(0, 1, At, B1); PG8_BAR; PG8_SCHED;
	s_waitcnt lgkmcnt(0)
	v_mfma_f32_16x16x32_bf16 v[62:65], v[130:133], v[178:181], v[62:65]
	v_mfma_f32_16x16x32_bf16 v[58:61], v[138:141], v[178:181], v[58:61]
	v_mfma_f32_16x16x32_bf16 v[46:49], v[130:133], v[194:197], v[46:49]
	v_mfma_f32_16x16x32_bf16 v[42:45], v[138:141], v[194:197], v[42:45]
	v_mfma_f32_16x16x32_bf16 v[30:33], v[130:133], v[202:205], v[30:33]
	v_mfma_f32_16x16x32_bf16 v[26:29], v[138:141], v[202:205], v[26:29]
	v_mfma_f32_16x16x32_bf16 v[14:17], v[130:133], v[210:213], v[14:17]
	v_mfma_f32_16x16x32_bf16 v[10:13], v[138:141], v[210:213], v[10:13]
	v_mfma_f32_16x16x32_bf16 v[62:65], v[134:137], v[182:185], v[62:65]
	v_mfma_f32_16x16x32_bf16 v[58:61], v[142:145], v[182:185], v[58:61]
	v_mfma_f32_16x16x32_bf16 v[46:49], v[134:137], v[198:201], v[46:49]
	v_mfma_f32_16x16x32_bf16 v[42:45], v[142:145], v[198:201], v[42:45]
	v_mfma_f32_16x16x32_bf16 v[30:33], v[134:137], v[206:209], v[30:33]
	v_mfma_f32_16x16x32_bf16 v[26:29], v[142:145], v[206:209], v[26:29]
	v_mfma_f32_16x16x32_bf16 v[14:17], v[134:137], v[214:217], v[14:17]
	v_mfma_f32_16x16x32_bf16 v[10:13], v[142:145], v[214:217], v[10:13]
	v_mfma_f32_16x16x32_bf16 v[54:57], v[146:149], v[178:181], v[54:57]
	v_mfma_f32_16x16x32_bf16 v[50:53], v[170:173], v[178:181], v[50:53]
	v_mfma_f32_16x16x32_bf16 v[38:41], v[146:149], v[194:197], v[38:41]
	v_mfma_f32_16x16x32_bf16 v[34:37], v[170:173], v[194:197], v[34:37]
	v_mfma_f32_16x16x32_bf16 v[22:25], v[146:149], v[202:205], v[22:25]
	v_mfma_f32_16x16x32_bf16 v[18:21], v[170:173], v[202:205], v[18:21]
	v_mfma_f32_16x16x32_bf16 v[6:9], v[146:149], v[210:213], v[6:9]
	v_mfma_f32_16x16x32_bf16 v[2:5], v[170:173], v[210:213], v[2:5]
	v_mfma_f32_16x16x32_bf16 v[54:57], v[150:153], v[182:185], v[54:57]
	v_mfma_f32_16x16x32_bf16 v[50:53], v[174:177], v[182:185], v[50:53]
	v_mfma_f32_16x16x32_bf16 v[38:41], v[150:153], v[198:201], v[38:41]
	v_mfma_f32_16x16x32_bf16 v[34:37], v[174:177], v[198:201], v[34:37]
	v_mfma_f32_16x16x32_bf16 v[22:25], v[150:153], v[206:209], v[22:25]
	v_mfma_f32_16x16x32_bf16 v[18:21], v[174:177], v[206:209], v[18:21]
	v_mfma_f32_16x16x32_bf16 v[6:9], v[150:153], v[214:217], v[6:9]
	v_mfma_f32_16x16x32_bf16 v[2:5], v[174:177], v[214:217], v[2:5]
	s_barrier
	s_add_i32 s18, 0, 0x18000
	s_add_i32 s19, 0, 0x1c000
	v_add_u32_e32 v142, s18, v188
	v_add_u32_e32 v174, s19, v188
	ds_read_b128 v[130:133], v142
	ds_read_b128 v[134:137], v142 offset:1024
	ds_read_b128 v[138:141], v142 offset:2048
	ds_read_b128 v[142:145], v142 offset:3072
	ds_read_b128 v[146:149], v174
	ds_read_b128 v[150:153], v174 offset:1024
	ds_read_b128 v[170:173], v174 offset:2048
	ds_read_b128 v[174:177], v174 offset:3072
	s_add_u32 s24, s40, 0x160000
	s_addc_u32 s25, s41, 0
	s_mov_b32 m0, s48
	v_lshl_add_u64 v[226:227], s[24:25], 0, v[154:155]
	ds_read_b128 v[178:181], v192 offset:32768
	ds_read_b128 v[182:185], v192 offset:33792
	ds_read_b128 v[194:197], v192 offset:34816
	ds_read_b128 v[198:201], v192 offset:35840
	ds_read_b128 v[202:205], v192 offset:36864
	ds_read_b128 v[206:209], v192 offset:37888
	ds_read_b128 v[210:213], v192 offset:38912
	ds_read_b128 v[214:217], v192 offset:39936
	global_load_lds_dwordx4 v[226:227], off
	v_lshl_add_u64 v[226:227], s[24:25], 0, v[158:159]
	s_mov_b32 m0, s49
	s_nop 0
	global_load_lds_dwordx4 v[226:227], off
	s_waitcnt vmcnt(8)
	s_waitcnt lgkmcnt(0)
	s_barrier
	s_waitcnt lgkmcnt(0)
	v_mfma_f32_16x16x32_bf16 v[126:129], v[130:133], v[178:181], v[126:129]
	v_mfma_f32_16x16x32_bf16 v[122:125], v[138:141], v[178:181], v[122:125]
	v_mfma_f32_16x16x32_bf16 v[110:113], v[130:133], v[194:197], v[110:113]
	v_mfma_f32_16x16x32_bf16 v[106:109], v[138:141], v[194:197], v[106:109]
	v_mfma_f32_16x16x32_bf16 v[94:97], v[130:133], v[202:205], v[94:97]
	v_mfma_f32_16x16x32_bf16 v[90:93], v[138:141], v[202:205], v[90:93]
	v_mfma_f32_16x16x32_bf16 v[78:81], v[130:133], v[210:213], v[78:81]
	v_mfma_f32_16x16x32_bf16 v[74:77], v[138:141], v[210:213], v[74:77]
	v_mfma_f32_16x16x32_bf16 v[126:129], v[134:137], v[182:185], v[126:129]
	v_mfma_f32_16x16x32_bf16 v[122:125], v[142:145], v[182:185], v[122:125]
	v_mfma_f32_16x16x32_bf16 v[110:113], v[134:137], v[198:201], v[110:113]
	v_mfma_f32_16x16x32_bf16 v[106:109], v[142:145], v[198:201], v[106:109]
	v_mfma_f32_16x16x32_bf16 v[94:97], v[134:137], v[206:209], v[94:97]
	v_mfma_f32_16x16x32_bf16 v[90:93], v[142:145], v[206:209], v[90:93]
	v_mfma_f32_16x16x32_bf16 v[78:81], v[134:137], v[214:217], v[78:81]
	v_mfma_f32_16x16x32_bf16 v[74:77], v[142:145], v[214:217], v[74:77]
	v_mfma_f32_16x16x32_bf16 v[118:121], v[146:149], v[178:181], v[118:121]
	v_mfma_f32_16x16x32_bf16 v[114:117], v[170:173], v[178:181], v[114:117]
	v_mfma_f32_16x16x32_bf16 v[102:105], v[146:149], v[194:197], v[102:105]
	v_mfma_f32_16x16x32_bf16 v[98:101], v[170:173], v[194:197], v[98:101]
	v_mfma_f32_16x16x32_bf16 v[86:89], v[146:149], v[202:205], v[86:89]
	v_mfma_f32_16x16x32_bf16 v[82:85], v[170:173], v[202:205], v[82:85]
	v_mfma_f32_16x16x32_bf16 v[70:73], v[146:149], v[210:213], v[70:73]
	v_mfma_f32_16x16x32_bf16 v[66:69], v[170:173], v[210:213], v[66:69]
	v_mfma_f32_16x16x32_bf16 v[118:121], v[150:153], v[182:185], v[118:121]
	v_mfma_f32_16x16x32_bf16 v[114:117], v[174:177], v[182:185], v[114:117]
	v_mfma_f32_16x16x32_bf16 v[102:105], v[150:153], v[198:201], v[102:105]
	v_mfma_f32_16x16x32_bf16 v[98:101], v[174:177], v[198:201], v[98:101]
	v_mfma_f32_16x16x32_bf16 v[86:89], v[150:153], v[206:209], v[86:89]
	v_mfma_f32_16x16x32_bf16 v[82:85], v[174:177], v[206:209], v[82:85]
	v_mfma_f32_16x16x32_bf16 v[70:73], v[150:153], v[214:217], v[70:73]
	v_mfma_f32_16x16x32_bf16 v[66:69], v[174:177], v[214:217], v[66:69]
	s_barrier
; #define PG8_STAGE(bufoff, gbase, voff) do { _Pragma("unroll") for (int _i = 0; _i < 2; ++_i) \
;         __builtin_amdgcn_global_load_lds((const unsigned*)((const char*)(gbase) + (voff)[_i]), (PG8_LAS unsigned*)(lds + (bufoff) + ldsw + _i * 8192), 16, 0, 0); } while (0)
; #define PG8_LDA(dst, b, h) do { _Pragma("unroll") for (int m = 0; m < 4; ++m) _Pragma("unroll") for (int k = 0; k < 2; ++k) dst[m][k] = *(const PG8_LAS bf16x8*)(lds + PG8_SA(b, h) + aoff + m * 2048 + k * 1024); } while (0)
; #define PG8_MMA(ai, bj, At, Bt) do { __builtin_amdgcn_s_setprio(1); _Pragma("unroll") for (int m = 0; m < 4; ++m) _Pragma("unroll") for (int n = 0; n < 2; ++n) _Pragma("unroll") for (int k = 0; k < 2; ++k) \
;         acc[ai][bj][m][n] = __builtin_amdgcn_mfma_f32_16x16x32_bf16(Bt[n][k], At[m][k], acc[ai][bj][m][n], 0, 0, 0); __builtin_amdgcn_s_setprio(0); } while (0)
; #define PG8_WAIT_V(n) asm volatile("s_waitcnt vmcnt(" #n ")" ::: "memory")
; #define PG8_WAIT_L(n) asm volatile("s_waitcnt lgkmcnt(" #n ")" ::: "memory")
; #define PG8_BAR __builtin_amdgcn_s_barrier()
; #define PG8_SCHED __builtin_amdgcn_sched_barrier(0)
; template <class Epi, class Sched, bool ALIGN_EPI = false, bool SP2 = false>
; __device__ __forceinline__ void gemm_phase(PG8_LAS unsigned char* lds, const Gemm g, const Sched& S, const Epi& E) {
;     ...
;             PG8_LDA(At, 1, 1); PG8_STAGE(PG8_SB(1, 0), b3, voffB); PG8_STAGE(PG8_SB(1, 1), b3 + hB, voffB); PG8_STAGE(PG8_SA(1, 0), a3, voffA);
;             PG8_WAIT_V(8); PG8_WAIT_L(0); PG8_BAR; PG8_MMA(1, 0, At, B0); PG8_MMA(1, 1, At, B1); PG8_BAR; PG8_SCHED;
;     ...
;         if constexpr (ALIGN_EPI) { if (wr == 0) PG8_BAR; }
	s_add_i32 s18, s18, s45
	v_lshl_add_u64 v[186:187], v[186:187], 0, s[16:17]
	s_mov_b32 m0, s18
	ds_read_b128 v[178:181], v192 offset:49152
	ds_read_b128 v[182:185], v192 offset:50176
	ds_read_b128 v[194:197], v192 offset:51200
	ds_read_b128 v[198:201], v192 offset:52224
	ds_read_b128 v[202:205], v192 offset:53248
	ds_read_b128 v[206:209], v192 offset:54272
	ds_read_b128 v[210:213], v192 offset:55296
	ds_read_b128 v[214:217], v192 offset:56320
	global_load_lds_dwordx4 v[186:187], off
	s_add_i32 m0, s18, 0x2000
	s_add_u32 s24, s38, 0x160080
	v_lshl_add_u64 v[186:187], v[218:219], 0, s[16:17]
	s_addc_u32 s25, s39, 0
	s_add_i32 s18, s19, s45
	global_load_lds_dwordx4 v[186:187], off
	v_lshl_add_u64 v[186:187], s[24:25], 0, v[156:157]
	s_mov_b32 m0, s18
	s_nop 0
	global_load_lds_dwordx4 v[186:187], off
	v_lshl_add_u64 v[186:187], s[24:25], 0, v[160:161]
	s_add_i32 m0, s18, 0x2000
	s_nop 0
	global_load_lds_dwordx4 v[186:187], off
	v_lshl_add_u64 v[186:187], v[220:221], 0, s[16:17]
	s_mov_b32 m0, s52
	s_nop 0
	global_load_lds_dwordx4 v[186:187], off
	v_lshl_add_u64 v[186:187], v[224:225], 0, s[16:17]
	s_mov_b32 m0, s53
	s_nop 0
	global_load_lds_dwordx4 v[186:187], off
	s_waitcnt vmcnt(8)
	s_waitcnt lgkmcnt(0)
	s_barrier
	s_waitcnt lgkmcnt(0)
	v_mfma_f32_16x16x32_bf16 v[62:65], v[130:133], v[178:181], v[62:65]
	v_mfma_f32_16x16x32_bf16 v[58:61], v[138:141], v[178:181], v[58:61]
	v_mfma_f32_16x16x32_bf16 v[46:49], v[130:133], v[194:197], v[46:49]
	v_mfma_f32_16x16x32_bf16 v[42:45], v[138:141], v[194:197], v[42:45]
	v_mfma_f32_16x16x32_bf16 v[30:33], v[130:133], v[202:205], v[30:33]
	v_mfma_f32_16x16x32_bf16 v[26:29], v[138:141], v[202:205], v[26:29]
	v_mfma_f32_16x16x32_bf16 v[14:17], v[130:133], v[210:213], v[14:17]
	v_mfma_f32_16x16x32_bf16 v[10:13], v[138:141], v[210:213], v[10:13]
	v_mfma_f32_16x16x32_bf16 v[62:65], v[134:137], v[182:185], v[62:65]
	v_mfma_f32_16x16x32_bf16 v[58:61], v[142:145], v[182:185], v[58:61]
	v_mfma_f32_16x16x32_bf16 v[46:49], v[134:137], v[198:201], v[46:49]
	v_mfma_f32_16x16x32_bf16 v[42:45], v[142:145], v[198:201], v[42:45]
	v_mfma_f32_16x16x32_bf16 v[30:33], v[134:137], v[206:209], v[30:33]
	v_mfma_f32_16x16x32_bf16 v[26:29], v[142:145], v[206:209], v[26:29]
	v_mfma_f32_16x16x32_bf16 v[14:17], v[134:137], v[214:217], v[14:17]
	v_mfma_f32_16x16x32_bf16 v[10:13], v[142:145], v[214:217], v[10:13]
	v_mfma_f32_16x16x32_bf16 v[54:57], v[146:149], v[178:181], v[54:57]
	v_mfma_f32_16x16x32_bf16 v[50:53], v[170:173], v[178:181], v[50:53]
	v_mfma_f32_16x16x32_bf16 v[38:41], v[146:149], v[194:197], v[38:41]
	v_mfma_f32_16x16x32_bf16 v[34:37], v[170:173], v[194:197], v[34:37]
	v_mfma_f32_16x16x32_bf16 v[22:25], v[146:149], v[202:205], v[22:25]
	v_mfma_f32_16x16x32_bf16 v[18:21], v[170:173], v[202:205], v[18:21]
	v_mfma_f32_16x16x32_bf16 v[6:9], v[146:149], v[210:213], v[6:9]
	v_mfma_f32_16x16x32_bf16 v[2:5], v[170:173], v[210:213], v[2:5]
	v_mfma_f32_16x16x32_bf16 v[54:57], v[150:153], v[182:185], v[54:57]
	v_mfma_f32_16x16x32_bf16 v[50:53], v[174:177], v[182:185], v[50:53]
	v_mfma_f32_16x16x32_bf16 v[38:41], v[150:153], v[198:201], v[38:41]
	v_mfma_f32_16x16x32_bf16 v[34:37], v[174:177], v[198:201], v[34:37]
	v_mfma_f32_16x16x32_bf16 v[22:25], v[150:153], v[206:209], v[22:25]
	v_mfma_f32_16x16x32_bf16 v[18:21], v[174:177], v[206:209], v[18:21]
	v_mfma_f32_16x16x32_bf16 v[6:9], v[150:153], v[214:217], v[6:9]
	v_mfma_f32_16x16x32_bf16 v[2:5], v[174:177], v[214:217], v[2:5]
	s_barrier
	s_add_i32 s63, s63, 2
	s_add_u32 s61, s61, 0x100
	s_addc_u32 s62, s62, 0
	s_cmpk_gt_u32 s63, 0x55
	s_mov_b64 s[24:25], s[36:37]
	s_cbranch_scc0 .LBB0_1127
	s_and_b64 vcc, exec, s[20:21]
	s_cbranch_vccz .LBB0_1130
	s_barrier

; #define PG8_WAIT_V(n) asm volatile("s_waitcnt vmcnt(" #n ")" ::: "memory")
; #define PG8_BAR __builtin_amdgcn_s_barrier()
; __device__ __forceinline__ unsigned xb_ld(unsigned* p)              { return __hip_atomic_load(p, __ATOMIC_RELAXED, __HIP_MEMORY_SCOPE_AGENT); }
; template <class Epi, class Sched, bool ALIGN_EPI = false, bool SP2 = false>
; __device__ __forceinline__ void gemm_phase(PG8_LAS unsigned char* lds, const Gemm g, const Sched& S, const Epi& E) {
;     ...
;     PG8_WAIT_V(0);
;     if constexpr (!ALIGN_EPI) { if (wr == 0) PG8_BAR; }
;     PG8_BAR;
; __device__ __forceinline__ void xcd_barrier_complete(unsigned* bar, unsigned x, unsigned& nloc, unsigned& nx) {
;     const unsigned G = gridDim.x * gridDim.y * gridDim.z;
;     unsigned sum, cnt, mine, sp = 0u;
;     for (;;) {
;         sum = 0u; cnt = 0u; mine = 0u;
; #pragma unroll
;         for (unsigned j = 0; j < 16; ++j) { const unsigned c = xb_ld(&bar[XB_XCNT(j)]); sum += c; cnt += (c > 0u) ? 1u : 0u; mine = (j == x) ? c : mine; }
.LBB0_1150:
	s_setprio 0
	s_waitcnt vmcnt(0)
	s_waitcnt lgkmcnt(0)
	s_barrier
	s_and_saveexec_b64 s[0:1], s[86:87]
	s_xor_b64 s[0:1], exec, s[0:1]
	s_cbranch_execz .LBB0_1203
	s_add_i32 s2, 0, 0x20040
	v_mov_b32_e32 v1, s2
	s_waitcnt vmcnt(0) expcnt(0) lgkmcnt(0)
	ds_read_b32 v3, v1
	s_add_i32 s2, 0, 0x20044
	v_mov_b32_e32 v1, s2
	ds_read_b32 v1, v1
	s_waitcnt lgkmcnt(1)
	v_cmp_ne_u32_e32 vcc, 0, v3
	s_cbranch_vccnz .LBB0_1166
	s_load_dwordx2 s[6:7], s[84:85], 0x0
	s_load_dword s5, s[84:85], 0x8
	s_add_u32 s2, s30, 0x1000
	s_addc_u32 s3, s31, 0
	s_add_u32 s4, s30, 0x1100
	s_waitcnt lgkmcnt(0)
	s_mul_i32 s16, s7, s6
	s_mul_i32 s16, s16, s5
	s_addc_u32 s5, s31, 0
	s_add_u32 s6, s30, 0x1200
	s_addc_u32 s7, s31, 0
	s_add_u32 s8, s30, 0x1300
	s_addc_u32 s9, s31, 0
	s_mov_b32 s17, 1
	v_mov_b32_e32 v17, 0
	s_branch .LBB0_1154

; __global__ void __launch_bounds__(512, 2) fwd_megakernel(Args a) {
	.amdhsa_kernel _Z14fwd_megakernel4Args
		.amdhsa_group_segment_fixed_size 0
		.amdhsa_private_segment_fixed_size 0
		.amdhsa_kernarg_size 368
		.amdhsa_user_sgpr_count 2
		.amdhsa_user_sgpr_dispatch_ptr 0
		.amdhsa_user_sgpr_queue_ptr 0
		.amdhsa_user_sgpr_kernarg_segment_ptr 1
		.amdhsa_user_sgpr_dispatch_id 0
		.amdhsa_user_sgpr_kernarg_preload_length 0
		.amdhsa_user_sgpr_kernarg_preload_offset 0
		.amdhsa_user_sgpr_private_segment_size 0
		.amdhsa_uses_dynamic_stack 0
		.amdhsa_enable_private_segment 0
		.amdhsa_system_sgpr_workgroup_id_x 1
		.amdhsa_system_sgpr_workgroup_id_y 0
		.amdhsa_system_sgpr_workgroup_id_z 0
		.amdhsa_system_sgpr_workgroup_info 0
		.amdhsa_system_vgpr_workitem_id 0
		.amdhsa_next_free_vgpr 256
		.amdhsa_next_free_sgpr 100
		.amdhsa_accum_offset 256
		.amdhsa_reserve_vcc 1
		.amdhsa_float_round_mode_32 0
		.amdhsa_float_round_mode_16_64 0
		.amdhsa_float_denorm_mode_32 3
		.amdhsa_float_denorm_mode_16_64 3
		.amdhsa_dx10_clamp 1
		.amdhsa_ieee_mode 1
		.amdhsa_fp16_overflow 0
		.amdhsa_tg_split 0
		.amdhsa_exception_fp_ieee_invalid_op 0
		.amdhsa_exception_fp_denorm_src 0
		.amdhsa_exception_fp_ieee_div_zero 0
		.amdhsa_exception_fp_ieee_overflow 0
		.amdhsa_exception_fp_ieee_underflow 0
		.amdhsa_exception_fp_ieee_inexact 0
		.amdhsa_exception_int_div_zero 0
	.end_amdhsa_kernel
